# speedup vs baseline: 1.0501x; 1.0232x over previous
; __device__ __forceinline__ unsigned pack2(float a, float b) { return (unsigned)f2bf(a) | ((unsigned)f2bf(b) << 16); }
; __device__ __forceinline__ float bflo(unsigned u) { return __uint_as_float(u << 16); }
; __device__ __forceinline__ float bfhi(unsigned u) { return __uint_as_float(u & 0xffff0000u); }
; __device__ __forceinline__ f32x16 mfma32(bf16x8 a, bf16x8 b, f32x16 c) { return __builtin_amdgcn_mfma_f32_32x32x16_bf16(a, b, c, 0, 0, 0); }
; __device__ void sgu_task(const Params& p, int l, int n, int g, char* smem) {
;     ...
;   for (int ks = 0; ks < 2 * w + 2; ++ks) {
;     bf16x8 B = *(const bf16x8*)(Wb + 16 * ks + 8 * hf);
; #pragma unroll
;     for (int cb = 0; cb < 4; ++cb) {
;       bf16x8 A = tr_frag<false>(vg, 136, 16 * ks, cb * 32, lane);
;       acc[cb] = mfma32(A, B, acc[cb]);
;     }
;   }
;   const int t = 32 * w + r;
;   const float bias = p.sgu_b[(l * 4 + g) * 128 + t];
;   const u16* up = p.H + (long)(tok0 + t) * INC + 5632 + g * 128 + 4 * hf;
;   u16* op = p.MIXIN + (long)(tok0 + t) * D_ + 1536 + g * 128 + 4 * hf;
; #pragma unroll
;   for (int cb = 0; cb < 4; ++cb)
; #pragma unroll
;     for (int g4 = 0; g4 < 4; ++g4) {
;       uint2 uraw = *(const uint2*)(up + cb * 32 + 8 * g4);
;       float uv[4] = {bflo(uraw.x), bfhi(uraw.x), bflo(uraw.y), bfhi(uraw.y)};
;       float y[4];
; #pragma unroll
;       for (int j = 0; j < 4; ++j) y[j] = gelu_t(uv[j]) * (acc[cb][4 * g4 + j] + bias);
;       uint2 pk; pk.x = pack2(y[0], y[1]); pk.y = pack2(y[2], y[3]);
;       *(uint2*)(op + cb * 32 + 8 * g4) = pk;
;     }
.LBB0_886:
	global_load_dwordx4 v[76:79], v[66:67], off
	v_add_u32_e32 v70, s11, v74
	ds_read_b64_tr_b16 v[80:81], v70
	ds_read_b64_tr_b16 v[82:83], v70 offset:1088
	s_addk_i32 s11, 0x1100
	v_cmp_eq_u32_e32 vcc, s11, v73
	v_lshl_add_u64 v[66:67], v[66:67], 0, 32
	s_or_b64 s[2:3], vcc, s[2:3]
	s_waitcnt vmcnt(0) lgkmcnt(0)
	v_mfma_f32_32x32x16_bf16 v[48:63], v[80:83], v[76:79], v[48:63]
	ds_read_b64_tr_b16 v[80:81], v70 offset:64
	ds_read_b64_tr_b16 v[82:83], v70 offset:1152
	s_waitcnt lgkmcnt(0)
	v_mfma_f32_32x32x16_bf16 v[32:47], v[80:83], v[76:79], v[32:47]
	ds_read_b64_tr_b16 v[80:81], v70 offset:128
	ds_read_b64_tr_b16 v[82:83], v70 offset:1216
	s_waitcnt lgkmcnt(0)
	v_mfma_f32_32x32x16_bf16 v[16:31], v[80:83], v[76:79], v[16:31]
	ds_read_b64_tr_b16 v[80:81], v70 offset:192
	ds_read_b64_tr_b16 v[82:83], v70 offset:1280
	s_waitcnt lgkmcnt(0)
	v_mfma_f32_32x32x16_bf16 v[0:15], v[80:83], v[76:79], v[0:15]
	s_andn2_b64 exec, exec, s[2:3]
	s_cbranch_execnz .LBB0_886
	s_or_b64 exec, exec, s[2:3]
	v_or_b32_e32 v69, v72, v69
	v_readlane_b32 s16, v252, 8
	v_or3_b32 v66, v64, s6, v69
	v_mov_b32_e32 v67, v177
	v_readlane_b32 s28, v252, 20
	v_readlane_b32 s29, v252, 21
	v_mov_b64_e32 v[70:71], s[56:57]
	v_lshrrev_b32_e32 v72, 2, v68
	v_lshl_add_u64 v[66:67], v[66:67], 2, s[28:29]
	global_load_dword v64, v[66:67], off
	v_or_b32_e32 v66, v65, v69
	v_mad_i64_i32 v[70:71], s[2:3], v66, s15, v[70:71]
	v_lshl_add_u64 v[70:71], v[70:71], 0, v[176:177]
	v_mov_b32_e32 v73, v177
	v_lshl_add_u64 v[70:71], v[70:71], 0, v[72:73]
	s_mov_b64 s[2:3], 0x2c00
	v_lshl_add_u64 v[68:69], v[70:71], 0, s[2:3]
	v_add_co_u32_e32 v70, vcc, s50, v70
	v_ashrrev_i32_e32 v67, 31, v66
	s_nop 0
	v_addc_co_u32_e32 v71, vcc, 0, v71, vcc
	global_load_dwordx2 v[70:71], v[70:71], off offset:3072
	global_load_dwordx2 v[78:79], v[68:69], off offset:16
	global_load_dwordx2 v[80:81], v[68:69], off offset:32
	global_load_dwordx2 v[82:83], v[68:69], off offset:48
	global_load_dwordx2 v[84:85], v[68:69], off offset:64
	global_load_dwordx2 v[86:87], v[68:69], off offset:80
	global_load_dwordx2 v[88:89], v[68:69], off offset:96
	global_load_dwordx2 v[90:91], v[68:69], off offset:112
	global_load_dwordx2 v[92:93], v[68:69], off offset:128
	global_load_dwordx2 v[94:95], v[68:69], off offset:144
	global_load_dwordx2 v[96:97], v[68:69], off offset:160
	global_load_dwordx2 v[98:99], v[68:69], off offset:176
	global_load_dwordx2 v[100:101], v[68:69], off offset:192
	global_load_dwordx2 v[102:103], v[68:69], off offset:208
	global_load_dwordx2 v[104:105], v[68:69], off offset:224
	global_load_dwordx2 v[106:107], v[68:69], off offset:240
	v_lshlrev_b64 v[66:67], 12, v[66:67]
	v_lshl_add_u64 v[66:67], s[58:59], 0, v[66:67]
	v_lshl_add_u64 v[66:67], v[66:67], 0, v[176:177]
	v_lshl_add_u64 v[66:67], v[66:67], 0, v[72:73]
	s_add_i32 s43, s43, s42
	s_add_i32 s86, s86, s42
	s_cmpk_gt_i32 s43, 0x1ff
	v_readlane_b32 s17, v252, 9
	v_readlane_b32 s18, v252, 10
	v_readlane_b32 s19, v252, 11
	v_readlane_b32 s20, v252, 12
	v_readlane_b32 s21, v252, 13
	v_readlane_b32 s22, v252, 14
	v_readlane_b32 s23, v252, 15
	v_readlane_b32 s24, v252, 16
	v_readlane_b32 s25, v252, 17
	v_readlane_b32 s26, v252, 18
	v_readlane_b32 s27, v252, 19
	v_readlane_b32 s30, v252, 22
	v_readlane_b32 s31, v252, 23
	s_waitcnt vmcnt(15)
	v_lshlrev_b32_e32 v73, 16, v71
	v_lshlrev_b32_e32 v72, 16, v70
	v_pk_mul_f32 v[74:75], v[72:73], v[72:73]
	v_and_b32_e32 v71, 0xffff0000, v71
	v_fmamk_f32 v65, v74, 0x3dd2d3e7, v213
	v_mul_f32_e32 v65, v65, v72
	v_exp_f32_e32 v65, v65
	v_and_b32_e32 v70, 0xffff0000, v70
	v_pk_mul_f32 v[76:77], v[70:71], v[70:71]
	v_add_f32_e32 v65, 1.0, v65
	v_rcp_f32_e32 v74, v65
	v_fmamk_f32 v65, v76, 0x3dd2d3e7, v213
	v_mul_f32_e32 v65, v65, v70
	v_exp_f32_e32 v65, v65
	s_nop 0
	v_add_f32_e32 v65, 1.0, v65
	v_rcp_f32_e32 v76, v65
	v_fmamk_f32 v65, v75, 0x3dd2d3e7, v213
	v_mul_f32_e32 v65, v65, v73
	v_exp_f32_e32 v65, v65
	s_nop 0
	v_add_f32_e32 v65, 1.0, v65
	v_rcp_f32_e32 v75, v65
	s_nop 0
	v_pk_fma_f32 v[72:73], v[72:73], v[74:75], v[72:73] neg_lo:[1,0,0] neg_hi:[1,0,0]
	v_mov_b32_e32 v74, v48
	v_fmamk_f32 v48, v77, 0x3dd2d3e7, v213
	v_mul_f32_e32 v48, v48, v71
	v_exp_f32_e32 v48, v48
	v_mov_b32_e32 v75, v50
	v_mov_b32_e32 v50, v49
	v_pk_add_f32 v[74:75], v[74:75], v[64:65] op_sel_hi:[1,0]
	v_add_f32_e32 v48, 1.0, v48
	v_rcp_f32_e32 v77, v48
	v_pk_add_f32 v[48:49], v[50:51], v[64:65] op_sel_hi:[1,0]
	v_pk_mul_f32 v[72:73], v[74:75], v[72:73]
	v_pk_fma_f32 v[70:71], v[70:71], v[76:77], v[70:71] neg_lo:[1,0,0] neg_hi:[1,0,0]
	s_nop 0
	v_pk_mul_f32 v[48:49], v[48:49], v[70:71]
	v_and_b32_sdwa v50, v73, v209 dst_sel:DWORD dst_unused:UNUSED_PAD src0_sel:WORD_1 src1_sel:DWORD
	v_and_b32_sdwa v65, v49, v209 dst_sel:DWORD dst_unused:UNUSED_PAD src0_sel:WORD_1 src1_sel:DWORD
	v_and_b32_sdwa v70, v48, v209 dst_sel:DWORD dst_unused:UNUSED_PAD src0_sel:WORD_1 src1_sel:DWORD
	v_and_b32_sdwa v51, v72, v209 dst_sel:DWORD dst_unused:UNUSED_PAD src0_sel:WORD_1 src1_sel:DWORD
	v_add3_u32 v49, v49, v65, s65
	v_add3_u32 v48, v48, v70, s65
	v_add3_u32 v51, v72, v51, s65
	v_add3_u32 v50, v73, v50, s65
	v_and_b32_e32 v49, 0xffff0000, v49
	v_and_b32_e32 v48, 0xffff0000, v48
	v_or_b32_sdwa v49, v49, v50 dst_sel:DWORD dst_unused:UNUSED_PAD src0_sel:DWORD src1_sel:WORD_1
	v_or_b32_sdwa v48, v48, v51 dst_sel:DWORD dst_unused:UNUSED_PAD src0_sel:DWORD src1_sel:WORD_1
	global_store_dwordx2 v[66:67], v[48:49], off offset:3072
	s_waitcnt vmcnt(15)
; __device__ __forceinline__ unsigned pack2(float a, float b) { return (unsigned)f2bf(a) | ((unsigned)f2bf(b) << 16); }
; __device__ __forceinline__ float bflo(unsigned u) { return __uint_as_float(u << 16); }
; __device__ __forceinline__ float bfhi(unsigned u) { return __uint_as_float(u & 0xffff0000u); }
; __device__ void sgu_task(const Params& p, int l, int n, int g, char* smem) {
;     ...
; #pragma unroll
;   for (int cb = 0; cb < 4; ++cb)
; #pragma unroll
;     for (int g4 = 0; g4 < 4; ++g4) {
;       uint2 uraw = *(const uint2*)(up + cb * 32 + 8 * g4);
;       float uv[4] = {bflo(uraw.x), bfhi(uraw.x), bflo(uraw.y), bfhi(uraw.y)};
;       float y[4];
; #pragma unroll
;       for (int j = 0; j < 4; ++j) y[j] = gelu_t(uv[j]) * (acc[cb][4 * g4 + j] + bias);
;       uint2 pk; pk.x = pack2(y[0], y[1]); pk.y = pack2(y[2], y[3]);
;       *(uint2*)(op + cb * 32 + 8 * g4) = pk;
;     }
	v_mov_b32_e32 v48, v78
	v_mov_b32_e32 v49, v79
	v_lshlrev_b32_e32 v51, 16, v49
	v_lshlrev_b32_e32 v50, 16, v48
	v_pk_mul_f32 v[70:71], v[50:51], v[50:51]
	v_and_b32_e32 v49, 0xffff0000, v49
	v_fmamk_f32 v65, v70, 0x3dd2d3e7, v213
	v_mul_f32_e32 v65, v65, v50
	v_exp_f32_e32 v65, v65
	v_and_b32_e32 v48, 0xffff0000, v48
	v_pk_mul_f32 v[72:73], v[48:49], v[48:49]
	v_add_f32_e32 v65, 1.0, v65
	v_rcp_f32_e32 v70, v65
	v_fmamk_f32 v65, v72, 0x3dd2d3e7, v213
	v_mul_f32_e32 v65, v65, v48
	v_exp_f32_e32 v65, v65
	s_nop 0
	v_add_f32_e32 v65, 1.0, v65
	v_rcp_f32_e32 v72, v65
	v_fmamk_f32 v65, v71, 0x3dd2d3e7, v213
	v_mul_f32_e32 v65, v65, v51
	v_exp_f32_e32 v65, v65
	s_nop 0
	v_add_f32_e32 v65, 1.0, v65
	v_rcp_f32_e32 v71, v65
	s_nop 0
	v_pk_fma_f32 v[50:51], v[50:51], v[70:71], v[50:51] neg_lo:[1,0,0] neg_hi:[1,0,0]
	v_mov_b32_e32 v70, v52
	v_fmamk_f32 v52, v73, 0x3dd2d3e7, v213
	v_mul_f32_e32 v52, v52, v49
	v_exp_f32_e32 v52, v52
	v_mov_b32_e32 v71, v54
	v_pk_add_f32 v[70:71], v[70:71], v[64:65] op_sel_hi:[1,0]
	v_mov_b32_e32 v54, v53
	v_add_f32_e32 v52, 1.0, v52
	v_rcp_f32_e32 v73, v52
	v_pk_mul_f32 v[50:51], v[70:71], v[50:51]
	v_pk_add_f32 v[52:53], v[54:55], v[64:65] op_sel_hi:[1,0]
	v_pk_fma_f32 v[48:49], v[48:49], v[72:73], v[48:49] neg_lo:[1,0,0] neg_hi:[1,0,0]
	s_nop 0
	v_pk_mul_f32 v[48:49], v[52:53], v[48:49]
	v_and_b32_sdwa v52, v51, v209 dst_sel:DWORD dst_unused:UNUSED_PAD src0_sel:WORD_1 src1_sel:DWORD
	v_and_b32_sdwa v53, v50, v209 dst_sel:DWORD dst_unused:UNUSED_PAD src0_sel:WORD_1 src1_sel:DWORD
	v_add3_u32 v50, v50, v53, s65
	v_add3_u32 v51, v51, v52, s65
	v_and_b32_sdwa v52, v49, v209 dst_sel:DWORD dst_unused:UNUSED_PAD src0_sel:WORD_1 src1_sel:DWORD
	v_and_b32_sdwa v53, v48, v209 dst_sel:DWORD dst_unused:UNUSED_PAD src0_sel:WORD_1 src1_sel:DWORD
	v_add3_u32 v49, v49, v52, s65
	v_add3_u32 v48, v48, v53, s65
	v_and_b32_e32 v49, 0xffff0000, v49
	v_and_b32_e32 v48, 0xffff0000, v48
	v_or_b32_sdwa v49, v49, v51 dst_sel:DWORD dst_unused:UNUSED_PAD src0_sel:DWORD src1_sel:WORD_1
	v_or_b32_sdwa v48, v48, v50 dst_sel:DWORD dst_unused:UNUSED_PAD src0_sel:DWORD src1_sel:WORD_1
	global_store_dwordx2 v[66:67], v[48:49], off offset:3088
	s_waitcnt vmcnt(15)
	v_mov_b32_e32 v48, v80
	v_mov_b32_e32 v49, v81
	v_lshlrev_b32_e32 v51, 16, v49
	v_lshlrev_b32_e32 v50, 16, v48
	v_pk_mul_f32 v[52:53], v[50:51], v[50:51]
	v_and_b32_e32 v49, 0xffff0000, v49
	v_fmamk_f32 v52, v52, 0x3dd2d3e7, v213
	v_fmamk_f32 v53, v53, 0x3dd2d3e7, v213
	v_mul_f32_e32 v52, v52, v50
	v_mul_f32_e32 v53, v53, v51
	v_exp_f32_e32 v52, v52
	v_exp_f32_e32 v53, v53
	v_and_b32_e32 v48, 0xffff0000, v48
	v_pk_mul_f32 v[54:55], v[48:49], v[48:49]
	v_add_f32_e32 v52, 1.0, v52
	v_add_f32_e32 v53, 1.0, v53
	v_rcp_f32_e32 v52, v52
	v_rcp_f32_e32 v53, v53
	v_fmamk_f32 v54, v54, 0x3dd2d3e7, v213
	v_mul_f32_e32 v54, v54, v48
	v_exp_f32_e32 v54, v54
	v_pk_fma_f32 v[50:51], v[50:51], v[52:53], v[50:51] neg_lo:[1,0,0] neg_hi:[1,0,0]
	v_mov_b32_e32 v52, v56
	v_mov_b32_e32 v53, v58
	v_pk_add_f32 v[52:53], v[52:53], v[64:65] op_sel_hi:[1,0]
	v_add_f32_e32 v54, 1.0, v54
	v_pk_mul_f32 v[50:51], v[52:53], v[50:51]
	v_fmamk_f32 v52, v55, 0x3dd2d3e7, v213
	v_mul_f32_e32 v52, v52, v49
	v_exp_f32_e32 v52, v52
	v_rcp_f32_e32 v54, v54
	v_mov_b32_e32 v58, v57
	v_add_f32_e32 v52, 1.0, v52
	v_rcp_f32_e32 v55, v52
	v_pk_add_f32 v[52:53], v[58:59], v[64:65] op_sel_hi:[1,0]
	v_pk_fma_f32 v[48:49], v[48:49], v[54:55], v[48:49] neg_lo:[1,0,0] neg_hi:[1,0,0]
	s_nop 0
	v_pk_mul_f32 v[48:49], v[52:53], v[48:49]
	v_and_b32_sdwa v52, v51, v209 dst_sel:DWORD dst_unused:UNUSED_PAD src0_sel:WORD_1 src1_sel:DWORD
	v_and_b32_sdwa v53, v50, v209 dst_sel:DWORD dst_unused:UNUSED_PAD src0_sel:WORD_1 src1_sel:DWORD
	v_add3_u32 v50, v50, v53, s65
	v_add3_u32 v51, v51, v52, s65
	v_and_b32_sdwa v52, v49, v209 dst_sel:DWORD dst_unused:UNUSED_PAD src0_sel:WORD_1 src1_sel:DWORD
	v_and_b32_sdwa v53, v48, v209 dst_sel:DWORD dst_unused:UNUSED_PAD src0_sel:WORD_1 src1_sel:DWORD
	v_add3_u32 v49, v49, v52, s65
	v_add3_u32 v48, v48, v53, s65
	v_and_b32_e32 v49, 0xffff0000, v49
	v_and_b32_e32 v48, 0xffff0000, v48
	v_or_b32_sdwa v49, v49, v51 dst_sel:DWORD dst_unused:UNUSED_PAD src0_sel:DWORD src1_sel:WORD_1
	v_or_b32_sdwa v48, v48, v50 dst_sel:DWORD dst_unused:UNUSED_PAD src0_sel:DWORD src1_sel:WORD_1
	global_store_dwordx2 v[66:67], v[48:49], off offset:3104
	s_waitcnt vmcnt(15)
	v_mov_b32_e32 v48, v82
	v_mov_b32_e32 v49, v83
	v_lshlrev_b32_e32 v51, 16, v49
	v_lshlrev_b32_e32 v50, 16, v48
	v_pk_mul_f32 v[52:53], v[50:51], v[50:51]
	v_and_b32_e32 v49, 0xffff0000, v49
	v_fmamk_f32 v52, v52, 0x3dd2d3e7, v213
	v_fmamk_f32 v53, v53, 0x3dd2d3e7, v213
	v_mul_f32_e32 v52, v52, v50
	v_mul_f32_e32 v53, v53, v51
	v_exp_f32_e32 v52, v52
	v_exp_f32_e32 v53, v53
	v_and_b32_e32 v48, 0xffff0000, v48
	v_pk_mul_f32 v[54:55], v[48:49], v[48:49]
	v_add_f32_e32 v52, 1.0, v52
	v_add_f32_e32 v53, 1.0, v53
	v_rcp_f32_e32 v52, v52
	v_rcp_f32_e32 v53, v53
	v_fmamk_f32 v54, v54, 0x3dd2d3e7, v213
	v_mul_f32_e32 v54, v54, v48
	v_exp_f32_e32 v54, v54
	v_pk_fma_f32 v[50:51], v[50:51], v[52:53], v[50:51] neg_lo:[1,0,0] neg_hi:[1,0,0]
	v_mov_b32_e32 v52, v60
	v_mov_b32_e32 v53, v62
	v_pk_add_f32 v[52:53], v[52:53], v[64:65] op_sel_hi:[1,0]
	v_add_f32_e32 v54, 1.0, v54
	v_pk_mul_f32 v[50:51], v[52:53], v[50:51]
	v_fmamk_f32 v52, v55, 0x3dd2d3e7, v213
	v_mul_f32_e32 v52, v52, v49
	v_exp_f32_e32 v52, v52
	v_rcp_f32_e32 v54, v54
	v_mov_b32_e32 v62, v61
	v_add_f32_e32 v52, 1.0, v52
	v_rcp_f32_e32 v55, v52
	v_pk_add_f32 v[52:53], v[62:63], v[64:65] op_sel_hi:[1,0]
	v_pk_fma_f32 v[48:49], v[48:49], v[54:55], v[48:49] neg_lo:[1,0,0] neg_hi:[1,0,0]
	s_nop 0
	v_pk_mul_f32 v[48:49], v[52:53], v[48:49]
	v_and_b32_sdwa v52, v51, v209 dst_sel:DWORD dst_unused:UNUSED_PAD src0_sel:WORD_1 src1_sel:DWORD
	v_and_b32_sdwa v53, v50, v209 dst_sel:DWORD dst_unused:UNUSED_PAD src0_sel:WORD_1 src1_sel:DWORD
	v_add3_u32 v50, v50, v53, s65
	v_add3_u32 v51, v51, v52, s65
	v_and_b32_sdwa v52, v49, v209 dst_sel:DWORD dst_unused:UNUSED_PAD src0_sel:WORD_1 src1_sel:DWORD
	v_and_b32_sdwa v53, v48, v209 dst_sel:DWORD dst_unused:UNUSED_PAD src0_sel:WORD_1 src1_sel:DWORD
	v_add3_u32 v49, v49, v52, s65
	v_add3_u32 v48, v48, v53, s65
	v_and_b32_e32 v49, 0xffff0000, v49
	v_and_b32_e32 v48, 0xffff0000, v48
	v_or_b32_sdwa v49, v49, v51 dst_sel:DWORD dst_unused:UNUSED_PAD src0_sel:DWORD src1_sel:WORD_1
	v_or_b32_sdwa v48, v48, v50 dst_sel:DWORD dst_unused:UNUSED_PAD src0_sel:DWORD src1_sel:WORD_1
	global_store_dwordx2 v[66:67], v[48:49], off offset:3120
	s_waitcnt vmcnt(15)
; __device__ __forceinline__ unsigned pack2(float a, float b) { return (unsigned)f2bf(a) | ((unsigned)f2bf(b) << 16); }
; __device__ __forceinline__ float bflo(unsigned u) { return __uint_as_float(u << 16); }
; __device__ __forceinline__ float bfhi(unsigned u) { return __uint_as_float(u & 0xffff0000u); }
; __device__ void sgu_task(const Params& p, int l, int n, int g, char* smem) {
;     ...
; #pragma unroll
;   for (int cb = 0; cb < 4; ++cb)
; #pragma unroll
;     for (int g4 = 0; g4 < 4; ++g4) {
;       uint2 uraw = *(const uint2*)(up + cb * 32 + 8 * g4);
;       float uv[4] = {bflo(uraw.x), bfhi(uraw.x), bflo(uraw.y), bfhi(uraw.y)};
;       float y[4];
; #pragma unroll
;       for (int j = 0; j < 4; ++j) y[j] = gelu_t(uv[j]) * (acc[cb][4 * g4 + j] + bias);
;       uint2 pk; pk.x = pack2(y[0], y[1]); pk.y = pack2(y[2], y[3]);
;       *(uint2*)(op + cb * 32 + 8 * g4) = pk;
;     }
	v_mov_b32_e32 v48, v84
	v_mov_b32_e32 v49, v85
	v_lshlrev_b32_e32 v51, 16, v49
	v_lshlrev_b32_e32 v50, 16, v48
	v_pk_mul_f32 v[52:53], v[50:51], v[50:51]
	v_and_b32_e32 v49, 0xffff0000, v49
	v_fmamk_f32 v52, v52, 0x3dd2d3e7, v213
	v_fmamk_f32 v53, v53, 0x3dd2d3e7, v213
	v_mul_f32_e32 v52, v52, v50
	v_mul_f32_e32 v53, v53, v51
	v_exp_f32_e32 v52, v52
	v_exp_f32_e32 v53, v53
	v_and_b32_e32 v48, 0xffff0000, v48
	v_pk_mul_f32 v[54:55], v[48:49], v[48:49]
	v_add_f32_e32 v52, 1.0, v52
	v_add_f32_e32 v53, 1.0, v53
	v_rcp_f32_e32 v52, v52
	v_rcp_f32_e32 v53, v53
	v_fmamk_f32 v54, v54, 0x3dd2d3e7, v213
	v_mul_f32_e32 v54, v54, v48
	v_exp_f32_e32 v54, v54
	v_pk_fma_f32 v[50:51], v[50:51], v[52:53], v[50:51] neg_lo:[1,0,0] neg_hi:[1,0,0]
	v_mov_b32_e32 v52, v32
	v_fmamk_f32 v32, v55, 0x3dd2d3e7, v213
	v_mul_f32_e32 v32, v32, v49
	v_exp_f32_e32 v32, v32
	v_add_f32_e32 v54, 1.0, v54
	v_rcp_f32_e32 v54, v54
	v_mov_b32_e32 v53, v34
	v_add_f32_e32 v32, 1.0, v32
	v_rcp_f32_e32 v55, v32
	v_mov_b32_e32 v34, v33
	v_pk_add_f32 v[32:33], v[34:35], v[64:65] op_sel_hi:[1,0]
	v_pk_add_f32 v[52:53], v[52:53], v[64:65] op_sel_hi:[1,0]
	v_pk_fma_f32 v[48:49], v[48:49], v[54:55], v[48:49] neg_lo:[1,0,0] neg_hi:[1,0,0]
	v_pk_mul_f32 v[50:51], v[52:53], v[50:51]
	v_pk_mul_f32 v[32:33], v[32:33], v[48:49]
	v_and_b32_sdwa v34, v51, v209 dst_sel:DWORD dst_unused:UNUSED_PAD src0_sel:WORD_1 src1_sel:DWORD
	v_and_b32_sdwa v48, v33, v209 dst_sel:DWORD dst_unused:UNUSED_PAD src0_sel:WORD_1 src1_sel:DWORD
	v_and_b32_sdwa v49, v32, v209 dst_sel:DWORD dst_unused:UNUSED_PAD src0_sel:WORD_1 src1_sel:DWORD
	v_and_b32_sdwa v35, v50, v209 dst_sel:DWORD dst_unused:UNUSED_PAD src0_sel:WORD_1 src1_sel:DWORD
	v_add3_u32 v33, v33, v48, s65
	v_add3_u32 v32, v32, v49, s65
	v_add3_u32 v35, v50, v35, s65
	v_add3_u32 v34, v51, v34, s65
	v_and_b32_e32 v33, 0xffff0000, v33
	v_and_b32_e32 v32, 0xffff0000, v32
	v_or_b32_sdwa v33, v33, v34 dst_sel:DWORD dst_unused:UNUSED_PAD src0_sel:DWORD src1_sel:WORD_1
	v_or_b32_sdwa v32, v32, v35 dst_sel:DWORD dst_unused:UNUSED_PAD src0_sel:DWORD src1_sel:WORD_1
	global_store_dwordx2 v[66:67], v[32:33], off offset:3136
	s_waitcnt vmcnt(15)
	v_mov_b32_e32 v32, v86
	v_mov_b32_e32 v33, v87
	v_lshlrev_b32_e32 v35, 16, v33
	v_lshlrev_b32_e32 v34, 16, v32
	v_pk_mul_f32 v[48:49], v[34:35], v[34:35]
	v_and_b32_e32 v33, 0xffff0000, v33
	v_fmamk_f32 v48, v48, 0x3dd2d3e7, v213
	v_fmamk_f32 v49, v49, 0x3dd2d3e7, v213
	v_mul_f32_e32 v48, v48, v34
	v_mul_f32_e32 v49, v49, v35
	v_exp_f32_e32 v48, v48
	v_exp_f32_e32 v49, v49
	v_and_b32_e32 v32, 0xffff0000, v32
	v_pk_mul_f32 v[50:51], v[32:33], v[32:33]
	v_add_f32_e32 v48, 1.0, v48
	v_add_f32_e32 v49, 1.0, v49
	v_rcp_f32_e32 v48, v48
	v_rcp_f32_e32 v49, v49
	v_fmamk_f32 v50, v50, 0x3dd2d3e7, v213
	v_mul_f32_e32 v50, v50, v32
	v_exp_f32_e32 v50, v50
	v_pk_fma_f32 v[34:35], v[34:35], v[48:49], v[34:35] neg_lo:[1,0,0] neg_hi:[1,0,0]
	v_mov_b32_e32 v48, v36
	v_fmamk_f32 v36, v51, 0x3dd2d3e7, v213
	v_mul_f32_e32 v36, v36, v33
	v_exp_f32_e32 v36, v36
	v_add_f32_e32 v50, 1.0, v50
	v_rcp_f32_e32 v50, v50
	v_mov_b32_e32 v49, v38
	v_add_f32_e32 v36, 1.0, v36
	v_rcp_f32_e32 v51, v36
	v_pk_add_f32 v[48:49], v[48:49], v[64:65] op_sel_hi:[1,0]
	v_mov_b32_e32 v38, v37
	v_pk_mul_f32 v[34:35], v[48:49], v[34:35]
	v_pk_fma_f32 v[32:33], v[32:33], v[50:51], v[32:33] neg_lo:[1,0,0] neg_hi:[1,0,0]
	v_pk_add_f32 v[36:37], v[38:39], v[64:65] op_sel_hi:[1,0]
	s_nop 0
	v_pk_mul_f32 v[32:33], v[36:37], v[32:33]
	v_and_b32_sdwa v36, v35, v209 dst_sel:DWORD dst_unused:UNUSED_PAD src0_sel:WORD_1 src1_sel:DWORD
	v_and_b32_sdwa v37, v34, v209 dst_sel:DWORD dst_unused:UNUSED_PAD src0_sel:WORD_1 src1_sel:DWORD
	v_add3_u32 v34, v34, v37, s65
	v_add3_u32 v35, v35, v36, s65
	v_and_b32_sdwa v36, v33, v209 dst_sel:DWORD dst_unused:UNUSED_PAD src0_sel:WORD_1 src1_sel:DWORD
	v_and_b32_sdwa v37, v32, v209 dst_sel:DWORD dst_unused:UNUSED_PAD src0_sel:WORD_1 src1_sel:DWORD
	v_add3_u32 v33, v33, v36, s65
	v_add3_u32 v32, v32, v37, s65
	v_and_b32_e32 v33, 0xffff0000, v33
	v_and_b32_e32 v32, 0xffff0000, v32
	v_or_b32_sdwa v33, v33, v35 dst_sel:DWORD dst_unused:UNUSED_PAD src0_sel:DWORD src1_sel:WORD_1
	v_or_b32_sdwa v32, v32, v34 dst_sel:DWORD dst_unused:UNUSED_PAD src0_sel:DWORD src1_sel:WORD_1
	global_store_dwordx2 v[66:67], v[32:33], off offset:3152
	s_waitcnt vmcnt(15)
	v_mov_b32_e32 v32, v88
	v_mov_b32_e32 v33, v89
	v_lshlrev_b32_e32 v35, 16, v33
	v_lshlrev_b32_e32 v34, 16, v32
	v_pk_mul_f32 v[36:37], v[34:35], v[34:35]
	v_and_b32_e32 v33, 0xffff0000, v33
	v_fmamk_f32 v36, v36, 0x3dd2d3e7, v213
	v_fmamk_f32 v37, v37, 0x3dd2d3e7, v213
	v_mul_f32_e32 v36, v36, v34
	v_mul_f32_e32 v37, v37, v35
	v_exp_f32_e32 v36, v36
	v_exp_f32_e32 v37, v37
	v_and_b32_e32 v32, 0xffff0000, v32
	v_pk_mul_f32 v[38:39], v[32:33], v[32:33]
	v_add_f32_e32 v36, 1.0, v36
	v_add_f32_e32 v37, 1.0, v37
	v_rcp_f32_e32 v36, v36
	v_rcp_f32_e32 v37, v37
	v_fmamk_f32 v38, v38, 0x3dd2d3e7, v213
	v_mul_f32_e32 v38, v38, v32
	v_exp_f32_e32 v38, v38
	v_pk_fma_f32 v[34:35], v[34:35], v[36:37], v[34:35] neg_lo:[1,0,0] neg_hi:[1,0,0]
	v_mov_b32_e32 v36, v40
	v_mov_b32_e32 v37, v42
	v_pk_add_f32 v[36:37], v[36:37], v[64:65] op_sel_hi:[1,0]
	v_add_f32_e32 v38, 1.0, v38
	v_pk_mul_f32 v[34:35], v[36:37], v[34:35]
	v_fmamk_f32 v36, v39, 0x3dd2d3e7, v213
	v_mul_f32_e32 v36, v36, v33
	v_exp_f32_e32 v36, v36
	v_rcp_f32_e32 v38, v38
	v_mov_b32_e32 v42, v41
	v_add_f32_e32 v36, 1.0, v36
	v_rcp_f32_e32 v39, v36
	v_pk_add_f32 v[36:37], v[42:43], v[64:65] op_sel_hi:[1,0]
	v_pk_fma_f32 v[32:33], v[32:33], v[38:39], v[32:33] neg_lo:[1,0,0] neg_hi:[1,0,0]
	s_nop 0
	v_pk_mul_f32 v[32:33], v[36:37], v[32:33]
	v_and_b32_sdwa v36, v35, v209 dst_sel:DWORD dst_unused:UNUSED_PAD src0_sel:WORD_1 src1_sel:DWORD
	v_and_b32_sdwa v37, v34, v209 dst_sel:DWORD dst_unused:UNUSED_PAD src0_sel:WORD_1 src1_sel:DWORD
	v_add3_u32 v34, v34, v37, s65
	v_add3_u32 v35, v35, v36, s65
	v_and_b32_sdwa v36, v33, v209 dst_sel:DWORD dst_unused:UNUSED_PAD src0_sel:WORD_1 src1_sel:DWORD
	v_and_b32_sdwa v37, v32, v209 dst_sel:DWORD dst_unused:UNUSED_PAD src0_sel:WORD_1 src1_sel:DWORD
	v_add3_u32 v33, v33, v36, s65
	v_add3_u32 v32, v32, v37, s65
	v_and_b32_e32 v33, 0xffff0000, v33
	v_and_b32_e32 v32, 0xffff0000, v32
	v_or_b32_sdwa v33, v33, v35 dst_sel:DWORD dst_unused:UNUSED_PAD src0_sel:DWORD src1_sel:WORD_1
	v_or_b32_sdwa v32, v32, v34 dst_sel:DWORD dst_unused:UNUSED_PAD src0_sel:DWORD src1_sel:WORD_1
	global_store_dwordx2 v[66:67], v[32:33], off offset:3168
	s_waitcnt vmcnt(15)
; __device__ __forceinline__ unsigned pack2(float a, float b) { return (unsigned)f2bf(a) | ((unsigned)f2bf(b) << 16); }
; __device__ __forceinline__ float bflo(unsigned u) { return __uint_as_float(u << 16); }
; __device__ __forceinline__ float bfhi(unsigned u) { return __uint_as_float(u & 0xffff0000u); }
; __device__ void sgu_task(const Params& p, int l, int n, int g, char* smem) {
;     ...
; #pragma unroll
;   for (int cb = 0; cb < 4; ++cb)
; #pragma unroll
;     for (int g4 = 0; g4 < 4; ++g4) {
;       uint2 uraw = *(const uint2*)(up + cb * 32 + 8 * g4);
;       float uv[4] = {bflo(uraw.x), bfhi(uraw.x), bflo(uraw.y), bfhi(uraw.y)};
;       float y[4];
; #pragma unroll
;       for (int j = 0; j < 4; ++j) y[j] = gelu_t(uv[j]) * (acc[cb][4 * g4 + j] + bias);
;       uint2 pk; pk.x = pack2(y[0], y[1]); pk.y = pack2(y[2], y[3]);
;       *(uint2*)(op + cb * 32 + 8 * g4) = pk;
;     }
	v_mov_b32_e32 v32, v90
	v_mov_b32_e32 v33, v91
	v_lshlrev_b32_e32 v35, 16, v33
	v_lshlrev_b32_e32 v34, 16, v32
	v_pk_mul_f32 v[36:37], v[34:35], v[34:35]
	v_and_b32_e32 v33, 0xffff0000, v33
	v_fmamk_f32 v36, v36, 0x3dd2d3e7, v213
	v_fmamk_f32 v37, v37, 0x3dd2d3e7, v213
	v_mul_f32_e32 v36, v36, v34
	v_mul_f32_e32 v37, v37, v35
	v_exp_f32_e32 v36, v36
	v_exp_f32_e32 v37, v37
	v_and_b32_e32 v32, 0xffff0000, v32
	v_pk_mul_f32 v[38:39], v[32:33], v[32:33]
	v_add_f32_e32 v36, 1.0, v36
	v_add_f32_e32 v37, 1.0, v37
	v_rcp_f32_e32 v36, v36
	v_rcp_f32_e32 v37, v37
	v_fmamk_f32 v38, v38, 0x3dd2d3e7, v213
	v_mul_f32_e32 v38, v38, v32
	v_exp_f32_e32 v38, v38
	v_pk_fma_f32 v[34:35], v[34:35], v[36:37], v[34:35] neg_lo:[1,0,0] neg_hi:[1,0,0]
	v_mov_b32_e32 v36, v44
	v_mov_b32_e32 v37, v46
	v_pk_add_f32 v[36:37], v[36:37], v[64:65] op_sel_hi:[1,0]
	v_add_f32_e32 v38, 1.0, v38
	v_pk_mul_f32 v[34:35], v[36:37], v[34:35]
	v_fmamk_f32 v36, v39, 0x3dd2d3e7, v213
	v_mul_f32_e32 v36, v36, v33
	v_exp_f32_e32 v36, v36
	v_rcp_f32_e32 v38, v38
	v_mov_b32_e32 v46, v45
	v_add_f32_e32 v36, 1.0, v36
	v_rcp_f32_e32 v39, v36
	v_pk_add_f32 v[36:37], v[46:47], v[64:65] op_sel_hi:[1,0]
	v_pk_fma_f32 v[32:33], v[32:33], v[38:39], v[32:33] neg_lo:[1,0,0] neg_hi:[1,0,0]
	s_nop 0
	v_pk_mul_f32 v[32:33], v[36:37], v[32:33]
	v_and_b32_sdwa v36, v35, v209 dst_sel:DWORD dst_unused:UNUSED_PAD src0_sel:WORD_1 src1_sel:DWORD
	v_and_b32_sdwa v37, v34, v209 dst_sel:DWORD dst_unused:UNUSED_PAD src0_sel:WORD_1 src1_sel:DWORD
	v_add3_u32 v34, v34, v37, s65
	v_add3_u32 v35, v35, v36, s65
	v_and_b32_sdwa v36, v33, v209 dst_sel:DWORD dst_unused:UNUSED_PAD src0_sel:WORD_1 src1_sel:DWORD
	v_and_b32_sdwa v37, v32, v209 dst_sel:DWORD dst_unused:UNUSED_PAD src0_sel:WORD_1 src1_sel:DWORD
	v_add3_u32 v33, v33, v36, s65
	v_add3_u32 v32, v32, v37, s65
	v_and_b32_e32 v33, 0xffff0000, v33
	v_and_b32_e32 v32, 0xffff0000, v32
	v_or_b32_sdwa v33, v33, v35 dst_sel:DWORD dst_unused:UNUSED_PAD src0_sel:DWORD src1_sel:WORD_1
	v_or_b32_sdwa v32, v32, v34 dst_sel:DWORD dst_unused:UNUSED_PAD src0_sel:DWORD src1_sel:WORD_1
	global_store_dwordx2 v[66:67], v[32:33], off offset:3184
	s_waitcnt vmcnt(15)
	v_mov_b32_e32 v32, v92
	v_mov_b32_e32 v33, v93
	v_lshlrev_b32_e32 v35, 16, v33
	v_lshlrev_b32_e32 v34, 16, v32
	v_pk_mul_f32 v[36:37], v[34:35], v[34:35]
	v_and_b32_e32 v33, 0xffff0000, v33
	v_fmamk_f32 v36, v36, 0x3dd2d3e7, v213
	v_fmamk_f32 v37, v37, 0x3dd2d3e7, v213
	v_mul_f32_e32 v36, v36, v34
	v_mul_f32_e32 v37, v37, v35
	v_exp_f32_e32 v36, v36
	v_exp_f32_e32 v37, v37
	v_and_b32_e32 v32, 0xffff0000, v32
	v_pk_mul_f32 v[38:39], v[32:33], v[32:33]
	v_add_f32_e32 v36, 1.0, v36
	v_add_f32_e32 v37, 1.0, v37
	v_rcp_f32_e32 v36, v36
	v_rcp_f32_e32 v37, v37
	v_fmamk_f32 v38, v38, 0x3dd2d3e7, v213
	v_mul_f32_e32 v38, v38, v32
	v_exp_f32_e32 v38, v38
	v_pk_fma_f32 v[34:35], v[34:35], v[36:37], v[34:35] neg_lo:[1,0,0] neg_hi:[1,0,0]
	v_mov_b32_e32 v36, v16
	v_fmamk_f32 v16, v39, 0x3dd2d3e7, v213
	v_mul_f32_e32 v16, v16, v33
	v_exp_f32_e32 v16, v16
	v_add_f32_e32 v38, 1.0, v38
	v_rcp_f32_e32 v38, v38
	v_mov_b32_e32 v37, v18
	v_add_f32_e32 v16, 1.0, v16
	v_rcp_f32_e32 v39, v16
	v_mov_b32_e32 v18, v17
	v_pk_add_f32 v[16:17], v[18:19], v[64:65] op_sel_hi:[1,0]
	v_pk_add_f32 v[36:37], v[36:37], v[64:65] op_sel_hi:[1,0]
	v_pk_fma_f32 v[32:33], v[32:33], v[38:39], v[32:33] neg_lo:[1,0,0] neg_hi:[1,0,0]
	v_pk_mul_f32 v[34:35], v[36:37], v[34:35]
	v_pk_mul_f32 v[16:17], v[16:17], v[32:33]
	v_and_b32_sdwa v18, v35, v209 dst_sel:DWORD dst_unused:UNUSED_PAD src0_sel:WORD_1 src1_sel:DWORD
	v_and_b32_sdwa v32, v17, v209 dst_sel:DWORD dst_unused:UNUSED_PAD src0_sel:WORD_1 src1_sel:DWORD
	v_and_b32_sdwa v33, v16, v209 dst_sel:DWORD dst_unused:UNUSED_PAD src0_sel:WORD_1 src1_sel:DWORD
	v_and_b32_sdwa v19, v34, v209 dst_sel:DWORD dst_unused:UNUSED_PAD src0_sel:WORD_1 src1_sel:DWORD
	v_add3_u32 v17, v17, v32, s65
	v_add3_u32 v16, v16, v33, s65
	v_add3_u32 v19, v34, v19, s65
	v_add3_u32 v18, v35, v18, s65
	v_and_b32_e32 v17, 0xffff0000, v17
	v_and_b32_e32 v16, 0xffff0000, v16
	v_or_b32_sdwa v17, v17, v18 dst_sel:DWORD dst_unused:UNUSED_PAD src0_sel:DWORD src1_sel:WORD_1
	v_or_b32_sdwa v16, v16, v19 dst_sel:DWORD dst_unused:UNUSED_PAD src0_sel:DWORD src1_sel:WORD_1
	global_store_dwordx2 v[66:67], v[16:17], off offset:3200
	s_waitcnt vmcnt(15)
	v_mov_b32_e32 v16, v94
	v_mov_b32_e32 v17, v95
	v_lshlrev_b32_e32 v19, 16, v17
	v_lshlrev_b32_e32 v18, 16, v16
	v_pk_mul_f32 v[32:33], v[18:19], v[18:19]
	v_and_b32_e32 v17, 0xffff0000, v17
	v_fmamk_f32 v32, v32, 0x3dd2d3e7, v213
	v_fmamk_f32 v33, v33, 0x3dd2d3e7, v213
	v_mul_f32_e32 v32, v32, v18
	v_mul_f32_e32 v33, v33, v19
	v_exp_f32_e32 v32, v32
	v_exp_f32_e32 v33, v33
	v_and_b32_e32 v16, 0xffff0000, v16
	v_pk_mul_f32 v[34:35], v[16:17], v[16:17]
	v_add_f32_e32 v32, 1.0, v32
	v_add_f32_e32 v33, 1.0, v33
	v_rcp_f32_e32 v32, v32
	v_rcp_f32_e32 v33, v33
	v_fmamk_f32 v34, v34, 0x3dd2d3e7, v213
	v_mul_f32_e32 v34, v34, v16
	v_exp_f32_e32 v34, v34
	v_pk_fma_f32 v[18:19], v[18:19], v[32:33], v[18:19] neg_lo:[1,0,0] neg_hi:[1,0,0]
	v_mov_b32_e32 v32, v20
	v_fmamk_f32 v20, v35, 0x3dd2d3e7, v213
	v_mul_f32_e32 v20, v20, v17
	v_exp_f32_e32 v20, v20
	v_add_f32_e32 v34, 1.0, v34
	v_rcp_f32_e32 v34, v34
	v_mov_b32_e32 v33, v22
	v_add_f32_e32 v20, 1.0, v20
	v_rcp_f32_e32 v35, v20
	v_pk_add_f32 v[32:33], v[32:33], v[64:65] op_sel_hi:[1,0]
	v_mov_b32_e32 v22, v21
	v_pk_mul_f32 v[18:19], v[32:33], v[18:19]
	v_pk_fma_f32 v[16:17], v[16:17], v[34:35], v[16:17] neg_lo:[1,0,0] neg_hi:[1,0,0]
	v_pk_add_f32 v[20:21], v[22:23], v[64:65] op_sel_hi:[1,0]
	s_nop 0
	v_pk_mul_f32 v[16:17], v[20:21], v[16:17]
	v_and_b32_sdwa v20, v19, v209 dst_sel:DWORD dst_unused:UNUSED_PAD src0_sel:WORD_1 src1_sel:DWORD
	v_and_b32_sdwa v21, v18, v209 dst_sel:DWORD dst_unused:UNUSED_PAD src0_sel:WORD_1 src1_sel:DWORD
	v_add3_u32 v18, v18, v21, s65
	v_add3_u32 v19, v19, v20, s65
	v_and_b32_sdwa v20, v17, v209 dst_sel:DWORD dst_unused:UNUSED_PAD src0_sel:WORD_1 src1_sel:DWORD
	v_and_b32_sdwa v21, v16, v209 dst_sel:DWORD dst_unused:UNUSED_PAD src0_sel:WORD_1 src1_sel:DWORD
	v_add3_u32 v17, v17, v20, s65
	v_add3_u32 v16, v16, v21, s65
	v_and_b32_e32 v17, 0xffff0000, v17
	v_and_b32_e32 v16, 0xffff0000, v16
	v_or_b32_sdwa v17, v17, v19 dst_sel:DWORD dst_unused:UNUSED_PAD src0_sel:DWORD src1_sel:WORD_1
	v_or_b32_sdwa v16, v16, v18 dst_sel:DWORD dst_unused:UNUSED_PAD src0_sel:DWORD src1_sel:WORD_1
	global_store_dwordx2 v[66:67], v[16:17], off offset:3216
	s_waitcnt vmcnt(15)
; __device__ __forceinline__ unsigned pack2(float a, float b) { return (unsigned)f2bf(a) | ((unsigned)f2bf(b) << 16); }
; __device__ __forceinline__ float bflo(unsigned u) { return __uint_as_float(u << 16); }
; __device__ __forceinline__ float bfhi(unsigned u) { return __uint_as_float(u & 0xffff0000u); }
; __device__ void sgu_task(const Params& p, int l, int n, int g, char* smem) {
;     ...
; #pragma unroll
;   for (int cb = 0; cb < 4; ++cb)
; #pragma unroll
;     for (int g4 = 0; g4 < 4; ++g4) {
;       uint2 uraw = *(const uint2*)(up + cb * 32 + 8 * g4);
;       float uv[4] = {bflo(uraw.x), bfhi(uraw.x), bflo(uraw.y), bfhi(uraw.y)};
;       float y[4];
; #pragma unroll
;       for (int j = 0; j < 4; ++j) y[j] = gelu_t(uv[j]) * (acc[cb][4 * g4 + j] + bias);
;       uint2 pk; pk.x = pack2(y[0], y[1]); pk.y = pack2(y[2], y[3]);
;       *(uint2*)(op + cb * 32 + 8 * g4) = pk;
;     }
	v_mov_b32_e32 v16, v96
	v_mov_b32_e32 v17, v97
	v_lshlrev_b32_e32 v19, 16, v17
	v_lshlrev_b32_e32 v18, 16, v16
	v_pk_mul_f32 v[20:21], v[18:19], v[18:19]
	v_and_b32_e32 v17, 0xffff0000, v17
	v_fmamk_f32 v20, v20, 0x3dd2d3e7, v213
	v_fmamk_f32 v21, v21, 0x3dd2d3e7, v213
	v_mul_f32_e32 v20, v20, v18
	v_mul_f32_e32 v21, v21, v19
	v_exp_f32_e32 v20, v20
	v_exp_f32_e32 v21, v21
	v_and_b32_e32 v16, 0xffff0000, v16
	v_pk_mul_f32 v[22:23], v[16:17], v[16:17]
	v_add_f32_e32 v20, 1.0, v20
	v_add_f32_e32 v21, 1.0, v21
	v_rcp_f32_e32 v20, v20
	v_rcp_f32_e32 v21, v21
	v_fmamk_f32 v22, v22, 0x3dd2d3e7, v213
	v_mul_f32_e32 v22, v22, v16
	v_exp_f32_e32 v22, v22
	v_pk_fma_f32 v[18:19], v[18:19], v[20:21], v[18:19] neg_lo:[1,0,0] neg_hi:[1,0,0]
	v_mov_b32_e32 v20, v24
	v_mov_b32_e32 v21, v26
	v_pk_add_f32 v[20:21], v[20:21], v[64:65] op_sel_hi:[1,0]
	v_add_f32_e32 v22, 1.0, v22
	v_pk_mul_f32 v[18:19], v[20:21], v[18:19]
	v_fmamk_f32 v20, v23, 0x3dd2d3e7, v213
	v_mul_f32_e32 v20, v20, v17
	v_exp_f32_e32 v20, v20
	v_rcp_f32_e32 v22, v22
	v_mov_b32_e32 v26, v25
	v_add_f32_e32 v20, 1.0, v20
	v_rcp_f32_e32 v23, v20
	v_pk_add_f32 v[20:21], v[26:27], v[64:65] op_sel_hi:[1,0]
	v_pk_fma_f32 v[16:17], v[16:17], v[22:23], v[16:17] neg_lo:[1,0,0] neg_hi:[1,0,0]
	s_nop 0
	v_pk_mul_f32 v[16:17], v[20:21], v[16:17]
	v_and_b32_sdwa v20, v19, v209 dst_sel:DWORD dst_unused:UNUSED_PAD src0_sel:WORD_1 src1_sel:DWORD
	v_and_b32_sdwa v21, v18, v209 dst_sel:DWORD dst_unused:UNUSED_PAD src0_sel:WORD_1 src1_sel:DWORD
	v_add3_u32 v18, v18, v21, s65
	v_add3_u32 v19, v19, v20, s65
	v_and_b32_sdwa v20, v17, v209 dst_sel:DWORD dst_unused:UNUSED_PAD src0_sel:WORD_1 src1_sel:DWORD
	v_and_b32_sdwa v21, v16, v209 dst_sel:DWORD dst_unused:UNUSED_PAD src0_sel:WORD_1 src1_sel:DWORD
	v_add3_u32 v17, v17, v20, s65
	v_add3_u32 v16, v16, v21, s65
	v_and_b32_e32 v17, 0xffff0000, v17
	v_and_b32_e32 v16, 0xffff0000, v16
	v_or_b32_sdwa v17, v17, v19 dst_sel:DWORD dst_unused:UNUSED_PAD src0_sel:DWORD src1_sel:WORD_1
	v_or_b32_sdwa v16, v16, v18 dst_sel:DWORD dst_unused:UNUSED_PAD src0_sel:DWORD src1_sel:WORD_1
	global_store_dwordx2 v[66:67], v[16:17], off offset:3232
	s_waitcnt vmcnt(15)
	v_mov_b32_e32 v16, v98
	v_mov_b32_e32 v17, v99
	v_lshlrev_b32_e32 v19, 16, v17
	v_lshlrev_b32_e32 v18, 16, v16
	v_pk_mul_f32 v[20:21], v[18:19], v[18:19]
	v_and_b32_e32 v17, 0xffff0000, v17
	v_fmamk_f32 v20, v20, 0x3dd2d3e7, v213
	v_fmamk_f32 v21, v21, 0x3dd2d3e7, v213
	v_mul_f32_e32 v20, v20, v18
	v_mul_f32_e32 v21, v21, v19
	v_exp_f32_e32 v20, v20
	v_exp_f32_e32 v21, v21
	v_and_b32_e32 v16, 0xffff0000, v16
	v_pk_mul_f32 v[22:23], v[16:17], v[16:17]
	v_add_f32_e32 v20, 1.0, v20
	v_add_f32_e32 v21, 1.0, v21
	v_rcp_f32_e32 v20, v20
	v_rcp_f32_e32 v21, v21
	v_fmamk_f32 v22, v22, 0x3dd2d3e7, v213
	v_mul_f32_e32 v22, v22, v16
	v_exp_f32_e32 v22, v22
	v_pk_fma_f32 v[18:19], v[18:19], v[20:21], v[18:19] neg_lo:[1,0,0] neg_hi:[1,0,0]
	v_mov_b32_e32 v20, v28
	v_mov_b32_e32 v21, v30
	v_pk_add_f32 v[20:21], v[20:21], v[64:65] op_sel_hi:[1,0]
	v_add_f32_e32 v22, 1.0, v22
	v_pk_mul_f32 v[18:19], v[20:21], v[18:19]
	v_fmamk_f32 v20, v23, 0x3dd2d3e7, v213
	v_mul_f32_e32 v20, v20, v17
	v_exp_f32_e32 v20, v20
	v_rcp_f32_e32 v22, v22
	v_mov_b32_e32 v30, v29
	v_add_f32_e32 v20, 1.0, v20
	v_rcp_f32_e32 v23, v20
	v_pk_add_f32 v[20:21], v[30:31], v[64:65] op_sel_hi:[1,0]
	v_pk_fma_f32 v[16:17], v[16:17], v[22:23], v[16:17] neg_lo:[1,0,0] neg_hi:[1,0,0]
	s_nop 0
	v_pk_mul_f32 v[16:17], v[20:21], v[16:17]
	v_and_b32_sdwa v20, v19, v209 dst_sel:DWORD dst_unused:UNUSED_PAD src0_sel:WORD_1 src1_sel:DWORD
	v_and_b32_sdwa v21, v18, v209 dst_sel:DWORD dst_unused:UNUSED_PAD src0_sel:WORD_1 src1_sel:DWORD
	v_add3_u32 v18, v18, v21, s65
	v_add3_u32 v19, v19, v20, s65
	v_and_b32_sdwa v20, v17, v209 dst_sel:DWORD dst_unused:UNUSED_PAD src0_sel:WORD_1 src1_sel:DWORD
	v_and_b32_sdwa v21, v16, v209 dst_sel:DWORD dst_unused:UNUSED_PAD src0_sel:WORD_1 src1_sel:DWORD
	v_add3_u32 v17, v17, v20, s65
	v_add3_u32 v16, v16, v21, s65
	v_and_b32_e32 v17, 0xffff0000, v17
	v_and_b32_e32 v16, 0xffff0000, v16
	v_or_b32_sdwa v17, v17, v19 dst_sel:DWORD dst_unused:UNUSED_PAD src0_sel:DWORD src1_sel:WORD_1
	v_or_b32_sdwa v16, v16, v18 dst_sel:DWORD dst_unused:UNUSED_PAD src0_sel:DWORD src1_sel:WORD_1
	global_store_dwordx2 v[66:67], v[16:17], off offset:3248
	s_waitcnt vmcnt(15)
	v_mov_b32_e32 v16, v100
	v_mov_b32_e32 v17, v101
	v_lshlrev_b32_e32 v19, 16, v17
	v_lshlrev_b32_e32 v18, 16, v16
	v_pk_mul_f32 v[20:21], v[18:19], v[18:19]
	v_and_b32_e32 v17, 0xffff0000, v17
	v_fmamk_f32 v20, v20, 0x3dd2d3e7, v213
	v_fmamk_f32 v21, v21, 0x3dd2d3e7, v213
	v_mul_f32_e32 v20, v20, v18
	v_mul_f32_e32 v21, v21, v19
	v_exp_f32_e32 v20, v20
	v_exp_f32_e32 v21, v21
	v_and_b32_e32 v16, 0xffff0000, v16
	v_pk_mul_f32 v[22:23], v[16:17], v[16:17]
	v_add_f32_e32 v20, 1.0, v20
	v_add_f32_e32 v21, 1.0, v21
	v_rcp_f32_e32 v20, v20
	v_rcp_f32_e32 v21, v21
	v_fmamk_f32 v22, v22, 0x3dd2d3e7, v213
	v_mul_f32_e32 v22, v22, v16
	v_exp_f32_e32 v22, v22
	v_pk_fma_f32 v[18:19], v[18:19], v[20:21], v[18:19] neg_lo:[1,0,0] neg_hi:[1,0,0]
	v_mov_b32_e32 v20, v0
	v_fmamk_f32 v0, v23, 0x3dd2d3e7, v213
	v_mul_f32_e32 v0, v0, v17
	v_exp_f32_e32 v0, v0
	v_add_f32_e32 v22, 1.0, v22
	v_rcp_f32_e32 v22, v22
	v_mov_b32_e32 v21, v2
	v_add_f32_e32 v0, 1.0, v0
	v_rcp_f32_e32 v23, v0
	v_mov_b32_e32 v2, v1
	v_pk_add_f32 v[0:1], v[2:3], v[64:65] op_sel_hi:[1,0]
	v_pk_add_f32 v[20:21], v[20:21], v[64:65] op_sel_hi:[1,0]
	v_pk_fma_f32 v[16:17], v[16:17], v[22:23], v[16:17] neg_lo:[1,0,0] neg_hi:[1,0,0]
	v_pk_mul_f32 v[18:19], v[20:21], v[18:19]
	v_pk_mul_f32 v[0:1], v[0:1], v[16:17]
	v_and_b32_sdwa v2, v19, v209 dst_sel:DWORD dst_unused:UNUSED_PAD src0_sel:WORD_1 src1_sel:DWORD
	v_and_b32_sdwa v16, v1, v209 dst_sel:DWORD dst_unused:UNUSED_PAD src0_sel:WORD_1 src1_sel:DWORD
	v_and_b32_sdwa v17, v0, v209 dst_sel:DWORD dst_unused:UNUSED_PAD src0_sel:WORD_1 src1_sel:DWORD
	v_and_b32_sdwa v3, v18, v209 dst_sel:DWORD dst_unused:UNUSED_PAD src0_sel:WORD_1 src1_sel:DWORD
	v_add3_u32 v1, v1, v16, s65
	v_add3_u32 v0, v0, v17, s65
	v_add3_u32 v3, v18, v3, s65
	v_add3_u32 v2, v19, v2, s65
	v_and_b32_e32 v1, 0xffff0000, v1
	v_and_b32_e32 v0, 0xffff0000, v0
	v_or_b32_sdwa v1, v1, v2 dst_sel:DWORD dst_unused:UNUSED_PAD src0_sel:DWORD src1_sel:WORD_1
	v_or_b32_sdwa v0, v0, v3 dst_sel:DWORD dst_unused:UNUSED_PAD src0_sel:DWORD src1_sel:WORD_1
	global_store_dwordx2 v[66:67], v[0:1], off offset:3264
	s_waitcnt vmcnt(15)
; __device__ __forceinline__ unsigned pack2(float a, float b) { return (unsigned)f2bf(a) | ((unsigned)f2bf(b) << 16); }
; __device__ __forceinline__ float bflo(unsigned u) { return __uint_as_float(u << 16); }
; __device__ __forceinline__ float bfhi(unsigned u) { return __uint_as_float(u & 0xffff0000u); }
; __device__ void sgu_task(const Params& p, int l, int n, int g, char* smem) {
;     ...
; #pragma unroll
;   for (int cb = 0; cb < 4; ++cb)
; #pragma unroll
;     for (int g4 = 0; g4 < 4; ++g4) {
;       uint2 uraw = *(const uint2*)(up + cb * 32 + 8 * g4);
;       float uv[4] = {bflo(uraw.x), bfhi(uraw.x), bflo(uraw.y), bfhi(uraw.y)};
;       float y[4];
; #pragma unroll
;       for (int j = 0; j < 4; ++j) y[j] = gelu_t(uv[j]) * (acc[cb][4 * g4 + j] + bias);
;       uint2 pk; pk.x = pack2(y[0], y[1]); pk.y = pack2(y[2], y[3]);
;       *(uint2*)(op + cb * 32 + 8 * g4) = pk;
;     }
; __device__ void phase_mixa(const Params& p, int l, char* smem) {
;     ...
;   for (int t0 = 0; t0 < 512; t0 += NVB) { int t = min(t0 + VB, 511); sgu_task(p, l, t >> 2, t & 3, sm); }
;   __syncthreads();
;   for (int t = VB; t < 1024; t += NVB) sb_task(p, t & 7, t >> 3, sm);
	v_mov_b32_e32 v0, v102
	v_mov_b32_e32 v1, v103
	v_lshlrev_b32_e32 v3, 16, v1
	v_lshlrev_b32_e32 v2, 16, v0
	v_pk_mul_f32 v[16:17], v[2:3], v[2:3]
	v_and_b32_e32 v1, 0xffff0000, v1
	v_fmamk_f32 v16, v16, 0x3dd2d3e7, v213
	v_fmamk_f32 v17, v17, 0x3dd2d3e7, v213
	v_mul_f32_e32 v16, v16, v2
	v_mul_f32_e32 v17, v17, v3
	v_exp_f32_e32 v16, v16
	v_exp_f32_e32 v17, v17
	v_and_b32_e32 v0, 0xffff0000, v0
	v_pk_mul_f32 v[18:19], v[0:1], v[0:1]
	v_add_f32_e32 v16, 1.0, v16
	v_add_f32_e32 v17, 1.0, v17
	v_rcp_f32_e32 v16, v16
	v_rcp_f32_e32 v17, v17
	v_fmamk_f32 v18, v18, 0x3dd2d3e7, v213
	v_mul_f32_e32 v18, v18, v0
	v_exp_f32_e32 v18, v18
	v_pk_fma_f32 v[2:3], v[2:3], v[16:17], v[2:3] neg_lo:[1,0,0] neg_hi:[1,0,0]
	v_mov_b32_e32 v16, v4
	v_fmamk_f32 v4, v19, 0x3dd2d3e7, v213
	v_mul_f32_e32 v4, v4, v1
	v_exp_f32_e32 v4, v4
	v_add_f32_e32 v18, 1.0, v18
	v_rcp_f32_e32 v18, v18
	v_mov_b32_e32 v17, v6
	v_add_f32_e32 v4, 1.0, v4
	v_rcp_f32_e32 v19, v4
	v_pk_add_f32 v[16:17], v[16:17], v[64:65] op_sel_hi:[1,0]
	v_mov_b32_e32 v6, v5
	v_pk_mul_f32 v[2:3], v[16:17], v[2:3]
	v_pk_fma_f32 v[0:1], v[0:1], v[18:19], v[0:1] neg_lo:[1,0,0] neg_hi:[1,0,0]
	v_pk_add_f32 v[4:5], v[6:7], v[64:65] op_sel_hi:[1,0]
	s_nop 0
	v_pk_mul_f32 v[0:1], v[4:5], v[0:1]
	v_and_b32_sdwa v4, v3, v209 dst_sel:DWORD dst_unused:UNUSED_PAD src0_sel:WORD_1 src1_sel:DWORD
	v_and_b32_sdwa v5, v2, v209 dst_sel:DWORD dst_unused:UNUSED_PAD src0_sel:WORD_1 src1_sel:DWORD
	v_add3_u32 v2, v2, v5, s65
	v_add3_u32 v3, v3, v4, s65
	v_and_b32_sdwa v4, v1, v209 dst_sel:DWORD dst_unused:UNUSED_PAD src0_sel:WORD_1 src1_sel:DWORD
	v_and_b32_sdwa v5, v0, v209 dst_sel:DWORD dst_unused:UNUSED_PAD src0_sel:WORD_1 src1_sel:DWORD
	v_add3_u32 v1, v1, v4, s65
	v_add3_u32 v0, v0, v5, s65
	v_and_b32_e32 v1, 0xffff0000, v1
	v_and_b32_e32 v0, 0xffff0000, v0
	v_or_b32_sdwa v1, v1, v3 dst_sel:DWORD dst_unused:UNUSED_PAD src0_sel:DWORD src1_sel:WORD_1
	v_or_b32_sdwa v0, v0, v2 dst_sel:DWORD dst_unused:UNUSED_PAD src0_sel:DWORD src1_sel:WORD_1
	global_store_dwordx2 v[66:67], v[0:1], off offset:3280
	s_waitcnt vmcnt(15)
	v_mov_b32_e32 v0, v104
	v_mov_b32_e32 v1, v105
	v_lshlrev_b32_e32 v3, 16, v1
	v_lshlrev_b32_e32 v2, 16, v0
	v_pk_mul_f32 v[4:5], v[2:3], v[2:3]
	v_and_b32_e32 v1, 0xffff0000, v1
	v_fmamk_f32 v4, v4, 0x3dd2d3e7, v213
	v_fmamk_f32 v5, v5, 0x3dd2d3e7, v213
	v_mul_f32_e32 v4, v4, v2
	v_mul_f32_e32 v5, v5, v3
	v_exp_f32_e32 v4, v4
	v_exp_f32_e32 v5, v5
	v_and_b32_e32 v0, 0xffff0000, v0
	v_pk_mul_f32 v[6:7], v[0:1], v[0:1]
	v_add_f32_e32 v4, 1.0, v4
	v_add_f32_e32 v5, 1.0, v5
	v_rcp_f32_e32 v4, v4
	v_rcp_f32_e32 v5, v5
	v_fmamk_f32 v6, v6, 0x3dd2d3e7, v213
	v_mul_f32_e32 v6, v6, v0
	v_exp_f32_e32 v6, v6
	v_pk_fma_f32 v[2:3], v[2:3], v[4:5], v[2:3] neg_lo:[1,0,0] neg_hi:[1,0,0]
	v_mov_b32_e32 v4, v8
	v_mov_b32_e32 v5, v10
	v_pk_add_f32 v[4:5], v[4:5], v[64:65] op_sel_hi:[1,0]
	v_add_f32_e32 v6, 1.0, v6
	v_pk_mul_f32 v[2:3], v[4:5], v[2:3]
	v_fmamk_f32 v4, v7, 0x3dd2d3e7, v213
	v_mul_f32_e32 v4, v4, v1
	v_exp_f32_e32 v4, v4
	v_rcp_f32_e32 v6, v6
	v_mov_b32_e32 v10, v9
	v_add_f32_e32 v4, 1.0, v4
	v_rcp_f32_e32 v7, v4
	v_pk_add_f32 v[4:5], v[10:11], v[64:65] op_sel_hi:[1,0]
	v_pk_fma_f32 v[0:1], v[0:1], v[6:7], v[0:1] neg_lo:[1,0,0] neg_hi:[1,0,0]
	s_nop 0
	v_pk_mul_f32 v[0:1], v[4:5], v[0:1]
	v_and_b32_sdwa v4, v3, v209 dst_sel:DWORD dst_unused:UNUSED_PAD src0_sel:WORD_1 src1_sel:DWORD
	v_and_b32_sdwa v5, v2, v209 dst_sel:DWORD dst_unused:UNUSED_PAD src0_sel:WORD_1 src1_sel:DWORD
	v_add3_u32 v2, v2, v5, s65
	v_add3_u32 v3, v3, v4, s65
	v_and_b32_sdwa v4, v1, v209 dst_sel:DWORD dst_unused:UNUSED_PAD src0_sel:WORD_1 src1_sel:DWORD
	v_and_b32_sdwa v5, v0, v209 dst_sel:DWORD dst_unused:UNUSED_PAD src0_sel:WORD_1 src1_sel:DWORD
	v_add3_u32 v1, v1, v4, s65
	v_add3_u32 v0, v0, v5, s65
	v_and_b32_e32 v1, 0xffff0000, v1
	v_and_b32_e32 v0, 0xffff0000, v0
	v_or_b32_sdwa v1, v1, v3 dst_sel:DWORD dst_unused:UNUSED_PAD src0_sel:DWORD src1_sel:WORD_1
	v_or_b32_sdwa v0, v0, v2 dst_sel:DWORD dst_unused:UNUSED_PAD src0_sel:DWORD src1_sel:WORD_1
	global_store_dwordx2 v[66:67], v[0:1], off offset:3296
	s_waitcnt vmcnt(15)
	v_mov_b32_e32 v0, v106
	v_mov_b32_e32 v1, v107
	v_lshlrev_b32_e32 v3, 16, v1
	v_lshlrev_b32_e32 v2, 16, v0
	v_pk_mul_f32 v[4:5], v[2:3], v[2:3]
	v_and_b32_e32 v1, 0xffff0000, v1
	v_fmamk_f32 v4, v4, 0x3dd2d3e7, v213
	v_fmamk_f32 v5, v5, 0x3dd2d3e7, v213
	v_mul_f32_e32 v4, v4, v2
	v_mul_f32_e32 v5, v5, v3
	v_exp_f32_e32 v4, v4
	v_exp_f32_e32 v5, v5
	v_and_b32_e32 v0, 0xffff0000, v0
	v_pk_mul_f32 v[6:7], v[0:1], v[0:1]
	v_add_f32_e32 v4, 1.0, v4
	v_add_f32_e32 v5, 1.0, v5
	v_rcp_f32_e32 v4, v4
	v_rcp_f32_e32 v5, v5
	v_fmamk_f32 v6, v6, 0x3dd2d3e7, v213
	v_mul_f32_e32 v6, v6, v0
	v_exp_f32_e32 v6, v6
	v_pk_fma_f32 v[2:3], v[2:3], v[4:5], v[2:3] neg_lo:[1,0,0] neg_hi:[1,0,0]
	v_mov_b32_e32 v4, v12
	v_mov_b32_e32 v5, v14
	v_pk_add_f32 v[4:5], v[4:5], v[64:65] op_sel_hi:[1,0]
	v_add_f32_e32 v6, 1.0, v6
	v_pk_mul_f32 v[2:3], v[4:5], v[2:3]
	v_fmamk_f32 v4, v7, 0x3dd2d3e7, v213
	v_mul_f32_e32 v4, v4, v1
	v_exp_f32_e32 v4, v4
	v_rcp_f32_e32 v6, v6
	v_mov_b32_e32 v14, v13
	v_add_f32_e32 v4, 1.0, v4
	v_rcp_f32_e32 v7, v4
	v_pk_add_f32 v[4:5], v[14:15], v[64:65] op_sel_hi:[1,0]
	v_pk_fma_f32 v[0:1], v[0:1], v[6:7], v[0:1] neg_lo:[1,0,0] neg_hi:[1,0,0]
	s_nop 0
	v_pk_mul_f32 v[0:1], v[4:5], v[0:1]
	v_and_b32_sdwa v4, v3, v209 dst_sel:DWORD dst_unused:UNUSED_PAD src0_sel:WORD_1 src1_sel:DWORD
	v_and_b32_sdwa v5, v2, v209 dst_sel:DWORD dst_unused:UNUSED_PAD src0_sel:WORD_1 src1_sel:DWORD
	v_add3_u32 v2, v2, v5, s65
	v_add3_u32 v3, v3, v4, s65
	v_and_b32_sdwa v4, v1, v209 dst_sel:DWORD dst_unused:UNUSED_PAD src0_sel:WORD_1 src1_sel:DWORD
	v_and_b32_sdwa v5, v0, v209 dst_sel:DWORD dst_unused:UNUSED_PAD src0_sel:WORD_1 src1_sel:DWORD
	v_add3_u32 v1, v1, v4, s65
	v_add3_u32 v0, v0, v5, s65
	v_and_b32_e32 v1, 0xffff0000, v1
	v_and_b32_e32 v0, 0xffff0000, v0
	v_or_b32_sdwa v1, v1, v3 dst_sel:DWORD dst_unused:UNUSED_PAD src0_sel:DWORD src1_sel:WORD_1
	v_or_b32_sdwa v0, v0, v2 dst_sel:DWORD dst_unused:UNUSED_PAD src0_sel:DWORD src1_sel:WORD_1
	global_store_dwordx2 v[66:67], v[0:1], off offset:3312
	s_cbranch_scc0 .LBB0_883
	v_mov_b32_e32 v0, v207
	s_barrier
	s_movk_i32 s0, 0x400
	v_ashrrev_i32_e32 v0, 8, v0
	v_add_u32_e32 v123, s61, v0
	v_cmp_gt_i32_e32 vcc, s0, v123
	v_xor_b32_e32 v122, 32, v219
	s_and_saveexec_b64 s[88:89], vcc
	v_readlane_b32 s20, v252, 0
	v_readlane_b32 s16, v250, 6
	v_readlane_b32 s24, v252, 4
	v_readlane_b32 s25, v252, 5
	v_readlane_b32 s26, v252, 6
	v_readlane_b32 s27, v252, 7
	v_readlane_b32 s17, v250, 7
	v_readlane_b32 s18, v250, 8
	v_readlane_b32 s19, v250, 9
	v_readlane_b32 s6, v250, 10
	v_readlane_b32 s21, v252, 1
	v_readlane_b32 s22, v252, 2
	v_readlane_b32 s23, v252, 3
	s_cbranch_execz .LBB0_899
	v_cmp_lt_i32_e32 vcc, v122, v121
	s_mov_b64 s[90:91], 0
	s_nop 0
	v_cndmask_b32_e32 v0, v219, v122, vcc
	v_lshlrev_b32_e32 v124, 2, v0
	s_branch .LBB0_892

; __device__ __forceinline__ int krow(int i, int hf) { return (i & 3) + 8 * (i >> 2) + 4 * hf; }
; __device__ __forceinline__ f32x16 mfma32(bf16x8 a, bf16x8 b, f32x16 c) { return __builtin_amdgcn_mfma_f32_32x32x16_bf16(a, b, c, 0, 0, 0); }
; __device__ void retout_task(const Params& p, int n, int hh, char* smem) {
;     ...
;   for (int sb = 0; sb <= w; ++sb) {
;     f32x16 X;
; #pragma unroll
;     for (int i = 0; i < 16; ++i) X[i] = 0.f;
;     bf16x8 kfc[8];
; #pragma unroll
;     for (int ks = 0; ks < 8; ++ks) kfc[ks] = kfn[ks];
;     {
;       const int sn = (sb < w) ? sb + 1 : sb;
;       const u16* kfp = p.KF + (long)(tok0 + sn * 32 + r) * 1024 + hh * 128 + 8 * hf;
;       __builtin_amdgcn_s_setprio(2);
; #pragma unroll
;       for (int ks = 0; ks < 8; ++ks) kfn[ks] = *(const bf16x8*)(kfp + 16 * ks);
;       __builtin_amdgcn_s_setprio(0);
;     }
; #pragma unroll
;     for (int ks = 0; ks < 8; ++ks) X = mfma32(kfc[ks], qf[ks], X);
;     float xv[16];
; #pragma unroll
;     for (int i = 0; i < 16; ++i) {
;       int s = sb * 32 + krow(i, hf);
;       int diff = c - s;
;       xv[i] = (diff >= 0) ? X[i] * exp2f(lg2 * (float)diff) : 0.f;
;     }
;     bf16x8 pb0 = pack8(xv), pb1 = pack8(xv + 8);
.LBB0_1010:
	s_add_i32 s28, s3, 1
	v_mov_b32_e32 v64, s3
	v_mov_b32_e32 v65, s28
	v_cmp_lt_u32_e32 vcc, s3, v234
	s_nop 1
	v_cndmask_b32_e32 v64, v64, v65, vcc
	v_lshl_add_u32 v64, v64, 5, v192
	v_ashrrev_i32_e32 v65, 31, v64
	v_lshlrev_b64 v[64:65], 11, v[64:65]
	v_lshl_add_u64 v[64:65], v[210:211], 0, v[64:65]
	s_setprio 2
	global_load_dwordx4 v[80:83], v[64:65], off
	global_load_dwordx4 v[84:87], v[64:65], off offset:32
	global_load_dwordx4 v[88:91], v[64:65], off offset:64
	global_load_dwordx4 v[92:95], v[64:65], off offset:96
	global_load_dwordx4 v[128:131], v[64:65], off offset:128
	global_load_dwordx4 v[132:135], v[64:65], off offset:160
	global_load_dwordx4 v[136:139], v[64:65], off offset:192
	global_load_dwordx4 v[140:143], v[64:65], off offset:224
	s_setprio 0
	s_waitcnt vmcnt(15)
	v_mfma_f32_32x32x16_bf16 v[64:79], v[144:147], v[96:99], 0
	v_add_u32_e32 v147, v235, v194
	v_cvt_f32_u32_e32 v144, v147
	v_add_u32_e32 v146, v235, v191
	v_mul_f32_e32 v145, v236, v144
	v_cmp_gt_f32_e32 vcc, s64, v145
	s_waitcnt vmcnt(14)
	v_mfma_f32_32x32x16_bf16 v[64:79], v[148:151], v[100:103], v[64:79]
	v_cndmask_b32_e32 v145, 0, v216, vcc
	v_fmac_f32_e32 v145, v236, v144
	v_exp_f32_e32 v144, v145
	v_cndmask_b32_e32 v145, 0, v217, vcc
	v_ldexp_f32 v144, v144, v145
	s_waitcnt vmcnt(13)
	v_mfma_f32_32x32x16_bf16 v[64:79], v[152:155], v[104:107], v[64:79]
	v_cvt_f32_u32_e32 v145, v146
	s_waitcnt vmcnt(5)
	v_mov_b64_e32 v[154:155], v[90:91]
	v_mov_b64_e32 v[152:153], v[88:89]
	v_mul_f32_e32 v148, v236, v145
	v_cmp_gt_f32_e32 vcc, s64, v148
	v_mfma_f32_32x32x16_bf16 v[64:79], v[156:159], v[108:111], v[64:79]
	s_nop 0
	v_cndmask_b32_e32 v148, 0, v216, vcc
	v_fmac_f32_e32 v148, v236, v145
	v_exp_f32_e32 v145, v148
	v_cndmask_b32_e32 v148, 0, v217, vcc
	v_cmp_lt_i32_e32 vcc, -1, v147
	v_add_u32_e32 v147, v196, v235
	v_ldexp_f32 v145, v145, v148
	v_mfma_f32_32x32x16_bf16 v[64:79], v[160:163], v[112:115], v[64:79]
	s_waitcnt vmcnt(4)
	v_mov_b64_e32 v[158:159], v[94:95]
	s_waitcnt vmcnt(3)
	v_mov_b64_e32 v[162:163], v[130:131]
	v_mov_b64_e32 v[156:157], v[92:93]
	v_mov_b64_e32 v[160:161], v[128:129]
	v_mfma_f32_32x32x16_bf16 v[64:79], v[164:167], v[116:119], v[64:79]
	s_waitcnt vmcnt(2)
	v_mov_b64_e32 v[166:167], v[134:135]
	v_mov_b64_e32 v[164:165], v[132:133]
	v_mfma_f32_32x32x16_bf16 v[64:79], v[168:171], v[120:123], v[64:79]
	s_waitcnt vmcnt(1)
	v_mov_b64_e32 v[170:171], v[138:139]
	v_mov_b64_e32 v[168:169], v[136:137]
	v_mfma_f32_32x32x16_bf16 v[64:79], v[172:175], v[124:127], v[64:79]
	s_waitcnt vmcnt(0)
	v_mov_b64_e32 v[174:175], v[142:143]
	v_mov_b64_e32 v[172:173], v[140:141]
	s_nop 8
	v_pk_mul_f32 v[64:65], v[144:145], v[64:65]
	s_nop 0
	v_cndmask_b32_e32 v144, 0, v64, vcc
	v_cvt_f32_u32_e32 v64, v147
	v_cmp_lt_i32_e32 vcc, -1, v146
	v_add_u32_e32 v146, v193, v235
	v_bfe_u32 v151, v144, 16, 1
	v_cndmask_b32_e32 v145, 0, v65, vcc
	v_mul_f32_e32 v65, v236, v64
	v_cmp_gt_f32_e32 vcc, s64, v65
	v_bfe_u32 v150, v145, 16, 1
	s_nop 0
	v_cndmask_b32_e32 v65, 0, v216, vcc
	v_fmac_f32_e32 v65, v236, v64
	v_exp_f32_e32 v64, v65
	v_cndmask_b32_e32 v65, 0, v217, vcc
	v_ldexp_f32 v64, v64, v65
	v_cvt_f32_u32_e32 v65, v146
	v_mul_f32_e32 v148, v236, v65
	v_cmp_gt_f32_e32 vcc, s64, v148
	s_nop 1
	v_cndmask_b32_e32 v148, 0, v216, vcc
	v_fmac_f32_e32 v148, v236, v65
	v_exp_f32_e32 v65, v148
	v_cndmask_b32_e32 v148, 0, v217, vcc
	v_cmp_lt_i32_e32 vcc, -1, v147
	v_add_u32_e32 v147, v198, v235
	v_ldexp_f32 v65, v65, v148
	v_pk_mul_f32 v[64:65], v[64:65], v[66:67]
	s_nop 0
	v_cndmask_b32_e32 v66, 0, v64, vcc
	v_cvt_f32_u32_e32 v64, v147
	v_cmp_lt_i32_e32 vcc, -1, v146
	v_add_u32_e32 v146, v195, v235
	s_nop 0
	v_cndmask_b32_e32 v67, 0, v65, vcc
	v_mul_f32_e32 v65, v236, v64
	v_cmp_gt_f32_e32 vcc, s64, v65
	s_nop 1
	v_cndmask_b32_e32 v65, 0, v216, vcc
	v_fmac_f32_e32 v65, v236, v64
	v_exp_f32_e32 v64, v65
	v_cndmask_b32_e32 v65, 0, v217, vcc
	v_ldexp_f32 v64, v64, v65
	v_cvt_f32_u32_e32 v65, v146
	v_mul_f32_e32 v148, v236, v65
	v_cmp_gt_f32_e32 vcc, s64, v148
	s_nop 1
	v_cndmask_b32_e32 v148, 0, v216, vcc
	v_fmac_f32_e32 v148, v236, v65
	v_exp_f32_e32 v65, v148
	v_cndmask_b32_e32 v148, 0, v217, vcc
	v_cmp_lt_i32_e32 vcc, -1, v147
	v_add_u32_e32 v147, v200, v235
	v_ldexp_f32 v65, v65, v148
	v_pk_mul_f32 v[64:65], v[64:65], v[68:69]
	s_nop 0
	v_cndmask_b32_e32 v68, 0, v64, vcc
	v_cvt_f32_u32_e32 v64, v147
	v_cmp_lt_i32_e32 vcc, -1, v146
	v_add_u32_e32 v146, v197, v235
	v_bfe_u32 v149, v68, 16, 1
	v_cndmask_b32_e32 v69, 0, v65, vcc
	v_mul_f32_e32 v65, v236, v64
	v_cmp_gt_f32_e32 vcc, s64, v65
	s_nop 1
	v_cndmask_b32_e32 v65, 0, v216, vcc
	v_fmac_f32_e32 v65, v236, v64
	v_exp_f32_e32 v64, v65
	v_cndmask_b32_e32 v65, 0, v217, vcc
	v_ldexp_f32 v64, v64, v65
	v_cvt_f32_u32_e32 v65, v146
	v_mul_f32_e32 v148, v236, v65
	v_cmp_gt_f32_e32 vcc, s64, v148
	s_nop 1
	v_cndmask_b32_e32 v148, 0, v216, vcc
	v_fmac_f32_e32 v148, v236, v65
	v_exp_f32_e32 v65, v148
	v_cndmask_b32_e32 v148, 0, v217, vcc
	v_cmp_lt_i32_e32 vcc, -1, v147
	v_ldexp_f32 v65, v65, v148
	v_pk_mul_f32 v[64:65], v[64:65], v[70:71]
	v_bfe_u32 v148, v69, 16, 1
	v_cndmask_b32_e32 v70, 0, v64, vcc
	v_cmp_lt_i32_e32 vcc, -1, v146
	v_bfe_u32 v147, v70, 16, 1
	v_bfe_u32 v64, v66, 16, 1
	v_cndmask_b32_e32 v71, 0, v65, vcc
	v_bfe_u32 v65, v67, 16, 1
	v_add3_u32 v65, v67, v65, s65
	v_add3_u32 v67, v70, v147, s65
	v_add_u32_e32 v147, v202, v235
	v_add3_u32 v64, v66, v64, s65
	v_add3_u32 v66, v68, v149, s65
	v_add3_u32 v68, v69, v148, s65
	v_add3_u32 v69, v144, v151, s65
	v_cvt_f32_u32_e32 v144, v147
	v_add3_u32 v70, v145, v150, s65
	v_bfe_u32 v146, v71, 16, 1
	v_add3_u32 v71, v71, v146, s65
	v_mul_f32_e32 v145, v236, v144
; __device__ __forceinline__ int krow(int i, int hf) { return (i & 3) + 8 * (i >> 2) + 4 * hf; }
; __device__ __forceinline__ f32x16 mfma32(bf16x8 a, bf16x8 b, f32x16 c) { return __builtin_amdgcn_mfma_f32_32x32x16_bf16(a, b, c, 0, 0, 0); }
; __device__ void retout_task(const Params& p, int n, int hh, char* smem) {
;     ...
;       int s = sb * 32 + krow(i, hf);
;       int diff = c - s;
;       xv[i] = (diff >= 0) ? X[i] * exp2f(lg2 * (float)diff) : 0.f;
;     }
;     bf16x8 pb0 = pack8(xv), pb1 = pack8(xv + 8);
; #pragma unroll
;     for (int mb = 0; mb < 4; ++mb) {
;       bf16x8 A0 = tr_frag<true>(Vt, 136, sb * 32, mb * 32, lane);
;       bf16x8 A1 = tr_frag<true>(Vt, 136, sb * 32 + 16, mb * 32, lane);
;       acc[mb] = mfma32(A0, pb0, acc[mb]);
;       acc[mb] = mfma32(A1, pb1, acc[mb]);
;     }
;   }
	v_cmp_gt_f32_e32 vcc, s64, v145
	v_add_u32_e32 v146, v199, v235
	v_perm_b32 v67, v71, v67, s12
	v_cndmask_b32_e32 v145, 0, v216, vcc
	v_fmac_f32_e32 v145, v236, v144
	v_exp_f32_e32 v144, v145
	v_cndmask_b32_e32 v145, 0, v217, vcc
	v_perm_b32 v65, v65, v64, s12
	v_perm_b32 v64, v70, v69, s12
	v_ldexp_f32 v144, v144, v145
	v_cvt_f32_u32_e32 v145, v146
	v_perm_b32 v66, v68, v66, s12
	v_mul_f32_e32 v148, v236, v145
	v_cmp_gt_f32_e32 vcc, s64, v148
	s_nop 1
	v_cndmask_b32_e32 v148, 0, v216, vcc
	v_fmac_f32_e32 v148, v236, v145
	v_exp_f32_e32 v145, v148
	v_cndmask_b32_e32 v148, 0, v217, vcc
	v_cmp_lt_i32_e32 vcc, -1, v147
	v_add_u32_e32 v147, v204, v235
	v_ldexp_f32 v145, v145, v148
	v_pk_mul_f32 v[72:73], v[144:145], v[72:73]
	s_nop 0
	v_cndmask_b32_e32 v144, 0, v72, vcc
	v_cvt_f32_u32_e32 v72, v147
	v_cmp_lt_i32_e32 vcc, -1, v146
	v_add_u32_e32 v146, v201, v235
	v_bfe_u32 v151, v144, 16, 1
	v_cndmask_b32_e32 v145, 0, v73, vcc
	v_mul_f32_e32 v73, v236, v72
	v_cmp_gt_f32_e32 vcc, s64, v73
	v_bfe_u32 v150, v145, 16, 1
	v_add3_u32 v144, v144, v151, s65
	v_cndmask_b32_e32 v73, 0, v216, vcc
	v_fmac_f32_e32 v73, v236, v72
	v_exp_f32_e32 v72, v73
	v_cndmask_b32_e32 v73, 0, v217, vcc
	v_add3_u32 v145, v145, v150, s65
	v_perm_b32 v68, v145, v144, s12
	v_ldexp_f32 v72, v72, v73
	v_cvt_f32_u32_e32 v73, v146
	v_mul_f32_e32 v148, v236, v73
	v_cmp_gt_f32_e32 vcc, s64, v148
	s_nop 1
	v_cndmask_b32_e32 v148, 0, v216, vcc
	v_fmac_f32_e32 v148, v236, v73
	v_exp_f32_e32 v73, v148
	v_cndmask_b32_e32 v148, 0, v217, vcc
	v_cmp_lt_i32_e32 vcc, -1, v147
	v_add_u32_e32 v147, v206, v235
	v_ldexp_f32 v73, v73, v148
	v_pk_mul_f32 v[72:73], v[72:73], v[74:75]
	s_nop 0
	v_cndmask_b32_e32 v74, 0, v72, vcc
	v_cvt_f32_u32_e32 v72, v147
	v_cmp_lt_i32_e32 vcc, -1, v146
	v_add_u32_e32 v146, v203, v235
	v_bfe_u32 v149, v74, 16, 1
	v_cndmask_b32_e32 v75, 0, v73, vcc
	v_mul_f32_e32 v73, v236, v72
	v_cmp_gt_f32_e32 vcc, s64, v73
	v_add3_u32 v74, v74, v149, s65
	s_nop 0
	v_cndmask_b32_e32 v73, 0, v216, vcc
	v_fmac_f32_e32 v73, v236, v72
	v_exp_f32_e32 v72, v73
	v_cndmask_b32_e32 v73, 0, v217, vcc
	v_ldexp_f32 v72, v72, v73
	v_cvt_f32_u32_e32 v73, v146
	v_mul_f32_e32 v148, v236, v73
	v_cmp_gt_f32_e32 vcc, s64, v148
	s_nop 1
	v_cndmask_b32_e32 v148, 0, v216, vcc
	v_fmac_f32_e32 v148, v236, v73
	v_exp_f32_e32 v73, v148
	v_cndmask_b32_e32 v148, 0, v217, vcc
	v_cmp_lt_i32_e32 vcc, -1, v147
	v_add_u32_e32 v147, v208, v235
	v_ldexp_f32 v73, v73, v148
	v_pk_mul_f32 v[72:73], v[72:73], v[76:77]
	s_nop 0
	v_cndmask_b32_e32 v76, 0, v72, vcc
	v_cvt_f32_u32_e32 v72, v147
	v_cmp_lt_i32_e32 vcc, -1, v146
	v_add_u32_e32 v146, v205, v235
	v_subrev_u32_e32 v235, 32, v235
	v_cndmask_b32_e32 v77, 0, v73, vcc
	v_mul_f32_e32 v73, v236, v72
	v_cmp_gt_f32_e32 vcc, s64, v73
	s_nop 1
	v_cndmask_b32_e32 v73, 0, v216, vcc
	v_fmac_f32_e32 v73, v236, v72
	v_exp_f32_e32 v72, v73
	v_cndmask_b32_e32 v73, 0, v217, vcc
	v_ldexp_f32 v72, v72, v73
	v_cvt_f32_u32_e32 v73, v146
	v_mul_f32_e32 v148, v236, v73
	v_cmp_gt_f32_e32 vcc, s64, v148
	s_nop 1
	v_cndmask_b32_e32 v148, 0, v216, vcc
	v_fmac_f32_e32 v148, v236, v73
	v_exp_f32_e32 v73, v148
	v_cndmask_b32_e32 v148, 0, v217, vcc
	v_cmp_lt_i32_e32 vcc, -1, v147
	v_bfe_u32 v147, v76, 16, 1
	v_ldexp_f32 v73, v73, v148
	v_pk_mul_f32 v[72:73], v[72:73], v[78:79]
	v_bfe_u32 v148, v75, 16, 1
	v_cndmask_b32_e32 v72, 0, v72, vcc
	v_cmp_lt_i32_e32 vcc, -1, v146
	v_bfe_u32 v79, v72, 16, 1
	v_bfe_u32 v146, v77, 16, 1
	v_cndmask_b32_e32 v73, 0, v73, vcc
	v_bfe_u32 v78, v73, 16, 1
	v_add3_u32 v75, v75, v148, s65
	v_add3_u32 v76, v76, v147, s65
	v_add3_u32 v77, v77, v146, s65
	v_add3_u32 v72, v72, v79, s65
	v_add3_u32 v73, v73, v78, s65
	v_perm_b32 v71, v73, v72, s12
	v_perm_b32 v70, v77, v76, s12
	v_perm_b32 v69, v75, v74, s12
	ds_read_b64_tr_b16 v[72:73], v176
	ds_read_b64_tr_b16 v[74:75], v176 offset:2176
	ds_read_b64_tr_b16 v[76:77], v176 offset:4352
	ds_read_b64_tr_b16 v[78:79], v176 offset:6528
	s_waitcnt lgkmcnt(2)
	v_mfma_f32_32x32x16_bf16 v[48:63], v[72:75], v[64:67], v[48:63]
	v_cmp_eq_u32_e32 vcc, s3, v234
	v_mov_b64_e32 v[146:147], v[82:83]
	v_mov_b64_e32 v[150:151], v[86:87]
	s_or_b64 s[0:1], vcc, s[0:1]
	v_mov_b64_e32 v[144:145], v[80:81]
	v_mov_b64_e32 v[148:149], v[84:85]
	s_mov_b32 s3, s28
	s_waitcnt lgkmcnt(0)
	v_mfma_f32_32x32x16_bf16 v[48:63], v[76:79], v[68:71], v[48:63]
	ds_read_b64_tr_b16 v[72:73], v176 offset:64
	ds_read_b64_tr_b16 v[74:75], v176 offset:2240
	ds_read_b64_tr_b16 v[76:77], v176 offset:4416
	ds_read_b64_tr_b16 v[78:79], v176 offset:6592
	s_waitcnt lgkmcnt(2)
	v_mfma_f32_32x32x16_bf16 v[32:47], v[72:75], v[64:67], v[32:47]
	s_waitcnt lgkmcnt(0)
	v_mfma_f32_32x32x16_bf16 v[32:47], v[76:79], v[68:71], v[32:47]
	ds_read_b64_tr_b16 v[72:73], v176 offset:128
	ds_read_b64_tr_b16 v[74:75], v176 offset:2304
	ds_read_b64_tr_b16 v[76:77], v176 offset:4480
	ds_read_b64_tr_b16 v[78:79], v176 offset:6656
	s_waitcnt lgkmcnt(2)
	v_mfma_f32_32x32x16_bf16 v[16:31], v[72:75], v[64:67], v[16:31]
	s_waitcnt lgkmcnt(0)
	v_mfma_f32_32x32x16_bf16 v[16:31], v[76:79], v[68:71], v[16:31]
	ds_read_b64_tr_b16 v[72:73], v176 offset:192
	ds_read_b64_tr_b16 v[74:75], v176 offset:2368
	ds_read_b64_tr_b16 v[76:77], v176 offset:4544
	ds_read_b64_tr_b16 v[78:79], v176 offset:6720
	v_add_u32_e32 v176, 0x2200, v176
	s_waitcnt lgkmcnt(2)
	v_mfma_f32_32x32x16_bf16 v[0:15], v[72:75], v[64:67], v[0:15]
	s_waitcnt lgkmcnt(0)
	v_mfma_f32_32x32x16_bf16 v[0:15], v[76:79], v[68:71], v[0:15]
	s_andn2_b64 exec, exec, s[0:1]
	s_cbranch_execnz .LBB0_1010
; __device__ __forceinline__ unsigned pack2(float a, float b) { return (unsigned)f2bf(a) | ((unsigned)f2bf(b) << 16); }
; __device__ __forceinline__ float bflo(unsigned u) { return __uint_as_float(u << 16); }
; __device__ __forceinline__ float bfhi(unsigned u) { return __uint_as_float(u & 0xffff0000u); }
; __device__ __forceinline__ float shx(float v, int m) { return __shfl_xor(v, m, 64); }
; __device__ void retout_task(const Params& p, int n, int hh, char* smem) {
;     ...
;   float sum = 0.f;
; #pragma unroll
;   for (int mb = 0; mb < 4; ++mb)
; #pragma unroll
;     for (int i = 0; i < 16; ++i) sum += acc[mb][i];
;   sum += shx(sum, 32);
;   float mu = sum * (1.f / 128.f), q = 0.f;
; #pragma unroll
;   for (int mb = 0; mb < 4; ++mb)
; #pragma unroll
;     for (int i = 0; i < 16; ++i) { float d = acc[mb][i] - mu; q += d * d; }
;   q += shx(q, 32);
;   float rstd = rsqrtf(q * (1.f / 128.f) + LN_EPS);
;   const u16* gp = p.H + (long)pos * INC + 4608 + hh * 128;
;   u16* op = p.MIXIN + (long)pos * D_ + 512 + hh * 128;
; #pragma unroll
;   for (int mb = 0; mb < 4; ++mb)
; #pragma unroll
;     for (int g4 = 0; g4 < 4; ++g4) {
;       int e0 = mb * 32 + 8 * g4 + 4 * hf;
;       uint2 graw = *(const uint2*)(gp + e0);
;       float gv[4] = {bflo(graw.x), bfhi(graw.x), bflo(graw.y), bfhi(graw.y)};
;       float y[4];
; #pragma unroll
;       for (int j = 0; j < 4; ++j) {
;         float yn = (acc[mb][4 * g4 + j] - mu) * rstd;
;         float sg = gv[j] / (1.f + __expf(-gv[j]));
;         y[j] = sg * yn;
;       }
;       uint2 pk; pk.x = pack2(y[0], y[1]); pk.y = pack2(y[2], y[3]);
;       *(uint2*)(op + e0) = pk;
	s_or_b64 exec, exec, s[0:1]
	v_add_f32_e32 v64, 0, v48
	v_add_f32_e32 v64, v49, v64
	v_add_f32_e32 v64, v50, v64
	v_add_f32_e32 v64, v51, v64
	v_add_f32_e32 v64, v52, v64
	v_add_f32_e32 v64, v53, v64
	v_add_f32_e32 v64, v54, v64
	v_add_f32_e32 v64, v55, v64
	v_add_f32_e32 v64, v56, v64
	v_add_f32_e32 v64, v57, v64
	v_add_f32_e32 v64, v58, v64
	v_add_f32_e32 v64, v59, v64
	v_add_f32_e32 v64, v60, v64
	v_add_f32_e32 v64, v61, v64
	v_add_f32_e32 v64, v62, v64
	v_add_f32_e32 v64, v63, v64
	v_add_f32_e32 v64, v32, v64
	v_add_f32_e32 v64, v33, v64
	v_add_f32_e32 v64, v34, v64
	v_add_f32_e32 v64, v35, v64
	v_add_f32_e32 v64, v36, v64
	v_add_f32_e32 v64, v37, v64
	v_add_f32_e32 v64, v38, v64
	v_add_f32_e32 v64, v39, v64
	v_add_f32_e32 v64, v40, v64
	v_add_f32_e32 v64, v41, v64
	v_add_f32_e32 v64, v42, v64
	v_add_f32_e32 v64, v43, v64
	v_add_f32_e32 v64, v44, v64
	v_add_f32_e32 v64, v45, v64
	v_add_f32_e32 v64, v46, v64
	v_add_f32_e32 v64, v47, v64
	v_add_f32_e32 v64, v16, v64
	v_add_f32_e32 v64, v17, v64
	v_add_f32_e32 v64, v18, v64
	v_add_f32_e32 v64, v19, v64
	v_add_f32_e32 v64, v20, v64
	v_add_f32_e32 v64, v21, v64
	v_add_f32_e32 v64, v22, v64
	v_add_f32_e32 v64, v23, v64
	v_add_f32_e32 v64, v24, v64
	v_add_f32_e32 v64, v25, v64
	v_add_f32_e32 v64, v26, v64
	v_add_f32_e32 v64, v27, v64
	v_add_f32_e32 v64, v28, v64
	v_add_f32_e32 v64, v29, v64
	v_add_f32_e32 v64, v30, v64
	v_add_f32_e32 v64, v31, v64
	v_add_f32_e32 v64, v0, v64
	v_add_f32_e32 v64, v1, v64
	v_add_f32_e32 v64, v2, v64
	v_add_f32_e32 v64, v3, v64
	v_add_f32_e32 v64, v4, v64
	v_add_f32_e32 v64, v5, v64
	v_add_f32_e32 v64, v6, v64
	v_add_f32_e32 v64, v7, v64
	v_add_f32_e32 v64, v8, v64
	v_add_f32_e32 v64, v9, v64
	v_add_f32_e32 v64, v10, v64
	v_add_f32_e32 v64, v11, v64
	v_add_f32_e32 v64, v12, v64
	v_add_f32_e32 v64, v13, v64
	v_add_f32_e32 v64, v14, v64
	v_add_f32_e32 v64, v15, v64
	ds_bpermute_b32 v65, v232, v64
	v_lshlrev_b64 v[66:67], 12, v[186:187]
	v_lshlrev_b32_e32 v176, 1, v190
	v_lshl_add_u64 v[66:67], s[58:59], 0, v[66:67]
	v_lshl_add_u64 v[70:71], v[66:67], 0, v[176:177]
	s_waitcnt lgkmcnt(0)
	v_add_f32_e32 v64, v64, v65
	v_mul_f32_e32 v68, 0x3c000000, v64
	v_lshl_add_u64 v[64:65], v[188:189], 0, v[176:177]
	v_lshlrev_b32_e32 v176, 3, v233
	v_lshl_add_u64 v[74:75], v[64:65], 0, v[176:177]
	v_lshl_add_u64 v[64:65], v[70:71], 0, v[176:177]
	v_mov_b32_e32 v70, v48
	v_add_co_u32_e32 v48, vcc, s50, v74
	v_mov_b32_e32 v71, v50
	v_mov_b32_e32 v50, v49
	v_addc_co_u32_e32 v49, vcc, 0, v75, vcc
	global_load_dwordx2 v[48:49], v[48:49], off offset:1024
	s_mov_b64 s[0:1], 0x2400
	v_lshl_add_u64 v[66:67], v[74:75], 0, s[0:1]
	global_load_dwordx2 v[136:137], v[66:67], off offset:16
	global_load_dwordx2 v[138:139], v[66:67], off offset:32
	global_load_dwordx2 v[140:141], v[66:67], off offset:48
	global_load_dwordx2 v[142:143], v[66:67], off offset:64
	global_load_dwordx2 v[144:145], v[66:67], off offset:80
	global_load_dwordx2 v[146:147], v[66:67], off offset:96
	global_load_dwordx2 v[148:149], v[66:67], off offset:112
	global_load_dwordx2 v[150:151], v[66:67], off offset:128
	global_load_dwordx2 v[152:153], v[66:67], off offset:144
	global_load_dwordx2 v[154:155], v[66:67], off offset:160
	global_load_dwordx2 v[156:157], v[66:67], off offset:176
	global_load_dwordx2 v[158:159], v[66:67], off offset:192
	global_load_dwordx2 v[160:161], v[66:67], off offset:208
	global_load_dwordx2 v[162:163], v[66:67], off offset:224
	global_load_dwordx2 v[164:165], v[66:67], off offset:240
	v_pk_add_f32 v[70:71], v[70:71], v[68:69] op_sel_hi:[1,0] neg_lo:[0,1] neg_hi:[0,1]
	v_pk_add_f32 v[72:73], v[50:51], v[68:69] op_sel_hi:[1,0] neg_lo:[0,1] neg_hi:[0,1]
	v_pk_mul_f32 v[76:77], v[70:71], v[70:71]
	v_pk_mul_f32 v[78:79], v[72:73], v[72:73]
	s_add_i32 s2, s2, s33
	s_cmpk_lt_i32 s2, 0x400
	s_waitcnt vmcnt(15)
	v_and_b32_e32 v75, 0xffff0000, v48
	v_lshlrev_b32_e32 v51, 16, v49
	v_lshlrev_b32_e32 v69, 16, v48
	v_and_b32_e32 v74, 0xffff0000, v49
	v_mul_f32_e32 v49, 0xbfb8aa3b, v75
	v_mul_f32_e32 v48, 0xbfb8aa3b, v69
	v_exp_f32_e32 v50, v49
	v_mul_f32_e32 v49, 0xbfb8aa3b, v51
	v_exp_f32_e32 v48, v48
	v_exp_f32_e32 v49, v49
	s_nop 0
	v_pk_add_f32 v[48:49], v[48:49], 1.0 op_sel_hi:[1,0]
	s_nop 0
	v_div_scale_f32 v80, s[0:1], v49, v49, v51
	v_rcp_f32_e32 v81, v80
	s_nop 0
	v_fma_f32 v82, -v80, v81, 1.0
	v_fmac_f32_e32 v81, v82, v81
	v_div_scale_f32 v82, vcc, v51, v49, v51
	v_mul_f32_e32 v83, v82, v81
	v_fma_f32 v84, -v80, v83, v82
	v_fmac_f32_e32 v83, v84, v81
	v_fma_f32 v80, -v80, v83, v82
	v_div_fmas_f32 v80, v80, v81, v83
	v_div_fixup_f32 v85, v80, v49, v51
	v_div_scale_f32 v49, s[0:1], v48, v48, v69
	v_rcp_f32_e32 v51, v49
	s_nop 0
	v_fma_f32 v80, -v49, v51, 1.0
	v_fmac_f32_e32 v51, v80, v51
	v_div_scale_f32 v80, vcc, v69, v48, v69
	v_mul_f32_e32 v81, v80, v51
	v_fma_f32 v82, -v49, v81, v80
	v_fmac_f32_e32 v81, v82, v51
	v_fma_f32 v49, -v49, v81, v80
	v_div_fmas_f32 v49, v49, v51, v81
	v_div_fixup_f32 v84, v49, v48, v69
	v_mul_f32_e32 v48, 0xbfb8aa3b, v74
	v_exp_f32_e32 v51, v48
	s_nop 0
	v_pk_add_f32 v[48:49], v[50:51], 1.0 op_sel_hi:[1,0]
	s_nop 0
	v_div_scale_f32 v50, s[0:1], v49, v49, v74
	v_rcp_f32_e32 v51, v50
	s_nop 0
	v_fma_f32 v69, -v50, v51, 1.0
	v_fmac_f32_e32 v51, v69, v51
	v_div_scale_f32 v69, vcc, v74, v49, v74
	v_mul_f32_e32 v80, v69, v51
	v_fma_f32 v81, -v50, v80, v69
	v_fmac_f32_e32 v80, v81, v51
	v_fma_f32 v50, -v50, v80, v69
	v_div_fmas_f32 v50, v50, v51, v80
	v_div_fixup_f32 v89, v50, v49, v74
	v_div_scale_f32 v49, s[0:1], v48, v48, v75
	v_rcp_f32_e32 v50, v49
	s_nop 0
	v_fma_f32 v51, -v49, v50, 1.0
	v_fmac_f32_e32 v50, v51, v50
	v_div_scale_f32 v51, vcc, v75, v48, v75
; __device__ __forceinline__ float shx(float v, int m) { return __shfl_xor(v, m, 64); }
; __device__ void retout_task(const Params& p, int n, int hh, char* smem) {
;     ...
;   float mu = sum * (1.f / 128.f), q = 0.f;
; #pragma unroll
;   for (int mb = 0; mb < 4; ++mb)
; #pragma unroll
;     for (int i = 0; i < 16; ++i) { float d = acc[mb][i] - mu; q += d * d; }
;   q += shx(q, 32);
	v_mul_f32_e32 v69, v51, v50
	v_fma_f32 v74, -v49, v69, v51
	v_fmac_f32_e32 v69, v74, v50
	v_fma_f32 v49, -v49, v69, v51
	v_div_fmas_f32 v49, v49, v50, v69
	v_div_fixup_f32 v88, v49, v48, v75
	v_mov_b32_e32 v48, v52
	v_mov_b32_e32 v49, v54
	v_pk_add_f32 v[90:91], v[48:49], v[68:69] op_sel_hi:[1,0] neg_lo:[0,1] neg_hi:[0,1]
	v_mov_b32_e32 v48, v56
	v_mov_b32_e32 v49, v58
	v_pk_add_f32 v[82:83], v[48:49], v[68:69] op_sel_hi:[1,0] neg_lo:[0,1] neg_hi:[0,1]
	v_mov_b32_e32 v48, v60
	v_mov_b32_e32 v49, v62
	v_pk_add_f32 v[74:75], v[48:49], v[68:69] op_sel_hi:[1,0] neg_lo:[0,1] neg_hi:[0,1]
	v_mov_b32_e32 v48, v32
	v_mov_b32_e32 v49, v34
	v_mov_b32_e32 v34, v33
	v_mov_b32_e32 v32, v36
	v_mov_b32_e32 v33, v38
	v_mov_b32_e32 v58, v57
	v_pk_add_f32 v[56:57], v[32:33], v[68:69] op_sel_hi:[1,0] neg_lo:[0,1] neg_hi:[0,1]
	v_mov_b32_e32 v32, v40
	v_mov_b32_e32 v33, v42
	v_mov_b32_e32 v54, v53
	v_pk_add_f32 v[52:53], v[32:33], v[68:69] op_sel_hi:[1,0] neg_lo:[0,1] neg_hi:[0,1]
	v_mov_b32_e32 v32, v44
	v_mov_b32_e32 v33, v46
	v_mov_b32_e32 v62, v61
	v_pk_add_f32 v[60:61], v[48:49], v[68:69] op_sel_hi:[1,0] neg_lo:[0,1] neg_hi:[0,1]
	v_pk_add_f32 v[48:49], v[32:33], v[68:69] op_sel_hi:[1,0] neg_lo:[0,1] neg_hi:[0,1]
	v_mov_b32_e32 v32, v16
	v_mov_b32_e32 v33, v18
	v_mov_b32_e32 v18, v17
	v_mov_b32_e32 v16, v20
	v_mov_b32_e32 v17, v22
	v_mov_b32_e32 v42, v41
	v_pk_add_f32 v[40:41], v[16:17], v[68:69] op_sel_hi:[1,0] neg_lo:[0,1] neg_hi:[0,1]
	v_mov_b32_e32 v16, v24
	v_mov_b32_e32 v17, v26
	v_mov_b32_e32 v38, v37
	v_pk_add_f32 v[36:37], v[16:17], v[68:69] op_sel_hi:[1,0] neg_lo:[0,1] neg_hi:[0,1]
	v_mov_b32_e32 v16, v28
	v_mov_b32_e32 v17, v30
	v_mov_b32_e32 v46, v45
	v_pk_add_f32 v[44:45], v[32:33], v[68:69] op_sel_hi:[1,0] neg_lo:[0,1] neg_hi:[0,1]
	v_pk_add_f32 v[32:33], v[16:17], v[68:69] op_sel_hi:[1,0] neg_lo:[0,1] neg_hi:[0,1]
	v_mov_b32_e32 v16, v0
	v_mov_b32_e32 v17, v2
	v_mov_b32_e32 v2, v1
	v_mov_b32_e32 v0, v4
	v_mov_b32_e32 v1, v6
	v_mov_b32_e32 v6, v5
	v_pk_add_f32 v[50:51], v[42:43], v[68:69] op_sel_hi:[1,0] neg_lo:[0,1] neg_hi:[0,1]
	v_pk_add_f32 v[42:43], v[18:19], v[68:69] op_sel_hi:[1,0] neg_lo:[0,1] neg_hi:[0,1]
	v_mov_b32_e32 v22, v21
	v_pk_add_f32 v[20:21], v[0:1], v[68:69] op_sel_hi:[1,0] neg_lo:[0,1] neg_hi:[0,1]
	v_pk_add_f32 v[18:19], v[6:7], v[68:69] op_sel_hi:[1,0] neg_lo:[0,1] neg_hi:[0,1]
	v_mov_b32_e32 v1, v21
	v_mov_b32_e32 v0, v19
	v_pk_mul_f32 v[4:5], v[0:1], v[0:1]
	v_mov_b32_e32 v0, v8
	v_mov_b32_e32 v1, v10
	v_mov_b32_e32 v10, v9
	v_mov_b32_e32 v26, v25
	v_pk_add_f32 v[24:25], v[16:17], v[68:69] op_sel_hi:[1,0] neg_lo:[0,1] neg_hi:[0,1]
	v_pk_add_f32 v[16:17], v[0:1], v[68:69] op_sel_hi:[1,0] neg_lo:[0,1] neg_hi:[0,1]
	v_pk_add_f32 v[6:7], v[10:11], v[68:69] op_sel_hi:[1,0] neg_lo:[0,1] neg_hi:[0,1]
	v_mov_b32_e32 v1, v16
	v_mov_b32_e32 v0, v6
	v_pk_mul_f32 v[8:9], v[0:1], v[0:1]
	v_mov_b32_e32 v0, v7
	v_mov_b32_e32 v1, v17
	v_mov_b32_e32 v30, v29
	v_pk_mul_f32 v[10:11], v[0:1], v[0:1]
	v_mov_b32_e32 v0, v12
	v_mov_b32_e32 v1, v14
	v_mov_b32_e32 v14, v13
	v_pk_add_f32 v[86:87], v[54:55], v[68:69] op_sel_hi:[1,0] neg_lo:[0,1] neg_hi:[0,1]
	v_pk_add_f32 v[80:81], v[58:59], v[68:69] op_sel_hi:[1,0] neg_lo:[0,1] neg_hi:[0,1]
	v_pk_add_f32 v[62:63], v[62:63], v[68:69] op_sel_hi:[1,0] neg_lo:[0,1] neg_hi:[0,1]
	v_pk_add_f32 v[58:59], v[34:35], v[68:69] op_sel_hi:[1,0] neg_lo:[0,1] neg_hi:[0,1]
	v_pk_add_f32 v[54:55], v[38:39], v[68:69] op_sel_hi:[1,0] neg_lo:[0,1] neg_hi:[0,1]
	v_pk_add_f32 v[46:47], v[46:47], v[68:69] op_sel_hi:[1,0] neg_lo:[0,1] neg_hi:[0,1]
	v_pk_add_f32 v[38:39], v[22:23], v[68:69] op_sel_hi:[1,0] neg_lo:[0,1] neg_hi:[0,1]
	v_pk_add_f32 v[34:35], v[26:27], v[68:69] op_sel_hi:[1,0] neg_lo:[0,1] neg_hi:[0,1]
	v_pk_add_f32 v[26:27], v[30:31], v[68:69] op_sel_hi:[1,0] neg_lo:[0,1] neg_hi:[0,1]
	v_pk_add_f32 v[22:23], v[2:3], v[68:69] op_sel_hi:[1,0] neg_lo:[0,1] neg_hi:[0,1]
	v_pk_add_f32 v[2:3], v[0:1], v[68:69] op_sel_hi:[1,0] neg_lo:[0,1] neg_hi:[0,1]
	v_pk_add_f32 v[0:1], v[14:15], v[68:69] op_sel_hi:[1,0] neg_lo:[0,1] neg_hi:[0,1]
	v_add_f32_e32 v68, v76, v78
	v_add_f32_e32 v68, v77, v68
	v_pk_mul_f32 v[92:93], v[90:91], v[90:91]
	v_add_f32_e32 v68, v79, v68
	v_pk_mul_f32 v[94:95], v[86:87], v[86:87]
	v_add_f32_e32 v68, v92, v68
	v_add_f32_e32 v68, v94, v68
	v_add_f32_e32 v68, v93, v68
	v_pk_mul_f32 v[96:97], v[82:83], v[82:83]
	v_add_f32_e32 v68, v95, v68
	v_pk_mul_f32 v[98:99], v[80:81], v[80:81]
	v_add_f32_e32 v68, v96, v68
	v_add_f32_e32 v68, v98, v68
	v_add_f32_e32 v68, v97, v68
	v_pk_mul_f32 v[100:101], v[74:75], v[74:75]
	v_add_f32_e32 v68, v99, v68
	v_pk_mul_f32 v[102:103], v[62:63], v[62:63]
	v_add_f32_e32 v68, v100, v68
	v_add_f32_e32 v68, v102, v68
	v_add_f32_e32 v68, v101, v68
	v_pk_mul_f32 v[104:105], v[60:61], v[60:61]
	v_add_f32_e32 v68, v103, v68
	v_pk_mul_f32 v[106:107], v[58:59], v[58:59]
	v_add_f32_e32 v68, v104, v68
	v_add_f32_e32 v68, v106, v68
	v_add_f32_e32 v68, v105, v68
	v_pk_mul_f32 v[108:109], v[56:57], v[56:57]
	v_add_f32_e32 v68, v107, v68
	v_pk_mul_f32 v[110:111], v[54:55], v[54:55]
	v_add_f32_e32 v68, v108, v68
	v_add_f32_e32 v68, v110, v68
	v_add_f32_e32 v68, v109, v68
	v_pk_mul_f32 v[112:113], v[52:53], v[52:53]
	v_add_f32_e32 v68, v111, v68
	v_pk_mul_f32 v[114:115], v[50:51], v[50:51]
	v_add_f32_e32 v68, v112, v68
	v_add_f32_e32 v68, v114, v68
	v_add_f32_e32 v68, v113, v68
	v_pk_mul_f32 v[116:117], v[48:49], v[48:49]
	v_add_f32_e32 v68, v115, v68
	v_pk_mul_f32 v[118:119], v[46:47], v[46:47]
	v_add_f32_e32 v68, v116, v68
	v_add_f32_e32 v68, v118, v68
	v_add_f32_e32 v68, v117, v68
	v_pk_mul_f32 v[120:121], v[44:45], v[44:45]
	v_add_f32_e32 v68, v119, v68
; __device__ __forceinline__ unsigned pack2(float a, float b) { return (unsigned)f2bf(a) | ((unsigned)f2bf(b) << 16); }
; __device__ __forceinline__ float bflo(unsigned u) { return __uint_as_float(u << 16); }
; __device__ __forceinline__ float bfhi(unsigned u) { return __uint_as_float(u & 0xffff0000u); }
; __device__ __forceinline__ float shx(float v, int m) { return __shfl_xor(v, m, 64); }
; __device__ void retout_task(const Params& p, int n, int hh, char* smem) {
;     ...
;   for (int mb = 0; mb < 4; ++mb)
; #pragma unroll
;     for (int i = 0; i < 16; ++i) { float d = acc[mb][i] - mu; q += d * d; }
;   q += shx(q, 32);
;   float rstd = rsqrtf(q * (1.f / 128.f) + LN_EPS);
;   const u16* gp = p.H + (long)pos * INC + 4608 + hh * 128;
;   u16* op = p.MIXIN + (long)pos * D_ + 512 + hh * 128;
; #pragma unroll
;   for (int mb = 0; mb < 4; ++mb)
; #pragma unroll
;     for (int g4 = 0; g4 < 4; ++g4) {
;       int e0 = mb * 32 + 8 * g4 + 4 * hf;
;       uint2 graw = *(const uint2*)(gp + e0);
;       float gv[4] = {bflo(graw.x), bfhi(graw.x), bflo(graw.y), bfhi(graw.y)};
;       float y[4];
; #pragma unroll
;       for (int j = 0; j < 4; ++j) {
;         float yn = (acc[mb][4 * g4 + j] - mu) * rstd;
;         float sg = gv[j] / (1.f + __expf(-gv[j]));
;         y[j] = sg * yn;
;       }
;       uint2 pk; pk.x = pack2(y[0], y[1]); pk.y = pack2(y[2], y[3]);
;       *(uint2*)(op + e0) = pk;
	v_pk_mul_f32 v[122:123], v[42:43], v[42:43]
	v_add_f32_e32 v68, v120, v68
	v_add_f32_e32 v68, v122, v68
	v_add_f32_e32 v68, v121, v68
	v_pk_mul_f32 v[124:125], v[40:41], v[40:41]
	v_add_f32_e32 v68, v123, v68
	v_pk_mul_f32 v[126:127], v[38:39], v[38:39]
	v_add_f32_e32 v68, v124, v68
	v_add_f32_e32 v68, v126, v68
	v_add_f32_e32 v68, v125, v68
	v_pk_mul_f32 v[128:129], v[36:37], v[36:37]
	v_add_f32_e32 v68, v127, v68
	v_pk_mul_f32 v[130:131], v[34:35], v[34:35]
	v_add_f32_e32 v68, v128, v68
	v_add_f32_e32 v68, v130, v68
	v_add_f32_e32 v68, v129, v68
	v_pk_mul_f32 v[132:133], v[32:33], v[32:33]
	v_add_f32_e32 v68, v131, v68
	v_pk_mul_f32 v[28:29], v[26:27], v[26:27]
	v_add_f32_e32 v68, v132, v68
	v_add_f32_e32 v28, v28, v68
	v_add_f32_e32 v28, v133, v28
	v_pk_mul_f32 v[30:31], v[24:25], v[24:25]
	v_add_f32_e32 v28, v29, v28
	v_pk_mul_f32 v[134:135], v[22:23], v[22:23]
	v_add_f32_e32 v28, v30, v28
	v_add_f32_e32 v28, v134, v28
	v_add_f32_e32 v28, v31, v28
	v_add_f32_e32 v28, v135, v28
	v_fmac_f32_e32 v28, v20, v20
	v_fmac_f32_e32 v28, v18, v18
	v_add_f32_e32 v5, v5, v28
	v_add_f32_e32 v4, v4, v5
	v_add_f32_e32 v4, v9, v4
	v_add_f32_e32 v4, v8, v4
	v_mov_b32_e32 v12, v0
	v_mov_b32_e32 v13, v2
	v_add_f32_e32 v4, v11, v4
	v_pk_mul_f32 v[12:13], v[12:13], v[12:13]
	v_add_f32_e32 v4, v10, v4
	v_mov_b32_e32 v14, v1
	v_mov_b32_e32 v15, v3
	v_add_f32_e32 v4, v13, v4
	v_pk_mul_f32 v[14:15], v[14:15], v[14:15]
	v_add_f32_e32 v4, v12, v4
	v_add_f32_e32 v4, v15, v4
	v_add_f32_e32 v4, v14, v4
	ds_bpermute_b32 v5, v232, v4
	s_waitcnt lgkmcnt(0)
	v_add_f32_e32 v4, v4, v5
	v_fmamk_f32 v4, v4, 0x3c000000, v214
	v_cmp_gt_f32_e32 vcc, s70, v4
	v_mul_f32_e32 v5, 0x4b800000, v4
	s_nop 0
	v_cndmask_b32_e32 v4, v4, v5, vcc
	v_rsq_f32_e32 v4, v4
	s_nop 0
	v_mul_f32_e32 v5, 0x45800000, v4
	v_cndmask_b32_e32 v4, v4, v5, vcc
	v_pk_mul_f32 v[8:9], v[70:71], v[4:5] op_sel_hi:[1,0]
	v_pk_mul_f32 v[10:11], v[72:73], v[4:5] op_sel_hi:[1,0]
	v_pk_mul_f32 v[8:9], v[84:85], v[8:9]
	v_pk_mul_f32 v[10:11], v[88:89], v[10:11]
	v_and_b32_sdwa v5, v9, v209 dst_sel:DWORD dst_unused:UNUSED_PAD src0_sel:WORD_1 src1_sel:DWORD
	v_and_b32_sdwa v12, v8, v209 dst_sel:DWORD dst_unused:UNUSED_PAD src0_sel:WORD_1 src1_sel:DWORD
	v_add3_u32 v8, v8, v12, s65
	v_add3_u32 v5, v9, v5, s65
	v_and_b32_sdwa v9, v11, v209 dst_sel:DWORD dst_unused:UNUSED_PAD src0_sel:WORD_1 src1_sel:DWORD
	v_and_b32_sdwa v12, v10, v209 dst_sel:DWORD dst_unused:UNUSED_PAD src0_sel:WORD_1 src1_sel:DWORD
	v_add3_u32 v9, v11, v9, s65
	v_add3_u32 v10, v10, v12, s65
	v_and_b32_e32 v9, 0xffff0000, v9
	v_and_b32_e32 v10, 0xffff0000, v10
	v_or_b32_sdwa v9, v9, v5 dst_sel:DWORD dst_unused:UNUSED_PAD src0_sel:DWORD src1_sel:WORD_1
	v_or_b32_sdwa v8, v10, v8 dst_sel:DWORD dst_unused:UNUSED_PAD src0_sel:DWORD src1_sel:WORD_1
	global_store_dwordx2 v[64:65], v[8:9], off offset:1024
	s_waitcnt vmcnt(15)
	v_mov_b32_e32 v8, v136
	v_mov_b32_e32 v9, v137
	v_and_b32_e32 v15, 0xffff0000, v8
	v_lshlrev_b32_e32 v5, 16, v9
	v_lshlrev_b32_e32 v11, 16, v8
	v_and_b32_e32 v14, 0xffff0000, v9
	v_mul_f32_e32 v9, 0xbfb8aa3b, v15
	v_mul_f32_e32 v8, 0xbfb8aa3b, v11
	v_exp_f32_e32 v10, v9
	v_mul_f32_e32 v9, 0xbfb8aa3b, v5
	v_exp_f32_e32 v8, v8
	v_exp_f32_e32 v9, v9
	v_pk_mul_f32 v[12:13], v[90:91], v[4:5] op_sel_hi:[1,0]
	v_pk_add_f32 v[8:9], v[8:9], 1.0 op_sel_hi:[1,0]
	s_nop 0
	v_div_scale_f32 v28, s[0:1], v9, v9, v5
	v_rcp_f32_e32 v29, v28
	s_nop 0
	v_fma_f32 v30, -v28, v29, 1.0
	v_fmac_f32_e32 v29, v30, v29
	v_div_scale_f32 v30, vcc, v5, v9, v5
	v_mul_f32_e32 v31, v30, v29
	v_fma_f32 v68, -v28, v31, v30
	v_fmac_f32_e32 v31, v68, v29
	v_fma_f32 v28, -v28, v31, v30
	v_div_fmas_f32 v28, v28, v29, v31
	v_div_fixup_f32 v9, v28, v9, v5
	v_div_scale_f32 v5, s[0:1], v8, v8, v11
	v_rcp_f32_e32 v28, v5
	s_nop 0
	v_fma_f32 v29, -v5, v28, 1.0
	v_fmac_f32_e32 v28, v29, v28
	v_div_scale_f32 v29, vcc, v11, v8, v11
	v_mul_f32_e32 v30, v29, v28
	v_fma_f32 v31, -v5, v30, v29
	v_fmac_f32_e32 v30, v31, v28
	v_fma_f32 v5, -v5, v30, v29
	v_div_fmas_f32 v5, v5, v28, v30
	v_div_fixup_f32 v8, v5, v8, v11
	v_pk_mul_f32 v[8:9], v[8:9], v[12:13]
	v_pk_mul_f32 v[12:13], v[86:87], v[4:5] op_sel_hi:[1,0]
	v_mul_f32_e32 v5, 0xbfb8aa3b, v14
	v_exp_f32_e32 v11, v5
	s_nop 0
	v_pk_add_f32 v[10:11], v[10:11], 1.0 op_sel_hi:[1,0]
	s_nop 0
	v_div_scale_f32 v5, s[0:1], v11, v11, v14
	v_rcp_f32_e32 v28, v5
	s_nop 0
	v_fma_f32 v29, -v5, v28, 1.0
	v_fmac_f32_e32 v28, v29, v28
	v_div_scale_f32 v29, vcc, v14, v11, v14
	v_mul_f32_e32 v30, v29, v28
	v_fma_f32 v31, -v5, v30, v29
	v_fmac_f32_e32 v30, v31, v28
	v_fma_f32 v5, -v5, v30, v29
	v_div_fmas_f32 v5, v5, v28, v30
	v_div_fixup_f32 v11, v5, v11, v14
	v_div_scale_f32 v5, s[0:1], v10, v10, v15
	v_rcp_f32_e32 v14, v5
	s_nop 0
	v_fma_f32 v28, -v5, v14, 1.0
	v_fmac_f32_e32 v14, v28, v14
	v_div_scale_f32 v28, vcc, v15, v10, v15
	v_mul_f32_e32 v29, v28, v14
	v_fma_f32 v30, -v5, v29, v28
	v_fmac_f32_e32 v29, v30, v14
	v_fma_f32 v5, -v5, v29, v28
	v_div_fmas_f32 v5, v5, v14, v29
	v_div_fixup_f32 v10, v5, v10, v15
	v_pk_mul_f32 v[10:11], v[10:11], v[12:13]
	v_and_b32_sdwa v5, v9, v209 dst_sel:DWORD dst_unused:UNUSED_PAD src0_sel:WORD_1 src1_sel:DWORD
	v_and_b32_sdwa v12, v8, v209 dst_sel:DWORD dst_unused:UNUSED_PAD src0_sel:WORD_1 src1_sel:DWORD
	v_add3_u32 v8, v8, v12, s65
	v_add3_u32 v5, v9, v5, s65
	v_and_b32_sdwa v9, v11, v209 dst_sel:DWORD dst_unused:UNUSED_PAD src0_sel:WORD_1 src1_sel:DWORD
	v_and_b32_sdwa v12, v10, v209 dst_sel:DWORD dst_unused:UNUSED_PAD src0_sel:WORD_1 src1_sel:DWORD
	v_add3_u32 v9, v11, v9, s65
	v_add3_u32 v10, v10, v12, s65
	v_and_b32_e32 v9, 0xffff0000, v9
	v_and_b32_e32 v10, 0xffff0000, v10
	v_or_b32_sdwa v9, v9, v5 dst_sel:DWORD dst_unused:UNUSED_PAD src0_sel:DWORD src1_sel:WORD_1
	v_or_b32_sdwa v8, v10, v8 dst_sel:DWORD dst_unused:UNUSED_PAD src0_sel:DWORD src1_sel:WORD_1
	global_store_dwordx2 v[64:65], v[8:9], off offset:1040
	s_waitcnt vmcnt(15)
; __device__ __forceinline__ unsigned pack2(float a, float b) { return (unsigned)f2bf(a) | ((unsigned)f2bf(b) << 16); }
; __device__ __forceinline__ float bflo(unsigned u) { return __uint_as_float(u << 16); }
; __device__ __forceinline__ float bfhi(unsigned u) { return __uint_as_float(u & 0xffff0000u); }
; __device__ void retout_task(const Params& p, int n, int hh, char* smem) {
;     ...
;   const u16* gp = p.H + (long)pos * INC + 4608 + hh * 128;
;   u16* op = p.MIXIN + (long)pos * D_ + 512 + hh * 128;
; #pragma unroll
;   for (int mb = 0; mb < 4; ++mb)
; #pragma unroll
;     for (int g4 = 0; g4 < 4; ++g4) {
;       int e0 = mb * 32 + 8 * g4 + 4 * hf;
;       uint2 graw = *(const uint2*)(gp + e0);
;       float gv[4] = {bflo(graw.x), bfhi(graw.x), bflo(graw.y), bfhi(graw.y)};
;       float y[4];
; #pragma unroll
;       for (int j = 0; j < 4; ++j) {
;         float yn = (acc[mb][4 * g4 + j] - mu) * rstd;
;         float sg = gv[j] / (1.f + __expf(-gv[j]));
;         y[j] = sg * yn;
;       }
;       uint2 pk; pk.x = pack2(y[0], y[1]); pk.y = pack2(y[2], y[3]);
;       *(uint2*)(op + e0) = pk;
;     }
	v_mov_b32_e32 v8, v138
	v_mov_b32_e32 v9, v139
	v_and_b32_e32 v15, 0xffff0000, v8
	v_lshlrev_b32_e32 v5, 16, v9
	v_lshlrev_b32_e32 v11, 16, v8
	v_and_b32_e32 v14, 0xffff0000, v9
	v_mul_f32_e32 v9, 0xbfb8aa3b, v15
	v_mul_f32_e32 v8, 0xbfb8aa3b, v11
	v_exp_f32_e32 v10, v9
	v_mul_f32_e32 v9, 0xbfb8aa3b, v5
	v_exp_f32_e32 v8, v8
	v_exp_f32_e32 v9, v9
	v_pk_mul_f32 v[12:13], v[82:83], v[4:5] op_sel_hi:[1,0]
	v_pk_add_f32 v[8:9], v[8:9], 1.0 op_sel_hi:[1,0]
	s_nop 0
	v_div_scale_f32 v28, s[0:1], v9, v9, v5
	v_rcp_f32_e32 v29, v28
	s_nop 0
	v_fma_f32 v30, -v28, v29, 1.0
	v_fmac_f32_e32 v29, v30, v29
	v_div_scale_f32 v30, vcc, v5, v9, v5
	v_mul_f32_e32 v31, v30, v29
	v_fma_f32 v68, -v28, v31, v30
	v_fmac_f32_e32 v31, v68, v29
	v_fma_f32 v28, -v28, v31, v30
	v_div_fmas_f32 v28, v28, v29, v31
	v_div_fixup_f32 v9, v28, v9, v5
	v_div_scale_f32 v5, s[0:1], v8, v8, v11
	v_rcp_f32_e32 v28, v5
	s_nop 0
	v_fma_f32 v29, -v5, v28, 1.0
	v_fmac_f32_e32 v28, v29, v28
	v_div_scale_f32 v29, vcc, v11, v8, v11
	v_mul_f32_e32 v30, v29, v28
	v_fma_f32 v31, -v5, v30, v29
	v_fmac_f32_e32 v30, v31, v28
	v_fma_f32 v5, -v5, v30, v29
	v_div_fmas_f32 v5, v5, v28, v30
	v_div_fixup_f32 v8, v5, v8, v11
	v_pk_mul_f32 v[8:9], v[8:9], v[12:13]
	v_pk_mul_f32 v[12:13], v[80:81], v[4:5] op_sel_hi:[1,0]
	v_mul_f32_e32 v5, 0xbfb8aa3b, v14
	v_exp_f32_e32 v11, v5
	s_nop 0
	v_pk_add_f32 v[10:11], v[10:11], 1.0 op_sel_hi:[1,0]
	s_nop 0
	v_div_scale_f32 v5, s[0:1], v11, v11, v14
	v_rcp_f32_e32 v28, v5
	s_nop 0
	v_fma_f32 v29, -v5, v28, 1.0
	v_fmac_f32_e32 v28, v29, v28
	v_div_scale_f32 v29, vcc, v14, v11, v14
	v_mul_f32_e32 v30, v29, v28
	v_fma_f32 v31, -v5, v30, v29
	v_fmac_f32_e32 v30, v31, v28
	v_fma_f32 v5, -v5, v30, v29
	v_div_fmas_f32 v5, v5, v28, v30
	v_div_fixup_f32 v11, v5, v11, v14
	v_div_scale_f32 v5, s[0:1], v10, v10, v15
	v_rcp_f32_e32 v14, v5
	s_nop 0
	v_fma_f32 v28, -v5, v14, 1.0
	v_fmac_f32_e32 v14, v28, v14
	v_div_scale_f32 v28, vcc, v15, v10, v15
	v_mul_f32_e32 v29, v28, v14
	v_fma_f32 v30, -v5, v29, v28
	v_fmac_f32_e32 v29, v30, v14
	v_fma_f32 v5, -v5, v29, v28
	v_div_fmas_f32 v5, v5, v14, v29
	v_div_fixup_f32 v10, v5, v10, v15
	v_pk_mul_f32 v[10:11], v[10:11], v[12:13]
	v_and_b32_sdwa v5, v9, v209 dst_sel:DWORD dst_unused:UNUSED_PAD src0_sel:WORD_1 src1_sel:DWORD
	v_and_b32_sdwa v12, v8, v209 dst_sel:DWORD dst_unused:UNUSED_PAD src0_sel:WORD_1 src1_sel:DWORD
	v_add3_u32 v8, v8, v12, s65
	v_add3_u32 v5, v9, v5, s65
	v_and_b32_sdwa v9, v11, v209 dst_sel:DWORD dst_unused:UNUSED_PAD src0_sel:WORD_1 src1_sel:DWORD
	v_and_b32_sdwa v12, v10, v209 dst_sel:DWORD dst_unused:UNUSED_PAD src0_sel:WORD_1 src1_sel:DWORD
	v_add3_u32 v9, v11, v9, s65
	v_add3_u32 v10, v10, v12, s65
	v_and_b32_e32 v9, 0xffff0000, v9
	v_and_b32_e32 v10, 0xffff0000, v10
	v_or_b32_sdwa v9, v9, v5 dst_sel:DWORD dst_unused:UNUSED_PAD src0_sel:DWORD src1_sel:WORD_1
	v_or_b32_sdwa v8, v10, v8 dst_sel:DWORD dst_unused:UNUSED_PAD src0_sel:DWORD src1_sel:WORD_1
	global_store_dwordx2 v[64:65], v[8:9], off offset:1056
	s_waitcnt vmcnt(15)
	v_mov_b32_e32 v8, v140
	v_mov_b32_e32 v9, v141
	v_and_b32_e32 v15, 0xffff0000, v8
	v_lshlrev_b32_e32 v5, 16, v9
	v_lshlrev_b32_e32 v11, 16, v8
	v_and_b32_e32 v14, 0xffff0000, v9
	v_mul_f32_e32 v9, 0xbfb8aa3b, v15
	v_mul_f32_e32 v8, 0xbfb8aa3b, v11
	v_exp_f32_e32 v10, v9
	v_mul_f32_e32 v9, 0xbfb8aa3b, v5
	v_exp_f32_e32 v8, v8
	v_exp_f32_e32 v9, v9
	v_pk_mul_f32 v[12:13], v[74:75], v[4:5] op_sel_hi:[1,0]
	v_pk_add_f32 v[8:9], v[8:9], 1.0 op_sel_hi:[1,0]
	s_nop 0
	v_div_scale_f32 v28, s[0:1], v9, v9, v5
	v_rcp_f32_e32 v29, v28
	s_nop 0
	v_fma_f32 v30, -v28, v29, 1.0
	v_fmac_f32_e32 v29, v30, v29
	v_div_scale_f32 v30, vcc, v5, v9, v5
	v_mul_f32_e32 v31, v30, v29
	v_fma_f32 v68, -v28, v31, v30
	v_fmac_f32_e32 v31, v68, v29
	v_fma_f32 v28, -v28, v31, v30
	v_div_fmas_f32 v28, v28, v29, v31
	v_div_fixup_f32 v9, v28, v9, v5
	v_div_scale_f32 v5, s[0:1], v8, v8, v11
	v_rcp_f32_e32 v28, v5
	s_nop 0
	v_fma_f32 v29, -v5, v28, 1.0
	v_fmac_f32_e32 v28, v29, v28
	v_div_scale_f32 v29, vcc, v11, v8, v11
	v_mul_f32_e32 v30, v29, v28
	v_fma_f32 v31, -v5, v30, v29
	v_fmac_f32_e32 v30, v31, v28
	v_fma_f32 v5, -v5, v30, v29
	v_div_fmas_f32 v5, v5, v28, v30
	v_div_fixup_f32 v8, v5, v8, v11
	v_pk_mul_f32 v[8:9], v[8:9], v[12:13]
	v_pk_mul_f32 v[12:13], v[62:63], v[4:5] op_sel_hi:[1,0]
	v_mul_f32_e32 v5, 0xbfb8aa3b, v14
	v_exp_f32_e32 v11, v5
	s_nop 0
	v_pk_add_f32 v[10:11], v[10:11], 1.0 op_sel_hi:[1,0]
	s_nop 0
	v_div_scale_f32 v5, s[0:1], v11, v11, v14
	v_rcp_f32_e32 v28, v5
	s_nop 0
	v_fma_f32 v29, -v5, v28, 1.0
	v_fmac_f32_e32 v28, v29, v28
	v_div_scale_f32 v29, vcc, v14, v11, v14
	v_mul_f32_e32 v30, v29, v28
	v_fma_f32 v31, -v5, v30, v29
	v_fmac_f32_e32 v30, v31, v28
	v_fma_f32 v5, -v5, v30, v29
	v_div_fmas_f32 v5, v5, v28, v30
	v_div_fixup_f32 v11, v5, v11, v14
	v_div_scale_f32 v5, s[0:1], v10, v10, v15
	v_rcp_f32_e32 v14, v5
	s_nop 0
	v_fma_f32 v28, -v5, v14, 1.0
	v_fmac_f32_e32 v14, v28, v14
	v_div_scale_f32 v28, vcc, v15, v10, v15
	v_mul_f32_e32 v29, v28, v14
	v_fma_f32 v30, -v5, v29, v28
	v_fmac_f32_e32 v29, v30, v14
	v_fma_f32 v5, -v5, v29, v28
	v_div_fmas_f32 v5, v5, v14, v29
	v_div_fixup_f32 v10, v5, v10, v15
	v_pk_mul_f32 v[10:11], v[10:11], v[12:13]
	v_and_b32_sdwa v5, v9, v209 dst_sel:DWORD dst_unused:UNUSED_PAD src0_sel:WORD_1 src1_sel:DWORD
	v_and_b32_sdwa v12, v8, v209 dst_sel:DWORD dst_unused:UNUSED_PAD src0_sel:WORD_1 src1_sel:DWORD
	v_add3_u32 v8, v8, v12, s65
	v_add3_u32 v5, v9, v5, s65
	v_and_b32_sdwa v9, v11, v209 dst_sel:DWORD dst_unused:UNUSED_PAD src0_sel:WORD_1 src1_sel:DWORD
	v_and_b32_sdwa v12, v10, v209 dst_sel:DWORD dst_unused:UNUSED_PAD src0_sel:WORD_1 src1_sel:DWORD
	v_add3_u32 v9, v11, v9, s65
	v_add3_u32 v10, v10, v12, s65
	v_and_b32_e32 v9, 0xffff0000, v9
	v_and_b32_e32 v10, 0xffff0000, v10
	v_or_b32_sdwa v9, v9, v5 dst_sel:DWORD dst_unused:UNUSED_PAD src0_sel:DWORD src1_sel:WORD_1
	v_or_b32_sdwa v8, v10, v8 dst_sel:DWORD dst_unused:UNUSED_PAD src0_sel:DWORD src1_sel:WORD_1
	global_store_dwordx2 v[64:65], v[8:9], off offset:1072
	s_waitcnt vmcnt(15)
; __device__ __forceinline__ unsigned pack2(float a, float b) { return (unsigned)f2bf(a) | ((unsigned)f2bf(b) << 16); }
; __device__ __forceinline__ float bflo(unsigned u) { return __uint_as_float(u << 16); }
; __device__ __forceinline__ float bfhi(unsigned u) { return __uint_as_float(u & 0xffff0000u); }
; __device__ void retout_task(const Params& p, int n, int hh, char* smem) {
;     ...
;   const u16* gp = p.H + (long)pos * INC + 4608 + hh * 128;
;   u16* op = p.MIXIN + (long)pos * D_ + 512 + hh * 128;
; #pragma unroll
;   for (int mb = 0; mb < 4; ++mb)
; #pragma unroll
;     for (int g4 = 0; g4 < 4; ++g4) {
;       int e0 = mb * 32 + 8 * g4 + 4 * hf;
;       uint2 graw = *(const uint2*)(gp + e0);
;       float gv[4] = {bflo(graw.x), bfhi(graw.x), bflo(graw.y), bfhi(graw.y)};
;       float y[4];
; #pragma unroll
;       for (int j = 0; j < 4; ++j) {
;         float yn = (acc[mb][4 * g4 + j] - mu) * rstd;
;         float sg = gv[j] / (1.f + __expf(-gv[j]));
;         y[j] = sg * yn;
;       }
;       uint2 pk; pk.x = pack2(y[0], y[1]); pk.y = pack2(y[2], y[3]);
;       *(uint2*)(op + e0) = pk;
;     }
	v_mov_b32_e32 v8, v142
	v_mov_b32_e32 v9, v143
	v_and_b32_e32 v15, 0xffff0000, v8
	v_lshlrev_b32_e32 v5, 16, v9
	v_lshlrev_b32_e32 v11, 16, v8
	v_and_b32_e32 v14, 0xffff0000, v9
	v_mul_f32_e32 v9, 0xbfb8aa3b, v15
	v_mul_f32_e32 v8, 0xbfb8aa3b, v11
	v_exp_f32_e32 v10, v9
	v_mul_f32_e32 v9, 0xbfb8aa3b, v5
	v_exp_f32_e32 v8, v8
	v_exp_f32_e32 v9, v9
	v_pk_mul_f32 v[12:13], v[60:61], v[4:5] op_sel_hi:[1,0]
	v_pk_add_f32 v[8:9], v[8:9], 1.0 op_sel_hi:[1,0]
	s_nop 0
	v_div_scale_f32 v28, s[0:1], v9, v9, v5
	v_rcp_f32_e32 v29, v28
	s_nop 0
	v_fma_f32 v30, -v28, v29, 1.0
	v_fmac_f32_e32 v29, v30, v29
	v_div_scale_f32 v30, vcc, v5, v9, v5
	v_mul_f32_e32 v31, v30, v29
	v_fma_f32 v60, -v28, v31, v30
	v_fmac_f32_e32 v31, v60, v29
	v_fma_f32 v28, -v28, v31, v30
	v_div_fmas_f32 v28, v28, v29, v31
	v_div_fixup_f32 v9, v28, v9, v5
	v_div_scale_f32 v5, s[0:1], v8, v8, v11
	v_rcp_f32_e32 v28, v5
	s_nop 0
	v_fma_f32 v29, -v5, v28, 1.0
	v_fmac_f32_e32 v28, v29, v28
	v_div_scale_f32 v29, vcc, v11, v8, v11
	v_mul_f32_e32 v30, v29, v28
	v_fma_f32 v31, -v5, v30, v29
	v_fmac_f32_e32 v30, v31, v28
	v_fma_f32 v5, -v5, v30, v29
	v_div_fmas_f32 v5, v5, v28, v30
	v_div_fixup_f32 v8, v5, v8, v11
	v_pk_mul_f32 v[8:9], v[8:9], v[12:13]
	v_pk_mul_f32 v[12:13], v[58:59], v[4:5] op_sel_hi:[1,0]
	v_mul_f32_e32 v5, 0xbfb8aa3b, v14
	v_exp_f32_e32 v11, v5
	s_nop 0
	v_pk_add_f32 v[10:11], v[10:11], 1.0 op_sel_hi:[1,0]
	s_nop 0
	v_div_scale_f32 v5, s[0:1], v11, v11, v14
	v_rcp_f32_e32 v28, v5
	s_nop 0
	v_fma_f32 v29, -v5, v28, 1.0
	v_fmac_f32_e32 v28, v29, v28
	v_div_scale_f32 v29, vcc, v14, v11, v14
	v_mul_f32_e32 v30, v29, v28
	v_fma_f32 v31, -v5, v30, v29
	v_fmac_f32_e32 v30, v31, v28
	v_fma_f32 v5, -v5, v30, v29
	v_div_fmas_f32 v5, v5, v28, v30
	v_div_fixup_f32 v11, v5, v11, v14
	v_div_scale_f32 v5, s[0:1], v10, v10, v15
	v_rcp_f32_e32 v14, v5
	s_nop 0
	v_fma_f32 v28, -v5, v14, 1.0
	v_fmac_f32_e32 v14, v28, v14
	v_div_scale_f32 v28, vcc, v15, v10, v15
	v_mul_f32_e32 v29, v28, v14
	v_fma_f32 v30, -v5, v29, v28
	v_fmac_f32_e32 v29, v30, v14
	v_fma_f32 v5, -v5, v29, v28
	v_div_fmas_f32 v5, v5, v14, v29
	v_div_fixup_f32 v10, v5, v10, v15
	v_pk_mul_f32 v[10:11], v[10:11], v[12:13]
	v_and_b32_sdwa v5, v9, v209 dst_sel:DWORD dst_unused:UNUSED_PAD src0_sel:WORD_1 src1_sel:DWORD
	v_and_b32_sdwa v12, v8, v209 dst_sel:DWORD dst_unused:UNUSED_PAD src0_sel:WORD_1 src1_sel:DWORD
	v_add3_u32 v8, v8, v12, s65
	v_add3_u32 v5, v9, v5, s65
	v_and_b32_sdwa v9, v11, v209 dst_sel:DWORD dst_unused:UNUSED_PAD src0_sel:WORD_1 src1_sel:DWORD
	v_and_b32_sdwa v12, v10, v209 dst_sel:DWORD dst_unused:UNUSED_PAD src0_sel:WORD_1 src1_sel:DWORD
	v_add3_u32 v9, v11, v9, s65
	v_add3_u32 v10, v10, v12, s65
	v_and_b32_e32 v9, 0xffff0000, v9
	v_and_b32_e32 v10, 0xffff0000, v10
	v_or_b32_sdwa v9, v9, v5 dst_sel:DWORD dst_unused:UNUSED_PAD src0_sel:DWORD src1_sel:WORD_1
	v_or_b32_sdwa v8, v10, v8 dst_sel:DWORD dst_unused:UNUSED_PAD src0_sel:DWORD src1_sel:WORD_1
	global_store_dwordx2 v[64:65], v[8:9], off offset:1088
	s_waitcnt vmcnt(15)
	v_mov_b32_e32 v8, v144
	v_mov_b32_e32 v9, v145
	v_and_b32_e32 v15, 0xffff0000, v8
	v_lshlrev_b32_e32 v5, 16, v9
	v_lshlrev_b32_e32 v11, 16, v8
	v_and_b32_e32 v14, 0xffff0000, v9
	v_mul_f32_e32 v9, 0xbfb8aa3b, v15
	v_mul_f32_e32 v8, 0xbfb8aa3b, v11
	v_exp_f32_e32 v10, v9
	v_mul_f32_e32 v9, 0xbfb8aa3b, v5
	v_exp_f32_e32 v8, v8
	v_exp_f32_e32 v9, v9
	v_pk_mul_f32 v[12:13], v[56:57], v[4:5] op_sel_hi:[1,0]
	v_pk_add_f32 v[8:9], v[8:9], 1.0 op_sel_hi:[1,0]
	s_nop 0
	v_div_scale_f32 v28, s[0:1], v9, v9, v5
	v_rcp_f32_e32 v29, v28
	s_nop 0
	v_fma_f32 v30, -v28, v29, 1.0
	v_fmac_f32_e32 v29, v30, v29
	v_div_scale_f32 v30, vcc, v5, v9, v5
	v_mul_f32_e32 v31, v30, v29
	v_fma_f32 v56, -v28, v31, v30
	v_fmac_f32_e32 v31, v56, v29
	v_fma_f32 v28, -v28, v31, v30
	v_div_fmas_f32 v28, v28, v29, v31
	v_div_fixup_f32 v9, v28, v9, v5
	v_div_scale_f32 v5, s[0:1], v8, v8, v11
	v_rcp_f32_e32 v28, v5
	s_nop 0
	v_fma_f32 v29, -v5, v28, 1.0
	v_fmac_f32_e32 v28, v29, v28
	v_div_scale_f32 v29, vcc, v11, v8, v11
	v_mul_f32_e32 v30, v29, v28
	v_fma_f32 v31, -v5, v30, v29
	v_fmac_f32_e32 v30, v31, v28
	v_fma_f32 v5, -v5, v30, v29
	v_div_fmas_f32 v5, v5, v28, v30
	v_div_fixup_f32 v8, v5, v8, v11
	v_pk_mul_f32 v[8:9], v[8:9], v[12:13]
	v_pk_mul_f32 v[12:13], v[54:55], v[4:5] op_sel_hi:[1,0]
	v_mul_f32_e32 v5, 0xbfb8aa3b, v14
	v_exp_f32_e32 v11, v5
	s_nop 0
	v_pk_add_f32 v[10:11], v[10:11], 1.0 op_sel_hi:[1,0]
	s_nop 0
	v_div_scale_f32 v5, s[0:1], v11, v11, v14
	v_rcp_f32_e32 v28, v5
	s_nop 0
	v_fma_f32 v29, -v5, v28, 1.0
	v_fmac_f32_e32 v28, v29, v28
	v_div_scale_f32 v29, vcc, v14, v11, v14
	v_mul_f32_e32 v30, v29, v28
	v_fma_f32 v31, -v5, v30, v29
	v_fmac_f32_e32 v30, v31, v28
	v_fma_f32 v5, -v5, v30, v29
	v_div_fmas_f32 v5, v5, v28, v30
	v_div_fixup_f32 v11, v5, v11, v14
	v_div_scale_f32 v5, s[0:1], v10, v10, v15
	v_rcp_f32_e32 v14, v5
	s_nop 0
	v_fma_f32 v28, -v5, v14, 1.0
	v_fmac_f32_e32 v14, v28, v14
	v_div_scale_f32 v28, vcc, v15, v10, v15
	v_mul_f32_e32 v29, v28, v14
	v_fma_f32 v30, -v5, v29, v28
	v_fmac_f32_e32 v29, v30, v14
	v_fma_f32 v5, -v5, v29, v28
	v_div_fmas_f32 v5, v5, v14, v29
	v_div_fixup_f32 v10, v5, v10, v15
	v_pk_mul_f32 v[10:11], v[10:11], v[12:13]
	v_and_b32_sdwa v5, v9, v209 dst_sel:DWORD dst_unused:UNUSED_PAD src0_sel:WORD_1 src1_sel:DWORD
	v_and_b32_sdwa v12, v8, v209 dst_sel:DWORD dst_unused:UNUSED_PAD src0_sel:WORD_1 src1_sel:DWORD
	v_add3_u32 v8, v8, v12, s65
	v_add3_u32 v5, v9, v5, s65
	v_and_b32_sdwa v9, v11, v209 dst_sel:DWORD dst_unused:UNUSED_PAD src0_sel:WORD_1 src1_sel:DWORD
	v_and_b32_sdwa v12, v10, v209 dst_sel:DWORD dst_unused:UNUSED_PAD src0_sel:WORD_1 src1_sel:DWORD
	v_add3_u32 v9, v11, v9, s65
	v_add3_u32 v10, v10, v12, s65
	v_and_b32_e32 v9, 0xffff0000, v9
	v_and_b32_e32 v10, 0xffff0000, v10
	v_or_b32_sdwa v9, v9, v5 dst_sel:DWORD dst_unused:UNUSED_PAD src0_sel:DWORD src1_sel:WORD_1
	v_or_b32_sdwa v8, v10, v8 dst_sel:DWORD dst_unused:UNUSED_PAD src0_sel:DWORD src1_sel:WORD_1
	global_store_dwordx2 v[64:65], v[8:9], off offset:1104
	s_waitcnt vmcnt(15)
; __device__ __forceinline__ unsigned pack2(float a, float b) { return (unsigned)f2bf(a) | ((unsigned)f2bf(b) << 16); }
; __device__ __forceinline__ float bflo(unsigned u) { return __uint_as_float(u << 16); }
; __device__ __forceinline__ float bfhi(unsigned u) { return __uint_as_float(u & 0xffff0000u); }
; __device__ void retout_task(const Params& p, int n, int hh, char* smem) {
;     ...
;   const u16* gp = p.H + (long)pos * INC + 4608 + hh * 128;
;   u16* op = p.MIXIN + (long)pos * D_ + 512 + hh * 128;
; #pragma unroll
;   for (int mb = 0; mb < 4; ++mb)
; #pragma unroll
;     for (int g4 = 0; g4 < 4; ++g4) {
;       int e0 = mb * 32 + 8 * g4 + 4 * hf;
;       uint2 graw = *(const uint2*)(gp + e0);
;       float gv[4] = {bflo(graw.x), bfhi(graw.x), bflo(graw.y), bfhi(graw.y)};
;       float y[4];
; #pragma unroll
;       for (int j = 0; j < 4; ++j) {
;         float yn = (acc[mb][4 * g4 + j] - mu) * rstd;
;         float sg = gv[j] / (1.f + __expf(-gv[j]));
;         y[j] = sg * yn;
;       }
;       uint2 pk; pk.x = pack2(y[0], y[1]); pk.y = pack2(y[2], y[3]);
;       *(uint2*)(op + e0) = pk;
;     }
	v_mov_b32_e32 v8, v146
	v_mov_b32_e32 v9, v147
	v_and_b32_e32 v15, 0xffff0000, v8
	v_lshlrev_b32_e32 v5, 16, v9
	v_lshlrev_b32_e32 v11, 16, v8
	v_and_b32_e32 v14, 0xffff0000, v9
	v_mul_f32_e32 v9, 0xbfb8aa3b, v15
	v_mul_f32_e32 v8, 0xbfb8aa3b, v11
	v_exp_f32_e32 v10, v9
	v_mul_f32_e32 v9, 0xbfb8aa3b, v5
	v_exp_f32_e32 v8, v8
	v_exp_f32_e32 v9, v9
	v_pk_mul_f32 v[12:13], v[52:53], v[4:5] op_sel_hi:[1,0]
	v_pk_add_f32 v[8:9], v[8:9], 1.0 op_sel_hi:[1,0]
	s_nop 0
	v_div_scale_f32 v28, s[0:1], v9, v9, v5
	v_rcp_f32_e32 v29, v28
	s_nop 0
	v_fma_f32 v30, -v28, v29, 1.0
	v_fmac_f32_e32 v29, v30, v29
	v_div_scale_f32 v30, vcc, v5, v9, v5
	v_mul_f32_e32 v31, v30, v29
	v_fma_f32 v52, -v28, v31, v30
	v_fmac_f32_e32 v31, v52, v29
	v_fma_f32 v28, -v28, v31, v30
	v_div_fmas_f32 v28, v28, v29, v31
	v_div_fixup_f32 v9, v28, v9, v5
	v_div_scale_f32 v5, s[0:1], v8, v8, v11
	v_rcp_f32_e32 v28, v5
	s_nop 0
	v_fma_f32 v29, -v5, v28, 1.0
	v_fmac_f32_e32 v28, v29, v28
	v_div_scale_f32 v29, vcc, v11, v8, v11
	v_mul_f32_e32 v30, v29, v28
	v_fma_f32 v31, -v5, v30, v29
	v_fmac_f32_e32 v30, v31, v28
	v_fma_f32 v5, -v5, v30, v29
	v_div_fmas_f32 v5, v5, v28, v30
	v_div_fixup_f32 v8, v5, v8, v11
	v_pk_mul_f32 v[8:9], v[8:9], v[12:13]
	v_pk_mul_f32 v[12:13], v[50:51], v[4:5] op_sel_hi:[1,0]
	v_mul_f32_e32 v5, 0xbfb8aa3b, v14
	v_exp_f32_e32 v11, v5
	s_nop 0
	v_pk_add_f32 v[10:11], v[10:11], 1.0 op_sel_hi:[1,0]
	s_nop 0
	v_div_scale_f32 v5, s[0:1], v11, v11, v14
	v_rcp_f32_e32 v28, v5
	s_nop 0
	v_fma_f32 v29, -v5, v28, 1.0
	v_fmac_f32_e32 v28, v29, v28
	v_div_scale_f32 v29, vcc, v14, v11, v14
	v_mul_f32_e32 v30, v29, v28
	v_fma_f32 v31, -v5, v30, v29
	v_fmac_f32_e32 v30, v31, v28
	v_fma_f32 v5, -v5, v30, v29
	v_div_fmas_f32 v5, v5, v28, v30
	v_div_fixup_f32 v11, v5, v11, v14
	v_div_scale_f32 v5, s[0:1], v10, v10, v15
	v_rcp_f32_e32 v14, v5
	s_nop 0
	v_fma_f32 v28, -v5, v14, 1.0
	v_fmac_f32_e32 v14, v28, v14
	v_div_scale_f32 v28, vcc, v15, v10, v15
	v_mul_f32_e32 v29, v28, v14
	v_fma_f32 v30, -v5, v29, v28
	v_fmac_f32_e32 v29, v30, v14
	v_fma_f32 v5, -v5, v29, v28
	v_div_fmas_f32 v5, v5, v14, v29
	v_div_fixup_f32 v10, v5, v10, v15
	v_pk_mul_f32 v[10:11], v[10:11], v[12:13]
	v_and_b32_sdwa v5, v9, v209 dst_sel:DWORD dst_unused:UNUSED_PAD src0_sel:WORD_1 src1_sel:DWORD
	v_and_b32_sdwa v12, v8, v209 dst_sel:DWORD dst_unused:UNUSED_PAD src0_sel:WORD_1 src1_sel:DWORD
	v_add3_u32 v8, v8, v12, s65
	v_add3_u32 v5, v9, v5, s65
	v_and_b32_sdwa v9, v11, v209 dst_sel:DWORD dst_unused:UNUSED_PAD src0_sel:WORD_1 src1_sel:DWORD
	v_and_b32_sdwa v12, v10, v209 dst_sel:DWORD dst_unused:UNUSED_PAD src0_sel:WORD_1 src1_sel:DWORD
	v_add3_u32 v9, v11, v9, s65
	v_add3_u32 v10, v10, v12, s65
	v_and_b32_e32 v9, 0xffff0000, v9
	v_and_b32_e32 v10, 0xffff0000, v10
	v_or_b32_sdwa v9, v9, v5 dst_sel:DWORD dst_unused:UNUSED_PAD src0_sel:DWORD src1_sel:WORD_1
	v_or_b32_sdwa v8, v10, v8 dst_sel:DWORD dst_unused:UNUSED_PAD src0_sel:DWORD src1_sel:WORD_1
	global_store_dwordx2 v[64:65], v[8:9], off offset:1120
	s_waitcnt vmcnt(15)
	v_mov_b32_e32 v8, v148
	v_mov_b32_e32 v9, v149
	v_and_b32_e32 v15, 0xffff0000, v8
	v_lshlrev_b32_e32 v5, 16, v9
	v_lshlrev_b32_e32 v11, 16, v8
	v_and_b32_e32 v14, 0xffff0000, v9
	v_mul_f32_e32 v9, 0xbfb8aa3b, v15
	v_mul_f32_e32 v8, 0xbfb8aa3b, v11
	v_exp_f32_e32 v10, v9
	v_mul_f32_e32 v9, 0xbfb8aa3b, v5
	v_exp_f32_e32 v8, v8
	v_exp_f32_e32 v9, v9
	v_pk_mul_f32 v[12:13], v[48:49], v[4:5] op_sel_hi:[1,0]
	v_pk_add_f32 v[8:9], v[8:9], 1.0 op_sel_hi:[1,0]
	s_nop 0
	v_div_scale_f32 v28, s[0:1], v9, v9, v5
	v_rcp_f32_e32 v29, v28
	s_nop 0
	v_fma_f32 v30, -v28, v29, 1.0
	v_fmac_f32_e32 v29, v30, v29
	v_div_scale_f32 v30, vcc, v5, v9, v5
	v_mul_f32_e32 v31, v30, v29
	v_fma_f32 v48, -v28, v31, v30
	v_fmac_f32_e32 v31, v48, v29
	v_fma_f32 v28, -v28, v31, v30
	v_div_fmas_f32 v28, v28, v29, v31
	v_div_fixup_f32 v9, v28, v9, v5
	v_div_scale_f32 v5, s[0:1], v8, v8, v11
	v_rcp_f32_e32 v28, v5
	s_nop 0
	v_fma_f32 v29, -v5, v28, 1.0
	v_fmac_f32_e32 v28, v29, v28
	v_div_scale_f32 v29, vcc, v11, v8, v11
	v_mul_f32_e32 v30, v29, v28
	v_fma_f32 v31, -v5, v30, v29
	v_fmac_f32_e32 v30, v31, v28
	v_fma_f32 v5, -v5, v30, v29
	v_div_fmas_f32 v5, v5, v28, v30
	v_div_fixup_f32 v8, v5, v8, v11
	v_pk_mul_f32 v[8:9], v[8:9], v[12:13]
	v_pk_mul_f32 v[12:13], v[46:47], v[4:5] op_sel_hi:[1,0]
	v_mul_f32_e32 v5, 0xbfb8aa3b, v14
	v_exp_f32_e32 v11, v5
	s_nop 0
	v_pk_add_f32 v[10:11], v[10:11], 1.0 op_sel_hi:[1,0]
	s_nop 0
	v_div_scale_f32 v5, s[0:1], v11, v11, v14
	v_rcp_f32_e32 v28, v5
	s_nop 0
	v_fma_f32 v29, -v5, v28, 1.0
	v_fmac_f32_e32 v28, v29, v28
	v_div_scale_f32 v29, vcc, v14, v11, v14
	v_mul_f32_e32 v30, v29, v28
	v_fma_f32 v31, -v5, v30, v29
	v_fmac_f32_e32 v30, v31, v28
	v_fma_f32 v5, -v5, v30, v29
	v_div_fmas_f32 v5, v5, v28, v30
	v_div_fixup_f32 v11, v5, v11, v14
	v_div_scale_f32 v5, s[0:1], v10, v10, v15
	v_rcp_f32_e32 v14, v5
	s_nop 0
	v_fma_f32 v28, -v5, v14, 1.0
	v_fmac_f32_e32 v14, v28, v14
	v_div_scale_f32 v28, vcc, v15, v10, v15
	v_mul_f32_e32 v29, v28, v14
	v_fma_f32 v30, -v5, v29, v28
	v_fmac_f32_e32 v29, v30, v14
	v_fma_f32 v5, -v5, v29, v28
	v_div_fmas_f32 v5, v5, v14, v29
	v_div_fixup_f32 v10, v5, v10, v15
	v_pk_mul_f32 v[10:11], v[10:11], v[12:13]
	v_and_b32_sdwa v5, v9, v209 dst_sel:DWORD dst_unused:UNUSED_PAD src0_sel:WORD_1 src1_sel:DWORD
	v_and_b32_sdwa v12, v8, v209 dst_sel:DWORD dst_unused:UNUSED_PAD src0_sel:WORD_1 src1_sel:DWORD
	v_add3_u32 v8, v8, v12, s65
	v_add3_u32 v5, v9, v5, s65
	v_and_b32_sdwa v9, v11, v209 dst_sel:DWORD dst_unused:UNUSED_PAD src0_sel:WORD_1 src1_sel:DWORD
	v_and_b32_sdwa v12, v10, v209 dst_sel:DWORD dst_unused:UNUSED_PAD src0_sel:WORD_1 src1_sel:DWORD
	v_add3_u32 v9, v11, v9, s65
	v_add3_u32 v10, v10, v12, s65
	v_and_b32_e32 v9, 0xffff0000, v9
	v_and_b32_e32 v10, 0xffff0000, v10
	v_or_b32_sdwa v9, v9, v5 dst_sel:DWORD dst_unused:UNUSED_PAD src0_sel:DWORD src1_sel:WORD_1
	v_or_b32_sdwa v8, v10, v8 dst_sel:DWORD dst_unused:UNUSED_PAD src0_sel:DWORD src1_sel:WORD_1
	global_store_dwordx2 v[64:65], v[8:9], off offset:1136
	s_waitcnt vmcnt(15)
; __device__ __forceinline__ unsigned pack2(float a, float b) { return (unsigned)f2bf(a) | ((unsigned)f2bf(b) << 16); }
; __device__ __forceinline__ float bflo(unsigned u) { return __uint_as_float(u << 16); }
; __device__ __forceinline__ float bfhi(unsigned u) { return __uint_as_float(u & 0xffff0000u); }
; __device__ void retout_task(const Params& p, int n, int hh, char* smem) {
;     ...
;   const u16* gp = p.H + (long)pos * INC + 4608 + hh * 128;
;   u16* op = p.MIXIN + (long)pos * D_ + 512 + hh * 128;
; #pragma unroll
;   for (int mb = 0; mb < 4; ++mb)
; #pragma unroll
;     for (int g4 = 0; g4 < 4; ++g4) {
;       int e0 = mb * 32 + 8 * g4 + 4 * hf;
;       uint2 graw = *(const uint2*)(gp + e0);
;       float gv[4] = {bflo(graw.x), bfhi(graw.x), bflo(graw.y), bfhi(graw.y)};
;       float y[4];
; #pragma unroll
;       for (int j = 0; j < 4; ++j) {
;         float yn = (acc[mb][4 * g4 + j] - mu) * rstd;
;         float sg = gv[j] / (1.f + __expf(-gv[j]));
;         y[j] = sg * yn;
;       }
;       uint2 pk; pk.x = pack2(y[0], y[1]); pk.y = pack2(y[2], y[3]);
;       *(uint2*)(op + e0) = pk;
;     }
	v_mov_b32_e32 v8, v150
	v_mov_b32_e32 v9, v151
	v_and_b32_e32 v15, 0xffff0000, v8
	v_lshlrev_b32_e32 v5, 16, v9
	v_lshlrev_b32_e32 v13, 16, v8
	v_and_b32_e32 v14, 0xffff0000, v9
	v_mul_f32_e32 v9, 0xbfb8aa3b, v15
	v_mul_f32_e32 v8, 0xbfb8aa3b, v13
	v_exp_f32_e32 v12, v9
	v_mul_f32_e32 v9, 0xbfb8aa3b, v5
	v_exp_f32_e32 v8, v8
	v_exp_f32_e32 v9, v9
	v_pk_mul_f32 v[10:11], v[44:45], v[4:5] op_sel_hi:[1,0]
	v_pk_add_f32 v[8:9], v[8:9], 1.0 op_sel_hi:[1,0]
	s_nop 0
	v_div_scale_f32 v28, s[0:1], v9, v9, v5
	v_rcp_f32_e32 v29, v28
	s_nop 0
	v_fma_f32 v30, -v28, v29, 1.0
	v_fmac_f32_e32 v29, v30, v29
	v_div_scale_f32 v30, vcc, v5, v9, v5
	v_mul_f32_e32 v31, v30, v29
	v_fma_f32 v44, -v28, v31, v30
	v_fmac_f32_e32 v31, v44, v29
	v_fma_f32 v28, -v28, v31, v30
	v_div_fmas_f32 v28, v28, v29, v31
	v_div_fixup_f32 v9, v28, v9, v5
	v_div_scale_f32 v5, s[0:1], v8, v8, v13
	v_rcp_f32_e32 v28, v5
	s_nop 0
	v_fma_f32 v29, -v5, v28, 1.0
	v_fmac_f32_e32 v28, v29, v28
	v_div_scale_f32 v29, vcc, v13, v8, v13
	v_mul_f32_e32 v30, v29, v28
	v_fma_f32 v31, -v5, v30, v29
	v_fmac_f32_e32 v30, v31, v28
	v_fma_f32 v5, -v5, v30, v29
	v_div_fmas_f32 v5, v5, v28, v30
	v_div_fixup_f32 v8, v5, v8, v13
	v_pk_mul_f32 v[8:9], v[8:9], v[10:11]
	v_pk_mul_f32 v[10:11], v[42:43], v[4:5] op_sel_hi:[1,0]
	v_mul_f32_e32 v5, 0xbfb8aa3b, v14
	v_exp_f32_e32 v13, v5
	s_nop 0
	v_pk_add_f32 v[12:13], v[12:13], 1.0 op_sel_hi:[1,0]
	s_nop 0
	v_div_scale_f32 v5, s[0:1], v13, v13, v14
	v_rcp_f32_e32 v28, v5
	s_nop 0
	v_fma_f32 v29, -v5, v28, 1.0
	v_fmac_f32_e32 v28, v29, v28
	v_div_scale_f32 v29, vcc, v14, v13, v14
	v_mul_f32_e32 v30, v29, v28
	v_fma_f32 v31, -v5, v30, v29
	v_fmac_f32_e32 v30, v31, v28
	v_fma_f32 v5, -v5, v30, v29
	v_div_fmas_f32 v5, v5, v28, v30
	v_div_fixup_f32 v13, v5, v13, v14
	v_div_scale_f32 v5, s[0:1], v12, v12, v15
	v_rcp_f32_e32 v14, v5
	s_nop 0
	v_fma_f32 v28, -v5, v14, 1.0
	v_fmac_f32_e32 v14, v28, v14
	v_div_scale_f32 v28, vcc, v15, v12, v15
	v_mul_f32_e32 v29, v28, v14
	v_fma_f32 v30, -v5, v29, v28
	v_fmac_f32_e32 v29, v30, v14
	v_fma_f32 v5, -v5, v29, v28
	v_div_fmas_f32 v5, v5, v14, v29
	v_div_fixup_f32 v12, v5, v12, v15
	v_pk_mul_f32 v[10:11], v[12:13], v[10:11]
	v_and_b32_sdwa v5, v9, v209 dst_sel:DWORD dst_unused:UNUSED_PAD src0_sel:WORD_1 src1_sel:DWORD
	v_and_b32_sdwa v12, v8, v209 dst_sel:DWORD dst_unused:UNUSED_PAD src0_sel:WORD_1 src1_sel:DWORD
	v_add3_u32 v8, v8, v12, s65
	v_add3_u32 v5, v9, v5, s65
	v_and_b32_sdwa v9, v11, v209 dst_sel:DWORD dst_unused:UNUSED_PAD src0_sel:WORD_1 src1_sel:DWORD
	v_and_b32_sdwa v12, v10, v209 dst_sel:DWORD dst_unused:UNUSED_PAD src0_sel:WORD_1 src1_sel:DWORD
	v_add3_u32 v9, v11, v9, s65
	v_add3_u32 v10, v10, v12, s65
	v_and_b32_e32 v9, 0xffff0000, v9
	v_and_b32_e32 v10, 0xffff0000, v10
	v_or_b32_sdwa v9, v9, v5 dst_sel:DWORD dst_unused:UNUSED_PAD src0_sel:DWORD src1_sel:WORD_1
	v_or_b32_sdwa v8, v10, v8 dst_sel:DWORD dst_unused:UNUSED_PAD src0_sel:DWORD src1_sel:WORD_1
	global_store_dwordx2 v[64:65], v[8:9], off offset:1152
	s_waitcnt vmcnt(15)
	v_mov_b32_e32 v8, v152
	v_mov_b32_e32 v9, v153
	v_and_b32_e32 v15, 0xffff0000, v8
	v_lshlrev_b32_e32 v5, 16, v9
	v_lshlrev_b32_e32 v13, 16, v8
	v_and_b32_e32 v14, 0xffff0000, v9
	v_mul_f32_e32 v9, 0xbfb8aa3b, v15
	v_mul_f32_e32 v8, 0xbfb8aa3b, v13
	v_exp_f32_e32 v12, v9
	v_mul_f32_e32 v9, 0xbfb8aa3b, v5
	v_exp_f32_e32 v8, v8
	v_exp_f32_e32 v9, v9
	v_pk_mul_f32 v[10:11], v[40:41], v[4:5] op_sel_hi:[1,0]
	v_pk_add_f32 v[8:9], v[8:9], 1.0 op_sel_hi:[1,0]
	s_nop 0
	v_div_scale_f32 v28, s[0:1], v9, v9, v5
	v_rcp_f32_e32 v29, v28
	s_nop 0
	v_fma_f32 v30, -v28, v29, 1.0
	v_fmac_f32_e32 v29, v30, v29
	v_div_scale_f32 v30, vcc, v5, v9, v5
	v_mul_f32_e32 v31, v30, v29
	v_fma_f32 v40, -v28, v31, v30
	v_fmac_f32_e32 v31, v40, v29
	v_fma_f32 v28, -v28, v31, v30
	v_div_fmas_f32 v28, v28, v29, v31
	v_div_fixup_f32 v9, v28, v9, v5
	v_div_scale_f32 v5, s[0:1], v8, v8, v13
	v_rcp_f32_e32 v28, v5
	s_nop 0
	v_fma_f32 v29, -v5, v28, 1.0
	v_fmac_f32_e32 v28, v29, v28
	v_div_scale_f32 v29, vcc, v13, v8, v13
	v_mul_f32_e32 v30, v29, v28
	v_fma_f32 v31, -v5, v30, v29
	v_fmac_f32_e32 v30, v31, v28
	v_fma_f32 v5, -v5, v30, v29
	v_div_fmas_f32 v5, v5, v28, v30
	v_div_fixup_f32 v8, v5, v8, v13
	v_pk_mul_f32 v[8:9], v[8:9], v[10:11]
	v_pk_mul_f32 v[10:11], v[38:39], v[4:5] op_sel_hi:[1,0]
	v_mul_f32_e32 v5, 0xbfb8aa3b, v14
	v_exp_f32_e32 v13, v5
	s_nop 0
	v_pk_add_f32 v[12:13], v[12:13], 1.0 op_sel_hi:[1,0]
	s_nop 0
	v_div_scale_f32 v5, s[0:1], v13, v13, v14
	v_rcp_f32_e32 v28, v5
	s_nop 0
	v_fma_f32 v29, -v5, v28, 1.0
	v_fmac_f32_e32 v28, v29, v28
	v_div_scale_f32 v29, vcc, v14, v13, v14
	v_mul_f32_e32 v30, v29, v28
	v_fma_f32 v31, -v5, v30, v29
	v_fmac_f32_e32 v30, v31, v28
	v_fma_f32 v5, -v5, v30, v29
	v_div_fmas_f32 v5, v5, v28, v30
	v_div_fixup_f32 v13, v5, v13, v14
	v_div_scale_f32 v5, s[0:1], v12, v12, v15
	v_rcp_f32_e32 v14, v5
	s_nop 0
	v_fma_f32 v28, -v5, v14, 1.0
	v_fmac_f32_e32 v14, v28, v14
	v_div_scale_f32 v28, vcc, v15, v12, v15
	v_mul_f32_e32 v29, v28, v14
	v_fma_f32 v30, -v5, v29, v28
	v_fmac_f32_e32 v29, v30, v14
	v_fma_f32 v5, -v5, v29, v28
	v_div_fmas_f32 v5, v5, v14, v29
	v_div_fixup_f32 v12, v5, v12, v15
	v_pk_mul_f32 v[10:11], v[12:13], v[10:11]
	v_and_b32_sdwa v5, v9, v209 dst_sel:DWORD dst_unused:UNUSED_PAD src0_sel:WORD_1 src1_sel:DWORD
	v_and_b32_sdwa v12, v8, v209 dst_sel:DWORD dst_unused:UNUSED_PAD src0_sel:WORD_1 src1_sel:DWORD
	v_add3_u32 v8, v8, v12, s65
	v_add3_u32 v5, v9, v5, s65
	v_and_b32_sdwa v9, v11, v209 dst_sel:DWORD dst_unused:UNUSED_PAD src0_sel:WORD_1 src1_sel:DWORD
	v_and_b32_sdwa v12, v10, v209 dst_sel:DWORD dst_unused:UNUSED_PAD src0_sel:WORD_1 src1_sel:DWORD
	v_add3_u32 v9, v11, v9, s65
	v_add3_u32 v10, v10, v12, s65
	v_and_b32_e32 v9, 0xffff0000, v9
	v_and_b32_e32 v10, 0xffff0000, v10
	v_or_b32_sdwa v9, v9, v5 dst_sel:DWORD dst_unused:UNUSED_PAD src0_sel:DWORD src1_sel:WORD_1
	v_or_b32_sdwa v8, v10, v8 dst_sel:DWORD dst_unused:UNUSED_PAD src0_sel:DWORD src1_sel:WORD_1
	global_store_dwordx2 v[64:65], v[8:9], off offset:1168
	s_waitcnt vmcnt(15)
; __device__ __forceinline__ unsigned pack2(float a, float b) { return (unsigned)f2bf(a) | ((unsigned)f2bf(b) << 16); }
; __device__ __forceinline__ float bflo(unsigned u) { return __uint_as_float(u << 16); }
; __device__ __forceinline__ float bfhi(unsigned u) { return __uint_as_float(u & 0xffff0000u); }
; __device__ void retout_task(const Params& p, int n, int hh, char* smem) {
;     ...
;   const u16* gp = p.H + (long)pos * INC + 4608 + hh * 128;
;   u16* op = p.MIXIN + (long)pos * D_ + 512 + hh * 128;
; #pragma unroll
;   for (int mb = 0; mb < 4; ++mb)
; #pragma unroll
;     for (int g4 = 0; g4 < 4; ++g4) {
;       int e0 = mb * 32 + 8 * g4 + 4 * hf;
;       uint2 graw = *(const uint2*)(gp + e0);
;       float gv[4] = {bflo(graw.x), bfhi(graw.x), bflo(graw.y), bfhi(graw.y)};
;       float y[4];
; #pragma unroll
;       for (int j = 0; j < 4; ++j) {
;         float yn = (acc[mb][4 * g4 + j] - mu) * rstd;
;         float sg = gv[j] / (1.f + __expf(-gv[j]));
;         y[j] = sg * yn;
;       }
;       uint2 pk; pk.x = pack2(y[0], y[1]); pk.y = pack2(y[2], y[3]);
;       *(uint2*)(op + e0) = pk;
;     }
	v_mov_b32_e32 v8, v154
	v_mov_b32_e32 v9, v155
	v_and_b32_e32 v15, 0xffff0000, v8
	v_lshlrev_b32_e32 v5, 16, v9
	v_lshlrev_b32_e32 v13, 16, v8
	v_and_b32_e32 v14, 0xffff0000, v9
	v_mul_f32_e32 v9, 0xbfb8aa3b, v15
	v_mul_f32_e32 v8, 0xbfb8aa3b, v13
	v_exp_f32_e32 v12, v9
	v_mul_f32_e32 v9, 0xbfb8aa3b, v5
	v_exp_f32_e32 v8, v8
	v_exp_f32_e32 v9, v9
	v_pk_mul_f32 v[10:11], v[36:37], v[4:5] op_sel_hi:[1,0]
	v_pk_add_f32 v[8:9], v[8:9], 1.0 op_sel_hi:[1,0]
	s_nop 0
	v_div_scale_f32 v28, s[0:1], v9, v9, v5
	v_rcp_f32_e32 v29, v28
	s_nop 0
	v_fma_f32 v30, -v28, v29, 1.0
	v_fmac_f32_e32 v29, v30, v29
	v_div_scale_f32 v30, vcc, v5, v9, v5
	v_mul_f32_e32 v31, v30, v29
	v_fma_f32 v36, -v28, v31, v30
	v_fmac_f32_e32 v31, v36, v29
	v_fma_f32 v28, -v28, v31, v30
	v_div_fmas_f32 v28, v28, v29, v31
	v_div_fixup_f32 v9, v28, v9, v5
	v_div_scale_f32 v5, s[0:1], v8, v8, v13
	v_rcp_f32_e32 v28, v5
	s_nop 0
	v_fma_f32 v29, -v5, v28, 1.0
	v_fmac_f32_e32 v28, v29, v28
	v_div_scale_f32 v29, vcc, v13, v8, v13
	v_mul_f32_e32 v30, v29, v28
	v_fma_f32 v31, -v5, v30, v29
	v_fmac_f32_e32 v30, v31, v28
	v_fma_f32 v5, -v5, v30, v29
	v_div_fmas_f32 v5, v5, v28, v30
	v_div_fixup_f32 v8, v5, v8, v13
	v_pk_mul_f32 v[8:9], v[8:9], v[10:11]
	v_pk_mul_f32 v[10:11], v[34:35], v[4:5] op_sel_hi:[1,0]
	v_mul_f32_e32 v5, 0xbfb8aa3b, v14
	v_exp_f32_e32 v13, v5
	s_nop 0
	v_pk_add_f32 v[12:13], v[12:13], 1.0 op_sel_hi:[1,0]
	s_nop 0
	v_div_scale_f32 v5, s[0:1], v13, v13, v14
	v_rcp_f32_e32 v28, v5
	s_nop 0
	v_fma_f32 v29, -v5, v28, 1.0
	v_fmac_f32_e32 v28, v29, v28
	v_div_scale_f32 v29, vcc, v14, v13, v14
	v_mul_f32_e32 v30, v29, v28
	v_fma_f32 v31, -v5, v30, v29
	v_fmac_f32_e32 v30, v31, v28
	v_fma_f32 v5, -v5, v30, v29
	v_div_fmas_f32 v5, v5, v28, v30
	v_div_fixup_f32 v13, v5, v13, v14
	v_div_scale_f32 v5, s[0:1], v12, v12, v15
	v_rcp_f32_e32 v14, v5
	s_nop 0
	v_fma_f32 v28, -v5, v14, 1.0
	v_fmac_f32_e32 v14, v28, v14
	v_div_scale_f32 v28, vcc, v15, v12, v15
	v_mul_f32_e32 v29, v28, v14
	v_fma_f32 v30, -v5, v29, v28
	v_fmac_f32_e32 v29, v30, v14
	v_fma_f32 v5, -v5, v29, v28
	v_div_fmas_f32 v5, v5, v14, v29
	v_div_fixup_f32 v12, v5, v12, v15
	v_pk_mul_f32 v[10:11], v[12:13], v[10:11]
	v_and_b32_sdwa v5, v9, v209 dst_sel:DWORD dst_unused:UNUSED_PAD src0_sel:WORD_1 src1_sel:DWORD
	v_and_b32_sdwa v12, v8, v209 dst_sel:DWORD dst_unused:UNUSED_PAD src0_sel:WORD_1 src1_sel:DWORD
	v_add3_u32 v8, v8, v12, s65
	v_add3_u32 v5, v9, v5, s65
	v_and_b32_sdwa v9, v11, v209 dst_sel:DWORD dst_unused:UNUSED_PAD src0_sel:WORD_1 src1_sel:DWORD
	v_and_b32_sdwa v12, v10, v209 dst_sel:DWORD dst_unused:UNUSED_PAD src0_sel:WORD_1 src1_sel:DWORD
	v_add3_u32 v9, v11, v9, s65
	v_add3_u32 v10, v10, v12, s65
	v_and_b32_e32 v9, 0xffff0000, v9
	v_and_b32_e32 v10, 0xffff0000, v10
	v_or_b32_sdwa v9, v9, v5 dst_sel:DWORD dst_unused:UNUSED_PAD src0_sel:DWORD src1_sel:WORD_1
	v_or_b32_sdwa v8, v10, v8 dst_sel:DWORD dst_unused:UNUSED_PAD src0_sel:DWORD src1_sel:WORD_1
	global_store_dwordx2 v[64:65], v[8:9], off offset:1184
	s_waitcnt vmcnt(15)
	v_mov_b32_e32 v8, v156
	v_mov_b32_e32 v9, v157
	v_and_b32_e32 v15, 0xffff0000, v8
	v_lshlrev_b32_e32 v5, 16, v9
	v_lshlrev_b32_e32 v13, 16, v8
	v_and_b32_e32 v14, 0xffff0000, v9
	v_mul_f32_e32 v9, 0xbfb8aa3b, v15
	v_mul_f32_e32 v8, 0xbfb8aa3b, v13
	v_exp_f32_e32 v12, v9
	v_mul_f32_e32 v9, 0xbfb8aa3b, v5
	v_exp_f32_e32 v8, v8
	v_exp_f32_e32 v9, v9
	v_pk_mul_f32 v[10:11], v[32:33], v[4:5] op_sel_hi:[1,0]
	v_pk_add_f32 v[8:9], v[8:9], 1.0 op_sel_hi:[1,0]
	s_nop 0
	v_div_scale_f32 v28, s[0:1], v9, v9, v5
	v_rcp_f32_e32 v29, v28
	s_nop 0
	v_fma_f32 v30, -v28, v29, 1.0
	v_fmac_f32_e32 v29, v30, v29
	v_div_scale_f32 v30, vcc, v5, v9, v5
	v_mul_f32_e32 v31, v30, v29
	v_fma_f32 v32, -v28, v31, v30
	v_fmac_f32_e32 v31, v32, v29
	v_fma_f32 v28, -v28, v31, v30
	v_div_fmas_f32 v28, v28, v29, v31
	v_div_fixup_f32 v9, v28, v9, v5
	v_div_scale_f32 v5, s[0:1], v8, v8, v13
	v_rcp_f32_e32 v28, v5
	s_nop 0
	v_fma_f32 v29, -v5, v28, 1.0
	v_fmac_f32_e32 v28, v29, v28
	v_div_scale_f32 v29, vcc, v13, v8, v13
	v_mul_f32_e32 v30, v29, v28
	v_fma_f32 v31, -v5, v30, v29
	v_fmac_f32_e32 v30, v31, v28
	v_fma_f32 v5, -v5, v30, v29
	v_div_fmas_f32 v5, v5, v28, v30
	v_div_fixup_f32 v8, v5, v8, v13
	v_pk_mul_f32 v[8:9], v[8:9], v[10:11]
	v_pk_mul_f32 v[10:11], v[26:27], v[4:5] op_sel_hi:[1,0]
	v_mul_f32_e32 v5, 0xbfb8aa3b, v14
	v_exp_f32_e32 v13, v5
	s_nop 0
	v_pk_add_f32 v[12:13], v[12:13], 1.0 op_sel_hi:[1,0]
	s_nop 0
	v_div_scale_f32 v5, s[0:1], v13, v13, v14
	v_rcp_f32_e32 v26, v5
	s_nop 0
	v_fma_f32 v27, -v5, v26, 1.0
	v_fmac_f32_e32 v26, v27, v26
	v_div_scale_f32 v27, vcc, v14, v13, v14
	v_mul_f32_e32 v28, v27, v26
	v_fma_f32 v29, -v5, v28, v27
	v_fmac_f32_e32 v28, v29, v26
	v_fma_f32 v5, -v5, v28, v27
	v_div_fmas_f32 v5, v5, v26, v28
	v_div_fixup_f32 v13, v5, v13, v14
	v_div_scale_f32 v5, s[0:1], v12, v12, v15
	v_rcp_f32_e32 v14, v5
	s_nop 0
	v_fma_f32 v26, -v5, v14, 1.0
	v_fmac_f32_e32 v14, v26, v14
	v_div_scale_f32 v26, vcc, v15, v12, v15
	v_mul_f32_e32 v27, v26, v14
	v_fma_f32 v28, -v5, v27, v26
	v_fmac_f32_e32 v27, v28, v14
	v_fma_f32 v5, -v5, v27, v26
	v_div_fmas_f32 v5, v5, v14, v27
	v_div_fixup_f32 v12, v5, v12, v15
	v_pk_mul_f32 v[10:11], v[12:13], v[10:11]
	v_and_b32_sdwa v5, v9, v209 dst_sel:DWORD dst_unused:UNUSED_PAD src0_sel:WORD_1 src1_sel:DWORD
	v_and_b32_sdwa v12, v8, v209 dst_sel:DWORD dst_unused:UNUSED_PAD src0_sel:WORD_1 src1_sel:DWORD
	v_add3_u32 v8, v8, v12, s65
	v_add3_u32 v5, v9, v5, s65
	v_and_b32_sdwa v9, v11, v209 dst_sel:DWORD dst_unused:UNUSED_PAD src0_sel:WORD_1 src1_sel:DWORD
	v_and_b32_sdwa v12, v10, v209 dst_sel:DWORD dst_unused:UNUSED_PAD src0_sel:WORD_1 src1_sel:DWORD
	v_add3_u32 v9, v11, v9, s65
	v_add3_u32 v10, v10, v12, s65
	v_and_b32_e32 v9, 0xffff0000, v9
	v_and_b32_e32 v10, 0xffff0000, v10
	v_or_b32_sdwa v9, v9, v5 dst_sel:DWORD dst_unused:UNUSED_PAD src0_sel:DWORD src1_sel:WORD_1
	v_or_b32_sdwa v8, v10, v8 dst_sel:DWORD dst_unused:UNUSED_PAD src0_sel:DWORD src1_sel:WORD_1
	global_store_dwordx2 v[64:65], v[8:9], off offset:1200
	s_waitcnt vmcnt(15)
; __device__ __forceinline__ unsigned pack2(float a, float b) { return (unsigned)f2bf(a) | ((unsigned)f2bf(b) << 16); }
; __device__ __forceinline__ float bflo(unsigned u) { return __uint_as_float(u << 16); }
; __device__ __forceinline__ float bfhi(unsigned u) { return __uint_as_float(u & 0xffff0000u); }
; __device__ void retout_task(const Params& p, int n, int hh, char* smem) {
;     ...
;   const u16* gp = p.H + (long)pos * INC + 4608 + hh * 128;
;   u16* op = p.MIXIN + (long)pos * D_ + 512 + hh * 128;
; #pragma unroll
;   for (int mb = 0; mb < 4; ++mb)
; #pragma unroll
;     for (int g4 = 0; g4 < 4; ++g4) {
;       int e0 = mb * 32 + 8 * g4 + 4 * hf;
;       uint2 graw = *(const uint2*)(gp + e0);
;       float gv[4] = {bflo(graw.x), bfhi(graw.x), bflo(graw.y), bfhi(graw.y)};
;       float y[4];
; #pragma unroll
;       for (int j = 0; j < 4; ++j) {
;         float yn = (acc[mb][4 * g4 + j] - mu) * rstd;
;         float sg = gv[j] / (1.f + __expf(-gv[j]));
;         y[j] = sg * yn;
;       }
;       uint2 pk; pk.x = pack2(y[0], y[1]); pk.y = pack2(y[2], y[3]);
;       *(uint2*)(op + e0) = pk;
;     }
	v_mov_b32_e32 v8, v158
	v_mov_b32_e32 v9, v159
	v_and_b32_e32 v15, 0xffff0000, v8
	v_lshlrev_b32_e32 v5, 16, v9
	v_lshlrev_b32_e32 v13, 16, v8
	v_and_b32_e32 v14, 0xffff0000, v9
	v_mul_f32_e32 v9, 0xbfb8aa3b, v15
	v_mul_f32_e32 v8, 0xbfb8aa3b, v13
	v_exp_f32_e32 v12, v9
	v_mul_f32_e32 v9, 0xbfb8aa3b, v5
	v_exp_f32_e32 v8, v8
	v_exp_f32_e32 v9, v9
	v_pk_mul_f32 v[10:11], v[24:25], v[4:5] op_sel_hi:[1,0]
	v_pk_add_f32 v[8:9], v[8:9], 1.0 op_sel_hi:[1,0]
	s_nop 0
	v_div_scale_f32 v24, s[0:1], v9, v9, v5
	v_rcp_f32_e32 v25, v24
	s_nop 0
	v_fma_f32 v26, -v24, v25, 1.0
	v_fmac_f32_e32 v25, v26, v25
	v_div_scale_f32 v26, vcc, v5, v9, v5
	v_mul_f32_e32 v27, v26, v25
	v_fma_f32 v28, -v24, v27, v26
	v_fmac_f32_e32 v27, v28, v25
	v_fma_f32 v24, -v24, v27, v26
	v_div_fmas_f32 v24, v24, v25, v27
	v_div_fixup_f32 v9, v24, v9, v5
	v_div_scale_f32 v5, s[0:1], v8, v8, v13
	v_rcp_f32_e32 v24, v5
	s_nop 0
	v_fma_f32 v25, -v5, v24, 1.0
	v_fmac_f32_e32 v24, v25, v24
	v_div_scale_f32 v25, vcc, v13, v8, v13
	v_mul_f32_e32 v26, v25, v24
	v_fma_f32 v27, -v5, v26, v25
	v_fmac_f32_e32 v26, v27, v24
	v_fma_f32 v5, -v5, v26, v25
	v_div_fmas_f32 v5, v5, v24, v26
	v_div_fixup_f32 v8, v5, v8, v13
	v_pk_mul_f32 v[8:9], v[8:9], v[10:11]
	v_pk_mul_f32 v[10:11], v[22:23], v[4:5] op_sel_hi:[1,0]
	v_mul_f32_e32 v5, 0xbfb8aa3b, v14
	v_exp_f32_e32 v13, v5
	s_nop 0
	v_pk_add_f32 v[12:13], v[12:13], 1.0 op_sel_hi:[1,0]
	s_nop 0
	v_div_scale_f32 v5, s[0:1], v13, v13, v14
	v_rcp_f32_e32 v22, v5
	s_nop 0
	v_fma_f32 v23, -v5, v22, 1.0
	v_fmac_f32_e32 v22, v23, v22
	v_div_scale_f32 v23, vcc, v14, v13, v14
	v_mul_f32_e32 v24, v23, v22
	v_fma_f32 v25, -v5, v24, v23
	v_fmac_f32_e32 v24, v25, v22
	v_fma_f32 v5, -v5, v24, v23
	v_div_fmas_f32 v5, v5, v22, v24
	v_div_fixup_f32 v13, v5, v13, v14
	v_div_scale_f32 v5, s[0:1], v12, v12, v15
	v_rcp_f32_e32 v14, v5
	s_nop 0
	v_fma_f32 v22, -v5, v14, 1.0
	v_fmac_f32_e32 v14, v22, v14
	v_div_scale_f32 v22, vcc, v15, v12, v15
	v_mul_f32_e32 v23, v22, v14
	v_fma_f32 v24, -v5, v23, v22
	v_fmac_f32_e32 v23, v24, v14
	v_fma_f32 v5, -v5, v23, v22
	v_div_fmas_f32 v5, v5, v14, v23
	v_div_fixup_f32 v12, v5, v12, v15
	v_pk_mul_f32 v[10:11], v[12:13], v[10:11]
	v_and_b32_sdwa v5, v9, v209 dst_sel:DWORD dst_unused:UNUSED_PAD src0_sel:WORD_1 src1_sel:DWORD
	v_and_b32_sdwa v12, v8, v209 dst_sel:DWORD dst_unused:UNUSED_PAD src0_sel:WORD_1 src1_sel:DWORD
	v_add3_u32 v8, v8, v12, s65
	v_add3_u32 v5, v9, v5, s65
	v_and_b32_sdwa v9, v11, v209 dst_sel:DWORD dst_unused:UNUSED_PAD src0_sel:WORD_1 src1_sel:DWORD
	v_and_b32_sdwa v12, v10, v209 dst_sel:DWORD dst_unused:UNUSED_PAD src0_sel:WORD_1 src1_sel:DWORD
	v_add3_u32 v9, v11, v9, s65
	v_add3_u32 v10, v10, v12, s65
	v_and_b32_e32 v9, 0xffff0000, v9
	v_and_b32_e32 v10, 0xffff0000, v10
	v_or_b32_sdwa v9, v9, v5 dst_sel:DWORD dst_unused:UNUSED_PAD src0_sel:DWORD src1_sel:WORD_1
	v_or_b32_sdwa v8, v10, v8 dst_sel:DWORD dst_unused:UNUSED_PAD src0_sel:DWORD src1_sel:WORD_1
	global_store_dwordx2 v[64:65], v[8:9], off offset:1216
	s_waitcnt vmcnt(15)
	v_mov_b32_e32 v8, v160
	v_mov_b32_e32 v9, v161
	v_and_b32_e32 v15, 0xffff0000, v8
	v_lshlrev_b32_e32 v5, 16, v9
	v_lshlrev_b32_e32 v13, 16, v8
	v_and_b32_e32 v14, 0xffff0000, v9
	v_mul_f32_e32 v9, 0xbfb8aa3b, v15
	v_mul_f32_e32 v8, 0xbfb8aa3b, v13
	v_exp_f32_e32 v12, v9
	v_mul_f32_e32 v9, 0xbfb8aa3b, v5
	v_exp_f32_e32 v8, v8
	v_exp_f32_e32 v9, v9
	v_pk_mul_f32 v[10:11], v[20:21], v[4:5] op_sel_hi:[1,0]
	v_pk_add_f32 v[8:9], v[8:9], 1.0 op_sel_hi:[1,0]
	s_nop 0
	v_div_scale_f32 v20, s[0:1], v9, v9, v5
	v_rcp_f32_e32 v21, v20
	s_nop 0
	v_fma_f32 v22, -v20, v21, 1.0
	v_fmac_f32_e32 v21, v22, v21
	v_div_scale_f32 v22, vcc, v5, v9, v5
	v_mul_f32_e32 v23, v22, v21
	v_fma_f32 v24, -v20, v23, v22
	v_fmac_f32_e32 v23, v24, v21
	v_fma_f32 v20, -v20, v23, v22
	v_div_fmas_f32 v20, v20, v21, v23
	v_div_fixup_f32 v9, v20, v9, v5
	v_div_scale_f32 v5, s[0:1], v8, v8, v13
	v_rcp_f32_e32 v20, v5
	s_nop 0
	v_fma_f32 v21, -v5, v20, 1.0
	v_fmac_f32_e32 v20, v21, v20
	v_div_scale_f32 v21, vcc, v13, v8, v13
	v_mul_f32_e32 v22, v21, v20
	v_fma_f32 v23, -v5, v22, v21
	v_fmac_f32_e32 v22, v23, v20
	v_fma_f32 v5, -v5, v22, v21
	v_div_fmas_f32 v5, v5, v20, v22
	v_div_fixup_f32 v8, v5, v8, v13
	v_pk_mul_f32 v[8:9], v[8:9], v[10:11]
	v_pk_mul_f32 v[10:11], v[18:19], v[4:5] op_sel_hi:[1,0]
	v_mul_f32_e32 v5, 0xbfb8aa3b, v14
	v_exp_f32_e32 v13, v5
	s_nop 0
	v_pk_add_f32 v[12:13], v[12:13], 1.0 op_sel_hi:[1,0]
	s_nop 0
	v_div_scale_f32 v5, s[0:1], v13, v13, v14
	v_rcp_f32_e32 v18, v5
	s_nop 0
	v_fma_f32 v19, -v5, v18, 1.0
	v_fmac_f32_e32 v18, v19, v18
	v_div_scale_f32 v19, vcc, v14, v13, v14
	v_mul_f32_e32 v20, v19, v18
	v_fma_f32 v21, -v5, v20, v19
	v_fmac_f32_e32 v20, v21, v18
	v_fma_f32 v5, -v5, v20, v19
	v_div_fmas_f32 v5, v5, v18, v20
	v_div_fixup_f32 v13, v5, v13, v14
	v_div_scale_f32 v5, s[0:1], v12, v12, v15
	v_rcp_f32_e32 v14, v5
	s_nop 0
	v_fma_f32 v18, -v5, v14, 1.0
	v_fmac_f32_e32 v14, v18, v14
	v_div_scale_f32 v18, vcc, v15, v12, v15
	v_mul_f32_e32 v19, v18, v14
	v_fma_f32 v20, -v5, v19, v18
	v_fmac_f32_e32 v19, v20, v14
	v_fma_f32 v5, -v5, v19, v18
	v_div_fmas_f32 v5, v5, v14, v19
	v_div_fixup_f32 v12, v5, v12, v15
	v_pk_mul_f32 v[10:11], v[12:13], v[10:11]
	v_and_b32_sdwa v5, v9, v209 dst_sel:DWORD dst_unused:UNUSED_PAD src0_sel:WORD_1 src1_sel:DWORD
	v_and_b32_sdwa v12, v8, v209 dst_sel:DWORD dst_unused:UNUSED_PAD src0_sel:WORD_1 src1_sel:DWORD
	v_add3_u32 v8, v8, v12, s65
	v_add3_u32 v5, v9, v5, s65
	v_and_b32_sdwa v9, v11, v209 dst_sel:DWORD dst_unused:UNUSED_PAD src0_sel:WORD_1 src1_sel:DWORD
	v_and_b32_sdwa v12, v10, v209 dst_sel:DWORD dst_unused:UNUSED_PAD src0_sel:WORD_1 src1_sel:DWORD
	v_add3_u32 v9, v11, v9, s65
	v_add3_u32 v10, v10, v12, s65
	v_and_b32_e32 v9, 0xffff0000, v9
	v_and_b32_e32 v10, 0xffff0000, v10
	v_or_b32_sdwa v9, v9, v5 dst_sel:DWORD dst_unused:UNUSED_PAD src0_sel:DWORD src1_sel:WORD_1
	v_or_b32_sdwa v8, v10, v8 dst_sel:DWORD dst_unused:UNUSED_PAD src0_sel:DWORD src1_sel:WORD_1
	global_store_dwordx2 v[64:65], v[8:9], off offset:1232
	s_waitcnt vmcnt(15)
; __device__ __forceinline__ unsigned pack2(float a, float b) { return (unsigned)f2bf(a) | ((unsigned)f2bf(b) << 16); }
; __device__ __forceinline__ float bflo(unsigned u) { return __uint_as_float(u << 16); }
; __device__ __forceinline__ float bfhi(unsigned u) { return __uint_as_float(u & 0xffff0000u); }
; __device__ void retout_task(const Params& p, int n, int hh, char* smem) {
;     ...
;   const u16* gp = p.H + (long)pos * INC + 4608 + hh * 128;
;   u16* op = p.MIXIN + (long)pos * D_ + 512 + hh * 128;
; #pragma unroll
;   for (int mb = 0; mb < 4; ++mb)
; #pragma unroll
;     for (int g4 = 0; g4 < 4; ++g4) {
;       int e0 = mb * 32 + 8 * g4 + 4 * hf;
;       uint2 graw = *(const uint2*)(gp + e0);
;       float gv[4] = {bflo(graw.x), bfhi(graw.x), bflo(graw.y), bfhi(graw.y)};
;       float y[4];
; #pragma unroll
;       for (int j = 0; j < 4; ++j) {
;         float yn = (acc[mb][4 * g4 + j] - mu) * rstd;
;         float sg = gv[j] / (1.f + __expf(-gv[j]));
;         y[j] = sg * yn;
;       }
;       uint2 pk; pk.x = pack2(y[0], y[1]); pk.y = pack2(y[2], y[3]);
;       *(uint2*)(op + e0) = pk;
;     }
; __device__ __forceinline__ void xcd_barrier(const XcdBarrier& b) {
;   asm volatile("s_waitcnt vmcnt(0)" ::: "memory");
;   __syncthreads();
;   if (threadIdx.x == 0) {
;     unsigned* bar = b.bar;
;     __builtin_amdgcn_s_waitcnt(0);
;     unsigned nloc = b.st[0], nx = b.st[1];
;     if (nloc == 0u) { xcd_barrier_complete(bar, b.x, nloc, nx); b.st[0] = nloc; b.st[1] = nx; }
	v_mov_b32_e32 v8, v162
	v_mov_b32_e32 v9, v163
	v_and_b32_e32 v15, 0xffff0000, v8
	v_lshlrev_b32_e32 v5, 16, v9
	v_lshlrev_b32_e32 v11, 16, v8
	v_and_b32_e32 v14, 0xffff0000, v9
	v_mul_f32_e32 v9, 0xbfb8aa3b, v15
	v_mul_f32_e32 v8, 0xbfb8aa3b, v11
	v_exp_f32_e32 v10, v9
	v_mul_f32_e32 v9, 0xbfb8aa3b, v5
	v_exp_f32_e32 v8, v8
	v_exp_f32_e32 v9, v9
	v_pk_mul_f32 v[12:13], v[16:17], v[4:5] op_sel_hi:[1,0]
	v_pk_add_f32 v[8:9], v[8:9], 1.0 op_sel_hi:[1,0]
	s_nop 0
	v_div_scale_f32 v16, s[0:1], v9, v9, v5
	v_rcp_f32_e32 v17, v16
	s_nop 0
	v_fma_f32 v18, -v16, v17, 1.0
	v_fmac_f32_e32 v17, v18, v17
	v_div_scale_f32 v18, vcc, v5, v9, v5
	v_mul_f32_e32 v19, v18, v17
	v_fma_f32 v20, -v16, v19, v18
	v_fmac_f32_e32 v19, v20, v17
	v_fma_f32 v16, -v16, v19, v18
	v_div_fmas_f32 v16, v16, v17, v19
	v_div_fixup_f32 v9, v16, v9, v5
	v_div_scale_f32 v5, s[0:1], v8, v8, v11
	v_rcp_f32_e32 v16, v5
	s_nop 0
	v_fma_f32 v17, -v5, v16, 1.0
	v_fmac_f32_e32 v16, v17, v16
	v_div_scale_f32 v17, vcc, v11, v8, v11
	v_mul_f32_e32 v18, v17, v16
	v_fma_f32 v19, -v5, v18, v17
	v_fmac_f32_e32 v18, v19, v16
	v_fma_f32 v5, -v5, v18, v17
	v_div_fmas_f32 v5, v5, v16, v18
	v_div_fixup_f32 v8, v5, v8, v11
	v_pk_mul_f32 v[6:7], v[6:7], v[4:5] op_sel_hi:[1,0]
	v_mul_f32_e32 v5, 0xbfb8aa3b, v14
	v_exp_f32_e32 v11, v5
	v_pk_mul_f32 v[8:9], v[8:9], v[12:13]
	v_pk_add_f32 v[10:11], v[10:11], 1.0 op_sel_hi:[1,0]
	s_nop 0
	v_div_scale_f32 v5, s[0:1], v11, v11, v14
	v_rcp_f32_e32 v12, v5
	s_nop 0
	v_fma_f32 v13, -v5, v12, 1.0
	v_fmac_f32_e32 v12, v13, v12
	v_div_scale_f32 v13, vcc, v14, v11, v14
	v_mul_f32_e32 v16, v13, v12
	v_fma_f32 v17, -v5, v16, v13
	v_fmac_f32_e32 v16, v17, v12
	v_fma_f32 v5, -v5, v16, v13
	v_div_fmas_f32 v5, v5, v12, v16
	v_div_fixup_f32 v11, v5, v11, v14
	v_div_scale_f32 v5, s[0:1], v10, v10, v15
	v_rcp_f32_e32 v12, v5
	s_nop 0
	v_fma_f32 v13, -v5, v12, 1.0
	v_fmac_f32_e32 v12, v13, v12
	v_div_scale_f32 v13, vcc, v15, v10, v15
	v_mul_f32_e32 v14, v13, v12
	v_fma_f32 v16, -v5, v14, v13
	v_fmac_f32_e32 v14, v16, v12
	v_fma_f32 v5, -v5, v14, v13
	v_div_fmas_f32 v5, v5, v12, v14
	v_div_fixup_f32 v10, v5, v10, v15
	v_pk_mul_f32 v[6:7], v[10:11], v[6:7]
	v_and_b32_sdwa v5, v9, v209 dst_sel:DWORD dst_unused:UNUSED_PAD src0_sel:WORD_1 src1_sel:DWORD
	v_and_b32_sdwa v10, v8, v209 dst_sel:DWORD dst_unused:UNUSED_PAD src0_sel:WORD_1 src1_sel:DWORD
	v_add3_u32 v8, v8, v10, s65
	v_add3_u32 v5, v9, v5, s65
	v_and_b32_sdwa v9, v7, v209 dst_sel:DWORD dst_unused:UNUSED_PAD src0_sel:WORD_1 src1_sel:DWORD
	v_and_b32_sdwa v10, v6, v209 dst_sel:DWORD dst_unused:UNUSED_PAD src0_sel:WORD_1 src1_sel:DWORD
	v_add3_u32 v7, v7, v9, s65
	v_add3_u32 v6, v6, v10, s65
	v_and_b32_e32 v7, 0xffff0000, v7
	v_and_b32_e32 v6, 0xffff0000, v6
	v_or_b32_sdwa v7, v7, v5 dst_sel:DWORD dst_unused:UNUSED_PAD src0_sel:DWORD src1_sel:WORD_1
	v_or_b32_sdwa v6, v6, v8 dst_sel:DWORD dst_unused:UNUSED_PAD src0_sel:DWORD src1_sel:WORD_1
	global_store_dwordx2 v[64:65], v[6:7], off offset:1248
	s_waitcnt vmcnt(15)
	v_mov_b32_e32 v6, v164
	v_mov_b32_e32 v7, v165
	v_and_b32_e32 v11, 0xffff0000, v6
	v_lshlrev_b32_e32 v5, 16, v7
	v_lshlrev_b32_e32 v9, 16, v6
	v_and_b32_e32 v10, 0xffff0000, v7
	v_mul_f32_e32 v7, 0xbfb8aa3b, v11
	v_mul_f32_e32 v6, 0xbfb8aa3b, v9
	v_exp_f32_e32 v8, v7
	v_mul_f32_e32 v7, 0xbfb8aa3b, v5
	v_exp_f32_e32 v6, v6
	v_exp_f32_e32 v7, v7
	v_pk_mul_f32 v[2:3], v[2:3], v[4:5] op_sel_hi:[1,0]
	v_pk_add_f32 v[6:7], v[6:7], 1.0 op_sel_hi:[1,0]
	s_nop 0
	v_div_scale_f32 v12, s[0:1], v7, v7, v5
	v_rcp_f32_e32 v13, v12
	s_nop 0
	v_fma_f32 v14, -v12, v13, 1.0
	v_fmac_f32_e32 v13, v14, v13
	v_div_scale_f32 v14, vcc, v5, v7, v5
	v_mul_f32_e32 v15, v14, v13
	v_fma_f32 v16, -v12, v15, v14
	v_fmac_f32_e32 v15, v16, v13
	v_fma_f32 v12, -v12, v15, v14
	v_div_fmas_f32 v12, v12, v13, v15
	v_div_fixup_f32 v7, v12, v7, v5
	v_div_scale_f32 v5, s[0:1], v6, v6, v9
	v_rcp_f32_e32 v12, v5
	s_nop 0
	v_fma_f32 v13, -v5, v12, 1.0
	v_fmac_f32_e32 v12, v13, v12
	v_div_scale_f32 v13, vcc, v9, v6, v9
	v_mul_f32_e32 v14, v13, v12
	v_fma_f32 v15, -v5, v14, v13
	v_fmac_f32_e32 v14, v15, v12
	v_fma_f32 v5, -v5, v14, v13
	v_div_fmas_f32 v5, v5, v12, v14
	v_pk_mul_f32 v[0:1], v[0:1], v[4:5] op_sel_hi:[1,0]
	v_mul_f32_e32 v4, 0xbfb8aa3b, v10
	v_div_fixup_f32 v6, v5, v6, v9
	v_exp_f32_e32 v9, v4
	v_pk_mul_f32 v[2:3], v[6:7], v[2:3]
	v_pk_add_f32 v[4:5], v[8:9], 1.0 op_sel_hi:[1,0]
	s_nop 0
	v_div_scale_f32 v6, s[0:1], v5, v5, v10
	v_rcp_f32_e32 v7, v6
	s_nop 0
	v_fma_f32 v8, -v6, v7, 1.0
	v_fmac_f32_e32 v7, v8, v7
	v_div_scale_f32 v8, vcc, v10, v5, v10
	v_mul_f32_e32 v9, v8, v7
	v_fma_f32 v12, -v6, v9, v8
	v_fmac_f32_e32 v9, v12, v7
	v_fma_f32 v6, -v6, v9, v8
	v_div_fmas_f32 v6, v6, v7, v9
	v_div_fixup_f32 v5, v6, v5, v10
	v_div_scale_f32 v6, s[0:1], v4, v4, v11
	v_rcp_f32_e32 v7, v6
	s_nop 0
	v_fma_f32 v8, -v6, v7, 1.0
	v_fmac_f32_e32 v7, v8, v7
	v_div_scale_f32 v8, vcc, v11, v4, v11
	v_mul_f32_e32 v9, v8, v7
	v_fma_f32 v10, -v6, v9, v8
	v_fmac_f32_e32 v9, v10, v7
	v_fma_f32 v6, -v6, v9, v8
	v_div_fmas_f32 v6, v6, v7, v9
	v_div_fixup_f32 v4, v6, v4, v11
	v_pk_mul_f32 v[0:1], v[4:5], v[0:1]
	v_and_b32_sdwa v4, v3, v209 dst_sel:DWORD dst_unused:UNUSED_PAD src0_sel:WORD_1 src1_sel:DWORD
	v_and_b32_sdwa v5, v2, v209 dst_sel:DWORD dst_unused:UNUSED_PAD src0_sel:WORD_1 src1_sel:DWORD
	v_add3_u32 v2, v2, v5, s65
	v_add3_u32 v3, v3, v4, s65
	v_and_b32_sdwa v4, v1, v209 dst_sel:DWORD dst_unused:UNUSED_PAD src0_sel:WORD_1 src1_sel:DWORD
	v_and_b32_sdwa v5, v0, v209 dst_sel:DWORD dst_unused:UNUSED_PAD src0_sel:WORD_1 src1_sel:DWORD
	v_add3_u32 v1, v1, v4, s65
	v_add3_u32 v0, v0, v5, s65
	v_and_b32_e32 v1, 0xffff0000, v1
	v_and_b32_e32 v0, 0xffff0000, v0
	v_or_b32_sdwa v1, v1, v3 dst_sel:DWORD dst_unused:UNUSED_PAD src0_sel:DWORD src1_sel:WORD_1
	v_or_b32_sdwa v0, v0, v2 dst_sel:DWORD dst_unused:UNUSED_PAD src0_sel:DWORD src1_sel:WORD_1
	global_store_dwordx2 v[64:65], v[0:1], off offset:1264
	s_cbranch_scc1 .LBB0_1009
	s_waitcnt vmcnt(0)
	s_barrier
	s_and_saveexec_b64 s[0:1], s[96:97]
	s_cbranch_execz .LBB0_1064
	s_waitcnt vmcnt(0) expcnt(0) lgkmcnt(0)
	ds_read_b32 v2, v177
	ds_read_b32 v0, v177 offset:4
	s_waitcnt lgkmcnt(1)
	v_cmp_ne_u32_e32 vcc, 0, v2
	s_cbranch_vccnz .LBB0_1028
	s_mov_b32 s11, 1
	s_branch .LBB0_1016

; #define PG8_STAGE(bufoff, gbase, voff) do { _Pragma("unroll") for (int _i = 0; _i < 2; ++_i) \
;     __builtin_amdgcn_global_load_lds((const unsigned*)((const char*)(gbase) + (voff)[_i]), (PG8_LAS unsigned*)(lds + (bufoff) + ldsw + _i * 8192), 16, 0, 0); } while (0)
; #define PG8_LDA(dst, b, h) do { _Pragma("unroll") for (int m = 0; m < 4; ++m) _Pragma("unroll") for (int k = 0; k < 2; ++k) dst[m][k] = *(const PG8_LAS bf16x8*)(lds + PG8_SA(b, h) + aoff + m * 2048 + k * 1024); } while (0)
; #define PG8_LDB(dst, b, h) do { _Pragma("unroll") for (int n = 0; n < 2; ++n) _Pragma("unroll") for (int k = 0; k < 2; ++k) dst[n][k] = *(const PG8_LAS bf16x8*)(lds + PG8_SB(b, h) + boff + n * 2048 + k * 1024); } while (0)
; #define PG8_MMA(ai, bj, At, Bt) do { __builtin_amdgcn_s_setprio(2); _Pragma("unroll") for (int m = 0; m < 4; ++m) _Pragma("unroll") for (int n = 0; n < 2; ++n) _Pragma("unroll") for (int k = 0; k < 2; ++k) \
;     acc[ai][bj][m][n] = __builtin_amdgcn_mfma_f32_16x16x32_bf16(Bt[n][k], At[m][k], acc[ai][bj][m][n], 0, 0, 0); __builtin_amdgcn_s_setprio(0); } while (0)
; #define PG8_WAIT_V(n) asm volatile("s_waitcnt vmcnt(" #n ")" ::: "memory")
; #define PG8_WAIT_L(n) asm volatile("s_waitcnt lgkmcnt(" #n ")" ::: "memory")
; #define PG8_BAR __builtin_amdgcn_s_barrier()
; #define PG8_SCHED __builtin_amdgcn_sched_barrier(0)
; template <class Epi, class Sched>
; __device__ __forceinline__ void gemm_phase(PG8_LAS unsigned char* lds, const Gemm g, const Sched& S, const Epi& E) {
;     ...
;       PG8_LDB(B0, 0, 0); PG8_SCHED; PG8_LDA(At, 0, 0); PG8_STAGE(PG8_SA(1, 1), a1 + hstep, voffA);
;       PG8_WAIT_L(8); PG8_BAR; PG8_WAIT_L(0); PG8_MMA(0, 0, At, B0); PG8_BAR; PG8_SCHED;
;       PG8_LDB(B1, 0, 1); PG8_STAGE(PG8_SB(0, 0), b2, voffB);
;       PG8_BAR; PG8_WAIT_L(0); PG8_MMA(0, 1, At, B1); PG8_BAR;
;       PG8_LDA(At, 0, 1); PG8_STAGE(PG8_SA(0, 0), a2, voffA);
;       PG8_BAR; PG8_WAIT_L(0); PG8_MMA(1, 0, At, B0); PG8_BAR; PG8_SCHED;
;       PG8_STAGE(PG8_SB(0, 1), b2 + hstep, voffB);
;       PG8_WAIT_V(6); PG8_BAR; PG8_MMA(1, 1, At, B1); PG8_BAR;
.LBB0_1075:
	s_add_u32 s4, s90, 0xfff80080
	s_addc_u32 s5, s91, -1
	s_add_i32 s75, 16, 0x10000
	v_add_u32_e32 v142, s75, v146
	ds_read_b128 v[138:141], v142
	ds_read_b128 v[150:153], v142 offset:1024
	ds_read_b128 v[154:157], v142 offset:2048
	ds_read_b128 v[158:161], v142 offset:3072
	s_cmp_eq_u32 s74, 28
	s_cselect_b32 vcc_hi, s41, s5
	s_cselect_b32 vcc_lo, s69, s4
	s_cselect_b32 s89, s1, s11
	s_cselect_b32 s88, s72, s73
	v_lshl_add_u64 v[142:143], s[90:91], 0, v[134:135]
	s_add_i32 m0, s77, 0xc000
	ds_read_b128 v[162:165], v148
	ds_read_b128 v[166:169], v148 offset:1024
	ds_read_b128 v[170:173], v148 offset:2048
	ds_read_b128 v[186:189], v148 offset:3072
	ds_read_b128 v[190:193], v148 offset:4096
	ds_read_b128 v[194:197], v148 offset:5120
	ds_read_b128 v[198:201], v148 offset:6144
	ds_read_b128 v[202:205], v148 offset:7168
	global_load_lds_dwordx4 v[142:143], off
	v_lshl_add_u64 v[142:143], s[90:91], 0, v[136:137]
	s_add_i32 m0, s77, 0xe000
	s_nop 0
	global_load_lds_dwordx4 v[142:143], off
	s_waitcnt lgkmcnt(8)
	s_barrier
	s_waitcnt lgkmcnt(0)
	s_setprio 2
	s_waitcnt lgkmcnt(0)
	v_mfma_f32_16x16x32_bf16 v[124:127], v[138:141], v[162:165], v[124:127]
	v_mfma_f32_16x16x32_bf16 v[120:123], v[154:157], v[162:165], v[120:123]
	v_mfma_f32_16x16x32_bf16 v[108:111], v[138:141], v[170:173], v[108:111]
	v_mfma_f32_16x16x32_bf16 v[104:107], v[154:157], v[170:173], v[104:107]
	v_mfma_f32_16x16x32_bf16 v[92:95], v[138:141], v[190:193], v[92:95]
	v_mfma_f32_16x16x32_bf16 v[88:91], v[154:157], v[190:193], v[88:91]
	v_mfma_f32_16x16x32_bf16 v[76:79], v[138:141], v[198:201], v[76:79]
	v_mfma_f32_16x16x32_bf16 v[72:75], v[154:157], v[198:201], v[72:75]
	v_mfma_f32_16x16x32_bf16 v[124:127], v[150:153], v[166:169], v[124:127]
	v_mfma_f32_16x16x32_bf16 v[120:123], v[158:161], v[166:169], v[120:123]
	v_mfma_f32_16x16x32_bf16 v[108:111], v[150:153], v[186:189], v[108:111]
	v_mfma_f32_16x16x32_bf16 v[104:107], v[158:161], v[186:189], v[104:107]
	v_mfma_f32_16x16x32_bf16 v[92:95], v[150:153], v[194:197], v[92:95]
	v_mfma_f32_16x16x32_bf16 v[88:91], v[158:161], v[194:197], v[88:91]
	v_mfma_f32_16x16x32_bf16 v[76:79], v[150:153], v[202:205], v[76:79]
	v_mfma_f32_16x16x32_bf16 v[72:75], v[158:161], v[202:205], v[72:75]
	s_setprio 0
	s_barrier
	s_add_i32 s4, 16, 0x14000
	v_add_u32_e32 v142, s4, v146
	s_add_i32 s5, s75, s76
	ds_read_b128 v[232:235], v142
	ds_read_b128 v[236:239], v142 offset:1024
	ds_read_b128 v[240:243], v142 offset:2048
	ds_read_b128 v[244:247], v142 offset:3072
	v_lshl_add_u64 v[142:143], s[88:89], 0, v[176:177]
	s_mov_b32 m0, s5
	v_lshl_add_u64 v[174:175], s[88:89], 0, v[128:129]
	global_load_lds_dwordx4 v[142:143], off
	s_add_i32 m0, s5, 0x2000
	s_nop 0
	global_load_lds_dwordx4 v[174:175], off
	s_barrier
	s_waitcnt lgkmcnt(0)
	s_setprio 2
	s_waitcnt lgkmcnt(0)
	v_mfma_f32_16x16x32_bf16 v[116:119], v[232:235], v[162:165], v[116:119]
	v_mfma_f32_16x16x32_bf16 v[112:115], v[240:243], v[162:165], v[112:115]
	v_mfma_f32_16x16x32_bf16 v[100:103], v[232:235], v[170:173], v[100:103]
	v_mfma_f32_16x16x32_bf16 v[96:99], v[240:243], v[170:173], v[96:99]
	v_mfma_f32_16x16x32_bf16 v[84:87], v[232:235], v[190:193], v[84:87]
	v_mfma_f32_16x16x32_bf16 v[80:83], v[240:243], v[190:193], v[80:83]
	v_mfma_f32_16x16x32_bf16 v[68:71], v[232:235], v[198:201], v[68:71]
	v_mfma_f32_16x16x32_bf16 v[64:67], v[240:243], v[198:201], v[64:67]
	v_mfma_f32_16x16x32_bf16 v[116:119], v[236:239], v[166:169], v[116:119]
	v_mfma_f32_16x16x32_bf16 v[112:115], v[244:247], v[166:169], v[112:115]
	v_mfma_f32_16x16x32_bf16 v[100:103], v[236:239], v[186:189], v[100:103]
	v_mfma_f32_16x16x32_bf16 v[96:99], v[244:247], v[186:189], v[96:99]
	v_mfma_f32_16x16x32_bf16 v[84:87], v[236:239], v[194:197], v[84:87]
	v_mfma_f32_16x16x32_bf16 v[80:83], v[244:247], v[194:197], v[80:83]
	v_mfma_f32_16x16x32_bf16 v[68:71], v[236:239], v[202:205], v[68:71]
	v_mfma_f32_16x16x32_bf16 v[64:67], v[244:247], v[202:205], v[64:67]
	s_setprio 0
	s_mov_b32 m0, s77
	v_lshl_add_u64 v[210:211], vcc, 0, v[132:133]
	s_barrier
	ds_read_b128 v[162:165], v148 offset:16384
	ds_read_b128 v[166:169], v148 offset:17408
	ds_read_b128 v[170:173], v148 offset:18432
	ds_read_b128 v[186:189], v148 offset:19456
	ds_read_b128 v[190:193], v148 offset:20480
	ds_read_b128 v[194:197], v148 offset:21504
	ds_read_b128 v[198:201], v148 offset:22528
	ds_read_b128 v[202:205], v148 offset:23552
	global_load_lds_dwordx4 v[210:211], off
	v_lshl_add_u64 v[248:249], vcc, 0, v[130:131]
	s_mov_b32 m0, s96
	s_nop 0
	global_load_lds_dwordx4 v[248:249], off
	s_barrier
	s_waitcnt lgkmcnt(0)
	s_setprio 2
	s_waitcnt lgkmcnt(0)
	v_mfma_f32_16x16x32_bf16 v[60:63], v[138:141], v[162:165], v[60:63]
	v_mfma_f32_16x16x32_bf16 v[56:59], v[154:157], v[162:165], v[56:59]
	v_mfma_f32_16x16x32_bf16 v[44:47], v[138:141], v[170:173], v[44:47]
	v_mfma_f32_16x16x32_bf16 v[40:43], v[154:157], v[170:173], v[40:43]
	v_mfma_f32_16x16x32_bf16 v[28:31], v[138:141], v[190:193], v[28:31]
	v_mfma_f32_16x16x32_bf16 v[24:27], v[154:157], v[190:193], v[24:27]
	v_mfma_f32_16x16x32_bf16 v[12:15], v[138:141], v[198:201], v[12:15]
	v_mfma_f32_16x16x32_bf16 v[8:11], v[154:157], v[198:201], v[8:11]
	v_mfma_f32_16x16x32_bf16 v[60:63], v[150:153], v[166:169], v[60:63]
	v_mfma_f32_16x16x32_bf16 v[56:59], v[158:161], v[166:169], v[56:59]
	v_mfma_f32_16x16x32_bf16 v[44:47], v[150:153], v[186:189], v[44:47]
	v_mfma_f32_16x16x32_bf16 v[40:43], v[158:161], v[186:189], v[40:43]
	v_mfma_f32_16x16x32_bf16 v[28:31], v[150:153], v[194:197], v[28:31]
	v_mfma_f32_16x16x32_bf16 v[24:27], v[158:161], v[194:197], v[24:27]
	v_mfma_f32_16x16x32_bf16 v[12:15], v[150:153], v[202:205], v[12:15]
	v_mfma_f32_16x16x32_bf16 v[8:11], v[158:161], v[202:205], v[8:11]
	s_setprio 0
	s_barrier
; #define PG8_STAGE(bufoff, gbase, voff) do { _Pragma("unroll") for (int _i = 0; _i < 2; ++_i) \
;     __builtin_amdgcn_global_load_lds((const unsigned*)((const char*)(gbase) + (voff)[_i]), (PG8_LAS unsigned*)(lds + (bufoff) + ldsw + _i * 8192), 16, 0, 0); } while (0)
; #define PG8_LDA(dst, b, h) do { _Pragma("unroll") for (int m = 0; m < 4; ++m) _Pragma("unroll") for (int k = 0; k < 2; ++k) dst[m][k] = *(const PG8_LAS bf16x8*)(lds + PG8_SA(b, h) + aoff + m * 2048 + k * 1024); } while (0)
; #define PG8_LDB(dst, b, h) do { _Pragma("unroll") for (int n = 0; n < 2; ++n) _Pragma("unroll") for (int k = 0; k < 2; ++k) dst[n][k] = *(const PG8_LAS bf16x8*)(lds + PG8_SB(b, h) + boff + n * 2048 + k * 1024); } while (0)
; #define PG8_MMA(ai, bj, At, Bt) do { __builtin_amdgcn_s_setprio(2); _Pragma("unroll") for (int m = 0; m < 4; ++m) _Pragma("unroll") for (int n = 0; n < 2; ++n) _Pragma("unroll") for (int k = 0; k < 2; ++k) \
;     acc[ai][bj][m][n] = __builtin_amdgcn_mfma_f32_16x16x32_bf16(Bt[n][k], At[m][k], acc[ai][bj][m][n], 0, 0, 0); __builtin_amdgcn_s_setprio(0); } while (0)
; #define PG8_WAIT_V(n) asm volatile("s_waitcnt vmcnt(" #n ")" ::: "memory")
; #define PG8_WAIT_L(n) asm volatile("s_waitcnt lgkmcnt(" #n ")" ::: "memory")
; #define PG8_BAR __builtin_amdgcn_s_barrier()
; #define PG8_SCHED __builtin_amdgcn_sched_barrier(0)
; template <class Epi, class Sched>
; __device__ __forceinline__ void gemm_phase(PG8_LAS unsigned char* lds, const Gemm g, const Sched& S, const Epi& E) {
;     ...
;       PG8_WAIT_V(6); PG8_BAR; PG8_MMA(1, 1, At, B1); PG8_BAR;
;       PG8_LDB(B0, 1, 0); PG8_SCHED; PG8_LDA(At, 1, 0); PG8_STAGE(PG8_SA(0, 1), a2 + hstep, voffA);
;       PG8_WAIT_L(8); PG8_BAR; PG8_WAIT_L(0); PG8_MMA(0, 0, At, B0); PG8_BAR; PG8_SCHED;
;       PG8_LDB(B1, 1, 1); PG8_STAGE(PG8_SB(1, 0), b3, voffB);
;       PG8_BAR; PG8_WAIT_L(0); PG8_MMA(0, 1, At, B1); PG8_BAR;
;       PG8_LDA(At, 1, 1); PG8_STAGE(PG8_SA(1, 0), a3, voffA);
;       PG8_BAR; PG8_WAIT_L(0); PG8_MMA(1, 0, At, B0); PG8_BAR; PG8_SCHED;
	s_add_u32 s78, s88, 0x80000
	s_addc_u32 s79, s89, 0
	s_add_i32 s4, s4, s76
	v_lshl_add_u64 v[138:139], s[78:79], 0, v[176:177]
	s_mov_b32 m0, s4
	s_nop 0
	global_load_lds_dwordx4 v[138:139], off
	v_lshl_add_u64 v[138:139], s[78:79], 0, v[128:129]
	s_add_i32 m0, s4, 0x2000
	s_nop 0
	global_load_lds_dwordx4 v[138:139], off
	s_waitcnt vmcnt(6)
	s_barrier
	s_setprio 2
	v_mfma_f32_16x16x32_bf16 v[52:55], v[232:235], v[162:165], v[52:55]
	v_mfma_f32_16x16x32_bf16 v[48:51], v[240:243], v[162:165], v[48:51]
	v_mfma_f32_16x16x32_bf16 v[36:39], v[232:235], v[170:173], v[36:39]
	v_mfma_f32_16x16x32_bf16 v[32:35], v[240:243], v[170:173], v[32:35]
	v_mfma_f32_16x16x32_bf16 v[20:23], v[232:235], v[190:193], v[20:23]
	v_mfma_f32_16x16x32_bf16 v[16:19], v[240:243], v[190:193], v[16:19]
	v_mfma_f32_16x16x32_bf16 v[4:7], v[232:235], v[198:201], v[4:7]
	v_mfma_f32_16x16x32_bf16 v[0:3], v[240:243], v[198:201], v[0:3]
	v_mfma_f32_16x16x32_bf16 v[52:55], v[236:239], v[166:169], v[52:55]
	v_mfma_f32_16x16x32_bf16 v[48:51], v[244:247], v[166:169], v[48:51]
	v_mfma_f32_16x16x32_bf16 v[36:39], v[236:239], v[186:189], v[36:39]
	v_mfma_f32_16x16x32_bf16 v[32:35], v[244:247], v[186:189], v[32:35]
	v_mfma_f32_16x16x32_bf16 v[20:23], v[236:239], v[194:197], v[20:23]
	v_mfma_f32_16x16x32_bf16 v[16:19], v[244:247], v[194:197], v[16:19]
	v_mfma_f32_16x16x32_bf16 v[4:7], v[236:239], v[202:205], v[4:7]
	v_mfma_f32_16x16x32_bf16 v[0:3], v[244:247], v[202:205], v[0:3]
	s_setprio 0
	s_add_i32 s4, 16, 0x18000
	v_add_u32_e32 v149, s4, v146
	s_barrier
	ds_read_b128 v[138:141], v149
	ds_read_b128 v[150:153], v149 offset:1024
	ds_read_b128 v[154:157], v149 offset:2048
	ds_read_b128 v[158:161], v149 offset:3072
	s_add_u32 s78, vcc_lo, 0x80000
	s_addc_u32 s79, vcc_hi, 0
	s_mov_b32 m0, s97
	v_lshl_add_u64 v[232:233], s[78:79], 0, v[132:133]
	ds_read_b128 v[162:165], v148 offset:32768
	ds_read_b128 v[166:169], v148 offset:33792
	ds_read_b128 v[170:173], v148 offset:34816
	ds_read_b128 v[186:189], v148 offset:35840
	ds_read_b128 v[190:193], v148 offset:36864
	ds_read_b128 v[194:197], v148 offset:37888
	ds_read_b128 v[198:201], v148 offset:38912
	ds_read_b128 v[202:205], v148 offset:39936
	global_load_lds_dwordx4 v[232:233], off
	v_lshl_add_u64 v[232:233], s[78:79], 0, v[130:131]
	s_mov_b32 m0, s28
	s_nop 0
	global_load_lds_dwordx4 v[232:233], off
	s_waitcnt lgkmcnt(8)
	s_barrier
	s_waitcnt lgkmcnt(0)
	s_setprio 2
	s_waitcnt lgkmcnt(0)
	v_mfma_f32_16x16x32_bf16 v[124:127], v[138:141], v[162:165], v[124:127]
	v_mfma_f32_16x16x32_bf16 v[120:123], v[154:157], v[162:165], v[120:123]
	v_mfma_f32_16x16x32_bf16 v[108:111], v[138:141], v[170:173], v[108:111]
	v_mfma_f32_16x16x32_bf16 v[104:107], v[154:157], v[170:173], v[104:107]
	v_mfma_f32_16x16x32_bf16 v[92:95], v[138:141], v[190:193], v[92:95]
	v_mfma_f32_16x16x32_bf16 v[88:91], v[154:157], v[190:193], v[88:91]
	v_mfma_f32_16x16x32_bf16 v[76:79], v[138:141], v[198:201], v[76:79]
	v_mfma_f32_16x16x32_bf16 v[72:75], v[154:157], v[198:201], v[72:75]
	v_mfma_f32_16x16x32_bf16 v[124:127], v[150:153], v[166:169], v[124:127]
	v_mfma_f32_16x16x32_bf16 v[120:123], v[158:161], v[166:169], v[120:123]
	v_mfma_f32_16x16x32_bf16 v[108:111], v[150:153], v[186:189], v[108:111]
	v_mfma_f32_16x16x32_bf16 v[104:107], v[158:161], v[186:189], v[104:107]
	v_mfma_f32_16x16x32_bf16 v[92:95], v[150:153], v[194:197], v[92:95]
	v_mfma_f32_16x16x32_bf16 v[88:91], v[158:161], v[194:197], v[88:91]
	v_mfma_f32_16x16x32_bf16 v[76:79], v[150:153], v[202:205], v[76:79]
	v_mfma_f32_16x16x32_bf16 v[72:75], v[158:161], v[202:205], v[72:75]
	s_setprio 0
	s_barrier
	s_add_i32 s5, 16, 0x1c000
	s_add_i32 s4, s4, s76
	v_add_u32_e32 v149, s5, v146
	v_lshl_add_u64 v[142:143], v[142:143], 0, s[34:35]
	s_mov_b32 m0, s4
	ds_read_b128 v[232:235], v149
	ds_read_b128 v[236:239], v149 offset:1024
	ds_read_b128 v[240:243], v149 offset:2048
	ds_read_b128 v[244:247], v149 offset:3072
	global_load_lds_dwordx4 v[142:143], off
	v_lshl_add_u64 v[142:143], v[174:175], 0, s[34:35]
	s_add_i32 m0, s4, 0x2000
	s_nop 0
	global_load_lds_dwordx4 v[142:143], off
	s_barrier
	s_waitcnt lgkmcnt(0)
	s_setprio 2
	s_waitcnt lgkmcnt(0)
	v_mfma_f32_16x16x32_bf16 v[116:119], v[232:235], v[162:165], v[116:119]
	v_mfma_f32_16x16x32_bf16 v[112:115], v[240:243], v[162:165], v[112:115]
	v_mfma_f32_16x16x32_bf16 v[100:103], v[232:235], v[170:173], v[100:103]
	v_mfma_f32_16x16x32_bf16 v[96:99], v[240:243], v[170:173], v[96:99]
	v_mfma_f32_16x16x32_bf16 v[84:87], v[232:235], v[190:193], v[84:87]
	v_mfma_f32_16x16x32_bf16 v[80:83], v[240:243], v[190:193], v[80:83]
	v_mfma_f32_16x16x32_bf16 v[68:71], v[232:235], v[198:201], v[68:71]
	v_mfma_f32_16x16x32_bf16 v[64:67], v[240:243], v[198:201], v[64:67]
	v_mfma_f32_16x16x32_bf16 v[116:119], v[236:239], v[166:169], v[116:119]
	v_mfma_f32_16x16x32_bf16 v[112:115], v[244:247], v[166:169], v[112:115]
	v_mfma_f32_16x16x32_bf16 v[100:103], v[236:239], v[186:189], v[100:103]
	v_mfma_f32_16x16x32_bf16 v[96:99], v[244:247], v[186:189], v[96:99]
	v_mfma_f32_16x16x32_bf16 v[84:87], v[236:239], v[194:197], v[84:87]
	v_mfma_f32_16x16x32_bf16 v[80:83], v[244:247], v[194:197], v[80:83]
	v_mfma_f32_16x16x32_bf16 v[68:71], v[236:239], v[202:205], v[68:71]
	v_mfma_f32_16x16x32_bf16 v[64:67], v[244:247], v[202:205], v[64:67]
	s_setprio 0
	s_mov_b32 m0, s82
	v_lshl_add_u64 v[142:143], v[210:211], 0, s[34:35]
	s_barrier
	ds_read_b128 v[162:165], v148 offset:49152
	ds_read_b128 v[166:169], v148 offset:50176
	ds_read_b128 v[170:173], v148 offset:51200
	ds_read_b128 v[186:189], v148 offset:52224
	ds_read_b128 v[190:193], v148 offset:53248
	ds_read_b128 v[194:197], v148 offset:54272
	ds_read_b128 v[198:201], v148 offset:55296
	ds_read_b128 v[202:205], v148 offset:56320
	global_load_lds_dwordx4 v[142:143], off
	v_lshl_add_u64 v[142:143], v[248:249], 0, s[34:35]
	s_mov_b32 m0, s83
	s_nop 0
	global_load_lds_dwordx4 v[142:143], off
	s_barrier
; __device__ __forceinline__ float bflo(unsigned u) { return __uint_as_float(u << 16); }
; __device__ __forceinline__ float bfhi(unsigned u) { return __uint_as_float(u & 0xffff0000u); }
; __device__ __forceinline__ unsigned cvt_pk_bf16(float lo, float hi) { unsigned r; asm volatile("v_cvt_pk_bf16_f32 %0, %1, %2" : "=v"(r) : "v"(lo), "v"(hi)); return r; }
; #define PG8_STAGE(bufoff, gbase, voff) do { _Pragma("unroll") for (int _i = 0; _i < 2; ++_i) \
;     __builtin_amdgcn_global_load_lds((const unsigned*)((const char*)(gbase) + (voff)[_i]), (PG8_LAS unsigned*)(lds + (bufoff) + ldsw + _i * 8192), 16, 0, 0); } while (0)
; #define PG8_MMA(ai, bj, At, Bt) do { __builtin_amdgcn_s_setprio(2); _Pragma("unroll") for (int m = 0; m < 4; ++m) _Pragma("unroll") for (int n = 0; n < 2; ++n) _Pragma("unroll") for (int k = 0; k < 2; ++k) \
;     acc[ai][bj][m][n] = __builtin_amdgcn_mfma_f32_16x16x32_bf16(Bt[n][k], At[m][k], acc[ai][bj][m][n], 0, 0, 0); __builtin_amdgcn_s_setprio(0); } while (0)
; #define PG8_WAIT_V(n) asm volatile("s_waitcnt vmcnt(" #n ")" ::: "memory")
; #define PG8_BAR __builtin_amdgcn_s_barrier()
;   __device__ __forceinline__ void operator()(const f32x4 (&acc)[2][2][4][2], const Unit& u, int wr, int wc, int fr, int fq) const {
;     const int row0 = u.pm * BM + wr * 64 + fr, col0 = u.pn * BM + wc * 32 + 8 * fq;
; #pragma unroll
;     for (int ai = 0; ai < 2; ++ai)
; #pragma unroll
;       for (int m = 0; m < 4; ++m) { const size_t ro = (size_t)(row0 + ai * HALF + m * 16) * ldc + col0;
; #pragma unroll
;         for (int bj = 0; bj < 2; ++bj) { const u32x4 xr = *(const u32x4*)(X + ro + bj * HALF);
;           const f32x4 v0 = acc[ai][bj][m][0], v1 = acc[ai][bj][m][1];
;           u32x4 w;
;           w.x = cvt_pk_bf16(ALPHA * bflo(xr.x) + v0[0], ALPHA * bfhi(xr.x) + v0[1]); w.y = cvt_pk_bf16(ALPHA * bflo(xr.y) + v0[2], ALPHA * bfhi(xr.y) + v0[3]);
;           w.z = cvt_pk_bf16(ALPHA * bflo(xr.z) + v1[0], ALPHA * bfhi(xr.z) + v1[1]); w.w = cvt_pk_bf16(ALPHA * bflo(xr.w) + v1[2], ALPHA * bfhi(xr.w) + v1[3]);
;           *(u32x4*)(Y + ro + bj * HALF) = w; } }
; template <class Epi, class Sched>
; __device__ __forceinline__ void gemm_phase(PG8_LAS unsigned char* lds, const Gemm g, const Sched& S, const Epi& E) {
;     ...
;       PG8_STAGE(PG8_SB(1, 1), b3 + hstep, voffB);
;       PG8_WAIT_V(6); PG8_BAR; PG8_MMA(1, 1, At, B1); PG8_BAR;
;     }
	s_waitcnt lgkmcnt(0)
	s_setprio 2
	s_waitcnt lgkmcnt(0)
	v_mfma_f32_16x16x32_bf16 v[60:63], v[138:141], v[162:165], v[60:63]
	v_mfma_f32_16x16x32_bf16 v[56:59], v[154:157], v[162:165], v[56:59]
	v_mfma_f32_16x16x32_bf16 v[44:47], v[138:141], v[170:173], v[44:47]
	v_mfma_f32_16x16x32_bf16 v[40:43], v[154:157], v[170:173], v[40:43]
	v_mfma_f32_16x16x32_bf16 v[28:31], v[138:141], v[190:193], v[28:31]
	v_mfma_f32_16x16x32_bf16 v[24:27], v[154:157], v[190:193], v[24:27]
	v_mfma_f32_16x16x32_bf16 v[12:15], v[138:141], v[198:201], v[12:15]
	v_mfma_f32_16x16x32_bf16 v[8:11], v[154:157], v[198:201], v[8:11]
	v_mfma_f32_16x16x32_bf16 v[60:63], v[150:153], v[166:169], v[60:63]
	v_mfma_f32_16x16x32_bf16 v[56:59], v[158:161], v[166:169], v[56:59]
	v_mfma_f32_16x16x32_bf16 v[44:47], v[150:153], v[186:189], v[44:47]
	v_mfma_f32_16x16x32_bf16 v[40:43], v[158:161], v[186:189], v[40:43]
	v_mfma_f32_16x16x32_bf16 v[28:31], v[150:153], v[194:197], v[28:31]
	v_mfma_f32_16x16x32_bf16 v[24:27], v[158:161], v[194:197], v[24:27]
	v_mfma_f32_16x16x32_bf16 v[12:15], v[150:153], v[202:205], v[12:15]
	v_mfma_f32_16x16x32_bf16 v[8:11], v[158:161], v[202:205], v[8:11]
	s_setprio 0
	s_barrier
	s_add_u32 s78, s88, 0x80080
	s_addc_u32 s79, s89, 0
	s_add_i32 s4, s5, s76
	v_lshl_add_u64 v[138:139], s[78:79], 0, v[176:177]
	s_mov_b32 m0, s4
	s_nop 0
	global_load_lds_dwordx4 v[138:139], off
	v_lshl_add_u64 v[138:139], s[78:79], 0, v[128:129]
	s_add_i32 m0, s4, 0x2000
	s_nop 0
	global_load_lds_dwordx4 v[138:139], off
	s_waitcnt vmcnt(6)
	s_barrier
	s_setprio 2
	v_mfma_f32_16x16x32_bf16 v[52:55], v[232:235], v[162:165], v[52:55]
	v_mfma_f32_16x16x32_bf16 v[48:51], v[240:243], v[162:165], v[48:51]
	v_mfma_f32_16x16x32_bf16 v[36:39], v[232:235], v[170:173], v[36:39]
	v_mfma_f32_16x16x32_bf16 v[32:35], v[240:243], v[170:173], v[32:35]
	v_mfma_f32_16x16x32_bf16 v[20:23], v[232:235], v[190:193], v[20:23]
	v_mfma_f32_16x16x32_bf16 v[16:19], v[240:243], v[190:193], v[16:19]
	v_mfma_f32_16x16x32_bf16 v[4:7], v[232:235], v[198:201], v[4:7]
	v_mfma_f32_16x16x32_bf16 v[0:3], v[240:243], v[198:201], v[0:3]
	v_mfma_f32_16x16x32_bf16 v[52:55], v[236:239], v[166:169], v[52:55]
	v_mfma_f32_16x16x32_bf16 v[48:51], v[244:247], v[166:169], v[48:51]
	v_mfma_f32_16x16x32_bf16 v[36:39], v[236:239], v[186:189], v[36:39]
	v_mfma_f32_16x16x32_bf16 v[32:35], v[244:247], v[186:189], v[32:35]
	v_mfma_f32_16x16x32_bf16 v[20:23], v[236:239], v[194:197], v[20:23]
	v_mfma_f32_16x16x32_bf16 v[16:19], v[244:247], v[194:197], v[16:19]
	v_mfma_f32_16x16x32_bf16 v[4:7], v[236:239], v[202:205], v[4:7]
	v_mfma_f32_16x16x32_bf16 v[0:3], v[244:247], v[202:205], v[0:3]
	s_setprio 0
	s_add_i32 s74, s74, 2
	s_add_u32 s90, s90, 0x100
	s_addc_u32 s91, s91, 0
	s_add_u32 s73, s73, 0x100
	s_addc_u32 s11, s11, 0
	s_cmp_gt_u32 s74, 29
	s_barrier
	s_cbranch_scc0 .LBB0_1075
	v_lshl_add_u32 v142, s68, 8, v145
	v_lshl_or_b32 v140, s67, 8, v147
	v_ashrrev_i32_e32 v143, 31, v142
	v_ashrrev_i32_e32 v141, 31, v140
	v_lshlrev_b64 v[138:139], 11, v[142:143]
	v_lshl_add_u64 v[138:139], v[138:139], 0, v[140:141]
	v_lshlrev_b64 v[138:139], 1, v[138:139]
	v_mov_b32_e32 v156, v138
	v_add_u32_e32 v157, 0x10000, v138
	v_add_u32_e32 v158, 0x20000, v138
	v_add_u32_e32 v159, 0x30000, v138
	v_add_u32_e32 v160, 0x80000, v138
	v_add_u32_e32 v161, 0x90000, v138
	v_add_u32_e32 v162, 0xa0000, v138
	v_add_u32_e32 v163, 0xb0000, v138
	global_load_dwordx4 v[164:167], v156, s[54:55]
	global_load_dwordx4 v[168:171], v156, s[54:55] offset:256
	global_load_dwordx4 v[186:189], v157, s[54:55]
	global_load_dwordx4 v[190:193], v157, s[54:55] offset:256
	global_load_dwordx4 v[194:197], v158, s[54:55]
	global_load_dwordx4 v[198:201], v158, s[54:55] offset:256
	global_load_dwordx4 v[202:205], v159, s[54:55]
	global_load_dwordx4 v[232:235], v159, s[54:55] offset:256
	global_load_dwordx4 v[236:239], v160, s[54:55]
	global_load_dwordx4 v[240:243], v160, s[54:55] offset:256
	global_load_dwordx4 v[244:247], v161, s[54:55]
	s_mov_b64 s[4:5], 0xb0000
	s_and_b64 vcc, exec, s[38:39]
	s_mov_b32 s67, s0
	s_mov_b32 s68, s40
	s_mov_b64 s[88:89], s[42:43]
	s_mov_b64 s[90:91], s[86:87]
	s_waitcnt vmcnt(10)
	v_lshlrev_b32_e32 v142, 16, v164
	v_and_b32_e32 v143, 0xffff0000, v164
	v_fmamk_f32 v124, v142, 0x3fb504f3, v124
	v_fmamk_f32 v125, v143, 0x3fb504f3, v125
	v_cvt_pk_bf16_f32 v124, v124, v125
	v_lshlrev_b32_e32 v142, 16, v165
	v_and_b32_e32 v143, 0xffff0000, v165
	v_fmamk_f32 v126, v142, 0x3fb504f3, v126
	v_fmamk_f32 v127, v143, 0x3fb504f3, v127
	v_cvt_pk_bf16_f32 v125, v126, v127
	v_lshlrev_b32_e32 v142, 16, v166
	v_and_b32_e32 v143, 0xffff0000, v166
	v_fmamk_f32 v120, v142, 0x3fb504f3, v120
	v_fmamk_f32 v121, v143, 0x3fb504f3, v121
	v_cvt_pk_bf16_f32 v126, v120, v121
	v_lshlrev_b32_e32 v142, 16, v167
	v_and_b32_e32 v143, 0xffff0000, v167
	v_fmamk_f32 v122, v142, 0x3fb504f3, v122
	v_fmamk_f32 v123, v143, 0x3fb504f3, v123
	v_cvt_pk_bf16_f32 v127, v122, v123
	global_store_dwordx4 v156, v[124:127], s[24:25]
	global_load_dwordx4 v[164:167], v161, s[54:55] offset:256
	s_waitcnt vmcnt(11)
	v_lshlrev_b32_e32 v142, 16, v168
	v_and_b32_e32 v143, 0xffff0000, v168
	v_fmamk_f32 v116, v142, 0x3fb504f3, v116
	v_fmamk_f32 v117, v143, 0x3fb504f3, v117
	v_cvt_pk_bf16_f32 v116, v116, v117
	v_lshlrev_b32_e32 v142, 16, v169
	v_and_b32_e32 v143, 0xffff0000, v169
	v_fmamk_f32 v118, v142, 0x3fb504f3, v118
	v_fmamk_f32 v119, v143, 0x3fb504f3, v119
	v_cvt_pk_bf16_f32 v117, v118, v119
	v_lshlrev_b32_e32 v142, 16, v170
	v_and_b32_e32 v143, 0xffff0000, v170
	v_fmamk_f32 v112, v142, 0x3fb504f3, v112
	v_fmamk_f32 v113, v143, 0x3fb504f3, v113
	v_cvt_pk_bf16_f32 v118, v112, v113
	v_lshlrev_b32_e32 v142, 16, v171
	v_and_b32_e32 v143, 0xffff0000, v171
	v_fmamk_f32 v114, v142, 0x3fb504f3, v114
	v_fmamk_f32 v115, v143, 0x3fb504f3, v115
	v_cvt_pk_bf16_f32 v119, v114, v115
	global_store_dwordx4 v156, v[116:119], s[24:25] offset:256
	global_load_dwordx4 v[168:171], v162, s[54:55]
	s_waitcnt vmcnt(12)
; __device__ __forceinline__ float bflo(unsigned u) { return __uint_as_float(u << 16); }
; __device__ __forceinline__ float bfhi(unsigned u) { return __uint_as_float(u & 0xffff0000u); }
; __device__ __forceinline__ unsigned cvt_pk_bf16(float lo, float hi) { unsigned r; asm volatile("v_cvt_pk_bf16_f32 %0, %1, %2" : "=v"(r) : "v"(lo), "v"(hi)); return r; }
;   __device__ __forceinline__ void operator()(const f32x4 (&acc)[2][2][4][2], const Unit& u, int wr, int wc, int fr, int fq) const {
;     ...
;       for (int m = 0; m < 4; ++m) { const size_t ro = (size_t)(row0 + ai * HALF + m * 16) * ldc + col0;
; #pragma unroll
;         for (int bj = 0; bj < 2; ++bj) { const u32x4 xr = *(const u32x4*)(X + ro + bj * HALF);
;           const f32x4 v0 = acc[ai][bj][m][0], v1 = acc[ai][bj][m][1];
;           u32x4 w;
;           w.x = cvt_pk_bf16(ALPHA * bflo(xr.x) + v0[0], ALPHA * bfhi(xr.x) + v0[1]); w.y = cvt_pk_bf16(ALPHA * bflo(xr.y) + v0[2], ALPHA * bfhi(xr.y) + v0[3]);
;           w.z = cvt_pk_bf16(ALPHA * bflo(xr.z) + v1[0], ALPHA * bfhi(xr.z) + v1[1]); w.w = cvt_pk_bf16(ALPHA * bflo(xr.w) + v1[2], ALPHA * bfhi(xr.w) + v1[3]);
;           *(u32x4*)(Y + ro + bj * HALF) = w; } }
	v_lshlrev_b32_e32 v142, 16, v186
	v_and_b32_e32 v143, 0xffff0000, v186
	v_fmamk_f32 v108, v142, 0x3fb504f3, v108
	v_fmamk_f32 v109, v143, 0x3fb504f3, v109
	v_cvt_pk_bf16_f32 v108, v108, v109
	v_lshlrev_b32_e32 v142, 16, v187
	v_and_b32_e32 v143, 0xffff0000, v187
	v_fmamk_f32 v110, v142, 0x3fb504f3, v110
	v_fmamk_f32 v111, v143, 0x3fb504f3, v111
	v_cvt_pk_bf16_f32 v109, v110, v111
	v_lshlrev_b32_e32 v142, 16, v188
	v_and_b32_e32 v143, 0xffff0000, v188
	v_fmamk_f32 v104, v142, 0x3fb504f3, v104
	v_fmamk_f32 v105, v143, 0x3fb504f3, v105
	v_cvt_pk_bf16_f32 v110, v104, v105
	v_lshlrev_b32_e32 v142, 16, v189
	v_and_b32_e32 v143, 0xffff0000, v189
	v_fmamk_f32 v106, v142, 0x3fb504f3, v106
	v_fmamk_f32 v107, v143, 0x3fb504f3, v107
	v_cvt_pk_bf16_f32 v111, v106, v107
	global_store_dwordx4 v157, v[108:111], s[24:25]
	global_load_dwordx4 v[186:189], v162, s[54:55] offset:256
	s_waitcnt vmcnt(13)
	v_lshlrev_b32_e32 v142, 16, v190
	v_and_b32_e32 v143, 0xffff0000, v190
	v_fmamk_f32 v100, v142, 0x3fb504f3, v100
	v_fmamk_f32 v101, v143, 0x3fb504f3, v101
	v_cvt_pk_bf16_f32 v100, v100, v101
	v_lshlrev_b32_e32 v142, 16, v191
	v_and_b32_e32 v143, 0xffff0000, v191
	v_fmamk_f32 v102, v142, 0x3fb504f3, v102
	v_fmamk_f32 v103, v143, 0x3fb504f3, v103
	v_cvt_pk_bf16_f32 v101, v102, v103
	v_lshlrev_b32_e32 v142, 16, v192
	v_and_b32_e32 v143, 0xffff0000, v192
	v_fmamk_f32 v96, v142, 0x3fb504f3, v96
	v_fmamk_f32 v97, v143, 0x3fb504f3, v97
	v_cvt_pk_bf16_f32 v102, v96, v97
	v_lshlrev_b32_e32 v142, 16, v193
	v_and_b32_e32 v143, 0xffff0000, v193
	v_fmamk_f32 v98, v142, 0x3fb504f3, v98
	v_fmamk_f32 v99, v143, 0x3fb504f3, v99
	v_cvt_pk_bf16_f32 v103, v98, v99
	global_store_dwordx4 v157, v[100:103], s[24:25] offset:256
	global_load_dwordx4 v[190:193], v163, s[54:55]
	s_waitcnt vmcnt(14)
	v_lshlrev_b32_e32 v142, 16, v194
	v_and_b32_e32 v143, 0xffff0000, v194
	v_fmamk_f32 v92, v142, 0x3fb504f3, v92
	v_fmamk_f32 v93, v143, 0x3fb504f3, v93
	v_cvt_pk_bf16_f32 v92, v92, v93
	v_lshlrev_b32_e32 v142, 16, v195
	v_and_b32_e32 v143, 0xffff0000, v195
	v_fmamk_f32 v94, v142, 0x3fb504f3, v94
	v_fmamk_f32 v95, v143, 0x3fb504f3, v95
	v_cvt_pk_bf16_f32 v93, v94, v95
	v_lshlrev_b32_e32 v142, 16, v196
	v_and_b32_e32 v143, 0xffff0000, v196
	v_fmamk_f32 v88, v142, 0x3fb504f3, v88
	v_fmamk_f32 v89, v143, 0x3fb504f3, v89
	v_cvt_pk_bf16_f32 v94, v88, v89
	v_lshlrev_b32_e32 v142, 16, v197
	v_and_b32_e32 v143, 0xffff0000, v197
	v_fmamk_f32 v90, v142, 0x3fb504f3, v90
	v_fmamk_f32 v91, v143, 0x3fb504f3, v91
	v_cvt_pk_bf16_f32 v95, v90, v91
	global_store_dwordx4 v158, v[92:95], s[24:25]
	global_load_dwordx4 v[194:197], v163, s[54:55] offset:256
	s_waitcnt vmcnt(15)
	v_lshlrev_b32_e32 v142, 16, v198
	v_and_b32_e32 v143, 0xffff0000, v198
	v_fmamk_f32 v84, v142, 0x3fb504f3, v84
	v_fmamk_f32 v85, v143, 0x3fb504f3, v85
	v_cvt_pk_bf16_f32 v84, v84, v85
	v_lshlrev_b32_e32 v142, 16, v199
	v_and_b32_e32 v143, 0xffff0000, v199
	v_fmamk_f32 v86, v142, 0x3fb504f3, v86
	v_fmamk_f32 v87, v143, 0x3fb504f3, v87
	v_cvt_pk_bf16_f32 v85, v86, v87
	v_lshlrev_b32_e32 v142, 16, v200
	v_and_b32_e32 v143, 0xffff0000, v200
	v_fmamk_f32 v80, v142, 0x3fb504f3, v80
	v_fmamk_f32 v81, v143, 0x3fb504f3, v81
	v_cvt_pk_bf16_f32 v86, v80, v81
	v_lshlrev_b32_e32 v142, 16, v201
	v_and_b32_e32 v143, 0xffff0000, v201
	v_fmamk_f32 v82, v142, 0x3fb504f3, v82
	v_fmamk_f32 v83, v143, 0x3fb504f3, v83
	v_cvt_pk_bf16_f32 v87, v82, v83
	global_store_dwordx4 v158, v[84:87], s[24:25] offset:256
	s_waitcnt vmcnt(15)
	v_lshlrev_b32_e32 v142, 16, v202
	v_and_b32_e32 v143, 0xffff0000, v202
	v_fmamk_f32 v76, v142, 0x3fb504f3, v76
	v_fmamk_f32 v77, v143, 0x3fb504f3, v77
	v_cvt_pk_bf16_f32 v76, v76, v77
	v_lshlrev_b32_e32 v142, 16, v203
	v_and_b32_e32 v143, 0xffff0000, v203
	v_fmamk_f32 v78, v142, 0x3fb504f3, v78
	v_fmamk_f32 v79, v143, 0x3fb504f3, v79
	v_cvt_pk_bf16_f32 v77, v78, v79
	v_lshlrev_b32_e32 v142, 16, v204
	v_and_b32_e32 v143, 0xffff0000, v204
	v_fmamk_f32 v72, v142, 0x3fb504f3, v72
	v_fmamk_f32 v73, v143, 0x3fb504f3, v73
	v_cvt_pk_bf16_f32 v78, v72, v73
	v_lshlrev_b32_e32 v142, 16, v205
	v_and_b32_e32 v143, 0xffff0000, v205
	v_fmamk_f32 v74, v142, 0x3fb504f3, v74
	v_fmamk_f32 v75, v143, 0x3fb504f3, v75
	v_cvt_pk_bf16_f32 v79, v74, v75
	global_store_dwordx4 v159, v[76:79], s[24:25]
	s_waitcnt vmcnt(15)
	v_lshlrev_b32_e32 v142, 16, v232
	v_and_b32_e32 v143, 0xffff0000, v232
	v_fmamk_f32 v68, v142, 0x3fb504f3, v68
	v_fmamk_f32 v69, v143, 0x3fb504f3, v69
	v_cvt_pk_bf16_f32 v68, v68, v69
	v_lshlrev_b32_e32 v142, 16, v233
	v_and_b32_e32 v143, 0xffff0000, v233
	v_fmamk_f32 v70, v142, 0x3fb504f3, v70
	v_fmamk_f32 v71, v143, 0x3fb504f3, v71
	v_cvt_pk_bf16_f32 v69, v70, v71
	v_lshlrev_b32_e32 v142, 16, v234
	v_and_b32_e32 v143, 0xffff0000, v234
	v_fmamk_f32 v64, v142, 0x3fb504f3, v64
	v_fmamk_f32 v65, v143, 0x3fb504f3, v65
	v_cvt_pk_bf16_f32 v70, v64, v65
	v_lshlrev_b32_e32 v142, 16, v235
	v_and_b32_e32 v143, 0xffff0000, v235
	v_fmamk_f32 v66, v142, 0x3fb504f3, v66
	v_fmamk_f32 v67, v143, 0x3fb504f3, v67
	v_cvt_pk_bf16_f32 v71, v66, v67
	global_store_dwordx4 v159, v[68:71], s[24:25] offset:256
	s_waitcnt vmcnt(15)
	v_lshlrev_b32_e32 v142, 16, v236
	v_and_b32_e32 v143, 0xffff0000, v236
	v_fmamk_f32 v60, v142, 0x3fb504f3, v60
	v_fmamk_f32 v61, v143, 0x3fb504f3, v61
	v_cvt_pk_bf16_f32 v60, v60, v61
	v_lshlrev_b32_e32 v142, 16, v237
	v_and_b32_e32 v143, 0xffff0000, v237
	v_fmamk_f32 v62, v142, 0x3fb504f3, v62
	v_fmamk_f32 v63, v143, 0x3fb504f3, v63
	v_cvt_pk_bf16_f32 v61, v62, v63
	v_lshlrev_b32_e32 v142, 16, v238
	v_and_b32_e32 v143, 0xffff0000, v238
	v_fmamk_f32 v56, v142, 0x3fb504f3, v56
	v_fmamk_f32 v57, v143, 0x3fb504f3, v57
	v_cvt_pk_bf16_f32 v62, v56, v57
	v_lshlrev_b32_e32 v142, 16, v239
	v_and_b32_e32 v143, 0xffff0000, v239
	v_fmamk_f32 v58, v142, 0x3fb504f3, v58
	v_fmamk_f32 v59, v143, 0x3fb504f3, v59
	v_cvt_pk_bf16_f32 v63, v58, v59
	global_store_dwordx4 v160, v[60:63], s[24:25]
	s_waitcnt vmcnt(15)
; __device__ __forceinline__ float bflo(unsigned u) { return __uint_as_float(u << 16); }
; __device__ __forceinline__ float bfhi(unsigned u) { return __uint_as_float(u & 0xffff0000u); }
; __device__ __forceinline__ unsigned cvt_pk_bf16(float lo, float hi) { unsigned r; asm volatile("v_cvt_pk_bf16_f32 %0, %1, %2" : "=v"(r) : "v"(lo), "v"(hi)); return r; }
; #define PG8_WAIT_V(n) asm volatile("s_waitcnt vmcnt(" #n ")" ::: "memory")
; #define PG8_BAR __builtin_amdgcn_s_barrier()
;   __device__ __forceinline__ void operator()(const f32x4 (&acc)[2][2][4][2], const Unit& u, int wr, int wc, int fr, int fq) const {
;     ...
;       for (int m = 0; m < 4; ++m) { const size_t ro = (size_t)(row0 + ai * HALF + m * 16) * ldc + col0;
; #pragma unroll
;         for (int bj = 0; bj < 2; ++bj) { const u32x4 xr = *(const u32x4*)(X + ro + bj * HALF);
;           const f32x4 v0 = acc[ai][bj][m][0], v1 = acc[ai][bj][m][1];
;           u32x4 w;
;           w.x = cvt_pk_bf16(ALPHA * bflo(xr.x) + v0[0], ALPHA * bfhi(xr.x) + v0[1]); w.y = cvt_pk_bf16(ALPHA * bflo(xr.y) + v0[2], ALPHA * bfhi(xr.y) + v0[3]);
;           w.z = cvt_pk_bf16(ALPHA * bflo(xr.z) + v1[0], ALPHA * bfhi(xr.z) + v1[1]); w.w = cvt_pk_bf16(ALPHA * bflo(xr.w) + v1[2], ALPHA * bfhi(xr.w) + v1[3]);
;           *(u32x4*)(Y + ro + bj * HALF) = w; } }
; template <class Epi, class Sched>
; __device__ __forceinline__ void gemm_phase(PG8_LAS unsigned char* lds, const Gemm g, const Sched& S, const Epi& E) {
;     ...
;     E(acc, cur, wr, wc, fr, fq); S.done(cur);
;     if (!has_next) break;
; #pragma unroll
;     for (int a = 0; a < 2; ++a)
; #pragma unroll
;       for (int b = 0; b < 2; ++b)
; #pragma unroll
;         for (int m = 0; m < 4; ++m)
; #pragma unroll
;           for (int n = 0; n < 2; ++n) acc[a][b][m][n] = (f32x4){zz, zz, zz, zz};
;     cur = nxt; cA = nA; cB = nB; ++ui;
;   }
;   PG8_WAIT_V(0);
;   if (wr == 0) PG8_BAR;
;   PG8_BAR;
	v_lshlrev_b32_e32 v142, 16, v240
	v_and_b32_e32 v143, 0xffff0000, v240
	v_fmamk_f32 v52, v142, 0x3fb504f3, v52
	v_fmamk_f32 v53, v143, 0x3fb504f3, v53
	v_cvt_pk_bf16_f32 v52, v52, v53
	v_lshlrev_b32_e32 v142, 16, v241
	v_and_b32_e32 v143, 0xffff0000, v241
	v_fmamk_f32 v54, v142, 0x3fb504f3, v54
	v_fmamk_f32 v55, v143, 0x3fb504f3, v55
	v_cvt_pk_bf16_f32 v53, v54, v55
	v_lshlrev_b32_e32 v142, 16, v242
	v_and_b32_e32 v143, 0xffff0000, v242
	v_fmamk_f32 v48, v142, 0x3fb504f3, v48
	v_fmamk_f32 v49, v143, 0x3fb504f3, v49
	v_cvt_pk_bf16_f32 v54, v48, v49
	v_lshlrev_b32_e32 v142, 16, v243
	v_and_b32_e32 v143, 0xffff0000, v243
	v_fmamk_f32 v50, v142, 0x3fb504f3, v50
	v_fmamk_f32 v51, v143, 0x3fb504f3, v51
	v_cvt_pk_bf16_f32 v55, v50, v51
	global_store_dwordx4 v160, v[52:55], s[24:25] offset:256
	s_waitcnt vmcnt(15)
	v_lshlrev_b32_e32 v142, 16, v244
	v_and_b32_e32 v143, 0xffff0000, v244
	v_fmamk_f32 v44, v142, 0x3fb504f3, v44
	v_fmamk_f32 v45, v143, 0x3fb504f3, v45
	v_cvt_pk_bf16_f32 v44, v44, v45
	v_lshlrev_b32_e32 v142, 16, v245
	v_and_b32_e32 v143, 0xffff0000, v245
	v_fmamk_f32 v46, v142, 0x3fb504f3, v46
	v_fmamk_f32 v47, v143, 0x3fb504f3, v47
	v_cvt_pk_bf16_f32 v45, v46, v47
	v_lshlrev_b32_e32 v142, 16, v246
	v_and_b32_e32 v143, 0xffff0000, v246
	v_fmamk_f32 v40, v142, 0x3fb504f3, v40
	v_fmamk_f32 v41, v143, 0x3fb504f3, v41
	v_cvt_pk_bf16_f32 v46, v40, v41
	v_lshlrev_b32_e32 v142, 16, v247
	v_and_b32_e32 v143, 0xffff0000, v247
	v_fmamk_f32 v42, v142, 0x3fb504f3, v42
	v_fmamk_f32 v43, v143, 0x3fb504f3, v43
	v_cvt_pk_bf16_f32 v47, v42, v43
	global_store_dwordx4 v161, v[44:47], s[24:25]
	s_waitcnt vmcnt(14)
	v_lshlrev_b32_e32 v142, 16, v164
	v_and_b32_e32 v143, 0xffff0000, v164
	v_fmamk_f32 v36, v142, 0x3fb504f3, v36
	v_fmamk_f32 v37, v143, 0x3fb504f3, v37
	v_cvt_pk_bf16_f32 v36, v36, v37
	v_lshlrev_b32_e32 v142, 16, v165
	v_and_b32_e32 v143, 0xffff0000, v165
	v_fmamk_f32 v38, v142, 0x3fb504f3, v38
	v_fmamk_f32 v39, v143, 0x3fb504f3, v39
	v_cvt_pk_bf16_f32 v37, v38, v39
	v_lshlrev_b32_e32 v142, 16, v166
	v_and_b32_e32 v143, 0xffff0000, v166
	v_fmamk_f32 v32, v142, 0x3fb504f3, v32
	v_fmamk_f32 v33, v143, 0x3fb504f3, v33
	v_cvt_pk_bf16_f32 v38, v32, v33
	v_lshlrev_b32_e32 v142, 16, v167
	v_and_b32_e32 v143, 0xffff0000, v167
	v_fmamk_f32 v34, v142, 0x3fb504f3, v34
	v_fmamk_f32 v35, v143, 0x3fb504f3, v35
	v_cvt_pk_bf16_f32 v39, v34, v35
	global_store_dwordx4 v161, v[36:39], s[24:25] offset:256
	s_waitcnt vmcnt(13)
	v_lshlrev_b32_e32 v142, 16, v168
	v_and_b32_e32 v143, 0xffff0000, v168
	v_fmamk_f32 v28, v142, 0x3fb504f3, v28
	v_fmamk_f32 v29, v143, 0x3fb504f3, v29
	v_cvt_pk_bf16_f32 v28, v28, v29
	v_lshlrev_b32_e32 v142, 16, v169
	v_and_b32_e32 v143, 0xffff0000, v169
	v_fmamk_f32 v30, v142, 0x3fb504f3, v30
	v_fmamk_f32 v31, v143, 0x3fb504f3, v31
	v_cvt_pk_bf16_f32 v29, v30, v31
	v_lshlrev_b32_e32 v142, 16, v170
	v_and_b32_e32 v143, 0xffff0000, v170
	v_fmamk_f32 v24, v142, 0x3fb504f3, v24
	v_fmamk_f32 v25, v143, 0x3fb504f3, v25
	v_cvt_pk_bf16_f32 v30, v24, v25
	v_lshlrev_b32_e32 v142, 16, v171
	v_and_b32_e32 v143, 0xffff0000, v171
	v_fmamk_f32 v26, v142, 0x3fb504f3, v26
	v_fmamk_f32 v27, v143, 0x3fb504f3, v27
	v_cvt_pk_bf16_f32 v31, v26, v27
	global_store_dwordx4 v162, v[28:31], s[24:25]
	s_waitcnt vmcnt(12)
	v_lshlrev_b32_e32 v142, 16, v186
	v_and_b32_e32 v143, 0xffff0000, v186
	v_fmamk_f32 v20, v142, 0x3fb504f3, v20
	v_fmamk_f32 v21, v143, 0x3fb504f3, v21
	v_cvt_pk_bf16_f32 v20, v20, v21
	v_lshlrev_b32_e32 v142, 16, v187
	v_and_b32_e32 v143, 0xffff0000, v187
	v_fmamk_f32 v22, v142, 0x3fb504f3, v22
	v_fmamk_f32 v23, v143, 0x3fb504f3, v23
	v_cvt_pk_bf16_f32 v21, v22, v23
	v_lshlrev_b32_e32 v142, 16, v188
	v_and_b32_e32 v143, 0xffff0000, v188
	v_fmamk_f32 v16, v142, 0x3fb504f3, v16
	v_fmamk_f32 v17, v143, 0x3fb504f3, v17
	v_cvt_pk_bf16_f32 v22, v16, v17
	v_lshlrev_b32_e32 v142, 16, v189
	v_and_b32_e32 v143, 0xffff0000, v189
	v_fmamk_f32 v18, v142, 0x3fb504f3, v18
	v_fmamk_f32 v19, v143, 0x3fb504f3, v19
	v_cvt_pk_bf16_f32 v23, v18, v19
	global_store_dwordx4 v162, v[20:23], s[24:25] offset:256
	s_waitcnt vmcnt(11)
	v_lshlrev_b32_e32 v142, 16, v190
	v_and_b32_e32 v143, 0xffff0000, v190
	v_fmamk_f32 v12, v142, 0x3fb504f3, v12
	v_fmamk_f32 v13, v143, 0x3fb504f3, v13
	v_cvt_pk_bf16_f32 v12, v12, v13
	v_lshlrev_b32_e32 v142, 16, v191
	v_and_b32_e32 v143, 0xffff0000, v191
	v_fmamk_f32 v14, v142, 0x3fb504f3, v14
	v_fmamk_f32 v15, v143, 0x3fb504f3, v15
	v_cvt_pk_bf16_f32 v13, v14, v15
	v_lshlrev_b32_e32 v142, 16, v192
	v_and_b32_e32 v143, 0xffff0000, v192
	v_fmamk_f32 v8, v142, 0x3fb504f3, v8
	v_fmamk_f32 v9, v143, 0x3fb504f3, v9
	v_cvt_pk_bf16_f32 v14, v8, v9
	v_lshlrev_b32_e32 v142, 16, v193
	v_and_b32_e32 v143, 0xffff0000, v193
	v_fmamk_f32 v10, v142, 0x3fb504f3, v10
	v_fmamk_f32 v11, v143, 0x3fb504f3, v11
	v_cvt_pk_bf16_f32 v15, v10, v11
	global_store_dwordx4 v163, v[12:15], s[24:25]
	s_waitcnt vmcnt(10)
	v_lshlrev_b32_e32 v142, 16, v194
	v_and_b32_e32 v143, 0xffff0000, v194
	v_fmamk_f32 v4, v142, 0x3fb504f3, v4
	v_fmamk_f32 v5, v143, 0x3fb504f3, v5
	v_cvt_pk_bf16_f32 v4, v4, v5
	v_lshlrev_b32_e32 v142, 16, v195
	v_and_b32_e32 v143, 0xffff0000, v195
	v_fmamk_f32 v6, v142, 0x3fb504f3, v6
	v_fmamk_f32 v7, v143, 0x3fb504f3, v7
	v_cvt_pk_bf16_f32 v5, v6, v7
	v_lshlrev_b32_e32 v142, 16, v196
	v_and_b32_e32 v143, 0xffff0000, v196
	v_fmamk_f32 v0, v142, 0x3fb504f3, v0
	v_fmamk_f32 v1, v143, 0x3fb504f3, v1
	v_cvt_pk_bf16_f32 v6, v0, v1
	v_lshlrev_b32_e32 v142, 16, v197
	v_and_b32_e32 v143, 0xffff0000, v197
	v_fmamk_f32 v2, v142, 0x3fb504f3, v2
	v_fmamk_f32 v3, v143, 0x3fb504f3, v3
	v_cvt_pk_bf16_f32 v7, v2, v3
	global_store_dwordx4 v163, v[4:7], s[24:25] offset:256
	s_cbranch_vccz .LBB0_1068
	s_waitcnt vmcnt(0)
	v_readlane_b32 s74, v251, 56
	v_readlane_b32 s96, v251, 58
	v_readlane_b32 s78, v250, 0
	v_readlane_b32 s86, v250, 2
	v_readlane_b32 s90, v250, 4
	s_cmpk_gt_u32 s19, 0xff
	v_readlane_b32 s75, v251, 57
	v_readlane_b32 s97, v251, 59
	v_readlane_b32 s82, v252, 43
	v_readlane_b32 s79, v250, 1
	v_readlane_b32 s87, v250, 3
	v_readlane_b32 s91, v250, 5
	s_movk_i32 s83, 0x4000
	s_cbranch_scc1 .LBB0_1079
	s_barrier
